# GEMM phases: one static s_setprio 1 for the trailing wave half at unit-loop entry (reset at loop exit) instead of per-segment priority flips
# speedup vs baseline: 1.0041x; 1.0041x over previous
.LBB0_252:
	s_add_u32 s12, s6, 0xec00000
	s_addc_u32 s13, s7, 0
	s_add_u32 s14, s6, 0x1ac00000
	s_addc_u32 s15, s7, 0
	s_add_u32 s18, s6, 0x1ec00000
	s_addc_u32 s19, s7, 0
	s_add_u32 s20, s6, 0xea00000
	s_addc_u32 s21, s7, 0
	s_lshl_b32 s68, s84, 2
	s_lshl_b64 s[24:25], s[68:69], 2
	s_waitcnt lgkmcnt(0)
	s_add_u32 s22, s22, s24
	s_addc_u32 s23, s23, s25
	s_add_u32 s24, s4, s24
	s_addc_u32 s25, s5, s25
	s_and_b32 s29, s28, 3
	s_add_i32 m0, s55, 0x18000
	v_lshl_add_u64 v[6:7], v[6:7], 0, s[76:77]
	s_lshl_b32 s30, s27, 13
	s_lshl_b32 s31, s29, 12
	s_waitcnt vmcnt(2)
	s_barrier
	global_load_lds_dwordx4 v[6:7], off
	v_lshl_add_u64 v[4:5], v[4:5], 0, s[76:77]
	s_add_i32 m0, s55, 0x1a000
	s_add_i32 s68, s55, 0x8000
	s_add_i32 s83, s55, 0xa000
	global_load_lds_dwordx4 v[4:5], off
	v_lshl_add_u64 v[0:1], v[0:1], 0, s[76:77]
	s_mov_b32 m0, s68
	s_add_u32 s4, s8, 0x40080
	global_load_lds_dwordx4 v[0:1], off
	v_lshl_add_u64 v[0:1], v[2:3], 0, s[76:77]
	s_mov_b32 m0, s83
	s_addc_u32 s5, s9, 0
	global_load_lds_dwordx4 v[0:1], off
	s_add_i32 m0, s55, 0x1c000
	v_lshl_add_u64 v[0:1], s[4:5], 0, v[192:193]
	global_load_lds_dwordx4 v[0:1], off
	v_lshl_add_u64 v[0:1], s[4:5], 0, v[152:153]
	s_add_i32 m0, s55, 0x1e000
	v_and_b32_e32 v2, 15, v8
	global_load_lds_dwordx4 v[0:1], off
	v_lshrrev_b32_e32 v1, 4, v8
	v_bfe_u32 v0, v8, 4, 2
	v_bitop3_b32 v1, s28, v1, 3 bitop3:0xa8
	v_lshlrev_b32_e32 v3, 3, v0
	v_lshlrev_b32_e32 v0, 4, v0
	v_cmp_eq_u32_e64 s[4:5], 0, v1
	v_mov_b32_e32 v1, v193
	v_lshl_or_b32 v181, s27, 6, v2
	v_lshl_or_b32 v2, v2, 6, v0
	v_lshl_add_u64 v[0:1], s[6:7], 0, v[0:1]
	s_mov_b64 s[6:7], 0x3cc00000
	v_lshl_add_u64 v[158:159], v[0:1], 0, s[6:7]
	v_lshlrev_b32_e32 v0, 14, v9
	v_and_b32_e32 v0, 0xffff8000, v0
	v_lshl_add_u32 v0, v10, 11, v0
	v_and_b32_e32 v1, 1, v9
	v_lshl_or_b32 v0, v1, 6, v0
	v_lshl_add_u32 v160, v11, 1, v0
	v_lshlrev_b32_e32 v0, 14, v13
	v_lshlrev_b32_e32 v4, 2, v8
	v_and_b32_e32 v0, 0xffff8000, v0
	v_and_b32_e32 v4, 32, v4
	s_waitcnt vmcnt(6)
	v_lshl_add_u32 v0, v12, 11, v0
	v_and_b32_e32 v1, 1, v13
	v_bitop3_b32 v5, v2, s30, v4 bitop3:0xde
	s_cmpk_lt_u32 s26, 0x100
	v_lshl_or_b32 v0, v1, 6, v0
	v_readlane_b32 s6, v255, 34
	v_bitop3_b32 v183, v2, s31, v4 bitop3:0xde
	s_cselect_b64 s[26:27], -1, 0
	s_mov_b32 s85, 0
	v_lshl_or_b32 v186, s29, 5, v3
	v_mov_b32_e32 v161, v193
	v_lshl_add_u32 v162, v14, 1, v0
	v_mov_b32_e32 v163, v193
	v_add_u32_e32 v187, 0, v5
	v_readlane_b32 s86, v255, 18
	s_mov_b32 s46, s6
	s_barrier
	v_readlane_b32 s7, v255, 35
	s_cmp_lt_u32 s33, 0x100
	s_cbranch_scc1 .Lsp0
	s_setprio 1
.Lsp0:
	s_branch .LBB0_255
.Lz255:
	s_add_u32 s88, s8, 0x100
	s_addc_u32 s89, s9, 0
	s_add_u32 s8, s38, 0x40080
	s_addc_u32 s9, s39, 0
	s_mov_b32 s90, -2
	s_add_u32 s38, s8, 0xfffc0080
	s_addc_u32 s39, s9, -1
	s_add_i32 s91, 0, 0x10000
	s_cmp_eq_u32 s90, 12
	s_cselect_b32 s57, s31, s39
	s_cselect_b32 s56, s47, s38
	s_cselect_b32 s39, s29, s89
	s_cselect_b32 s38, s87, s88
	s_add_i32 s94, 0, 0x14000
	v_add_u32_e32 v140, s91, v183
	v_add_u32_e32 v168, s94, v183
	ds_read_b128 v[128:131], v140
	ds_read_b128 v[132:135], v140 offset:1024
	ds_read_b128 v[136:139], v140 offset:2048
	ds_read_b128 v[140:143], v140 offset:3072
	ds_read_b128 v[144:147], v168
	ds_read_b128 v[148:151], v168 offset:1024
	ds_read_b128 v[164:167], v168 offset:2048
	ds_read_b128 v[168:171], v168 offset:3072
	v_lshl_add_u64 v[184:185], s[8:9], 0, v[162:163]
	s_add_i32 m0, s55, 0xc000
	ds_read_b128 v[172:175], v187
	ds_read_b128 v[176:179], v187 offset:1024
	ds_read_b128 v[188:191], v187 offset:2048
	ds_read_b128 v[202:205], v187 offset:3072
	ds_read_b128 v[206:209], v187 offset:4096
	ds_read_b128 v[210:213], v187 offset:5120
	ds_read_b128 v[214:217], v187 offset:6144
	ds_read_b128 v[218:221], v187 offset:7168
	global_load_lds_dwordx4 v[184:185], off
	v_lshl_add_u64 v[184:185], s[8:9], 0, v[160:161]
	s_add_i32 m0, s55, 0xe000
	s_nop 0
	global_load_lds_dwordx4 v[184:185], off
	s_add_i32 s85, s85, 1
	s_mul_i32 s6, s85, s43
	s_mul_hi_u32 s7, s85, s42
	s_add_i32 s7, s7, s6
	s_mul_i32 s6, s85, s42
	s_add_u32 s34, s6, s2
	s_addc_u32 s35, s7, s41
	v_mov_b64_e32 v[0:1], 0xf00
	v_cmp_lt_i64_e64 s[6:7], s[34:35], v[0:1]
	v_mov_b64_e32 v[0:1], 0xeff
	v_cmp_gt_i64_e32 vcc, s[34:35], v[0:1]
	s_cbranch_vccnz .Lz257
	s_ashr_i32 s28, s34, 31
	s_lshr_b32 s28, s28, 29
	s_add_i32 s28, s34, s28
	s_ashr_i32 s29, s28, 3
	s_and_b32 s28, s28, -8
	s_sub_i32 s28, s34, s28
	s_cmp_lt_i32 s28, 0
	s_movk_i32 s30, 0x1e1
	s_cselect_b32 s30, s30, 0x1e0
	s_mul_i32 s28, s28, s30
	s_add_i32 s28, s28, s29
	s_mul_hi_i32 s29, s28, 0x88888889
	s_add_i32 s29, s29, s28
	s_lshr_b32 s30, s29, 31
	s_ashr_i32 s29, s29, 6
	s_add_i32 s29, s29, s30
	s_lshl_b32 s30, s29, 3
	s_sub_i32 s31, 0x100, s30
	s_min_i32 s31, s31, 8
	s_abs_i32 s34, s31
	v_cvt_f32_u32_e32 v0, s34
	s_sub_i32 s36, 0, s34
	s_mulk_i32 s29, 0x78
	s_sub_i32 s29, s28, s29
	v_rcp_iflag_f32_e32 v0, v0
	s_abs_i32 s28, s29
	s_xor_b32 s35, s29, s31
	s_ashr_i32 s35, s35, 31
	v_mul_f32_e32 v0, 0x4f7ffffe, v0
	v_cvt_u32_f32_e32 v0, v0
	s_nop 0
	v_readfirstlane_b32 s37, v0
	s_mul_i32 s36, s36, s37
	s_mul_hi_u32 s36, s37, s36
	s_add_i32 s37, s37, s36
	s_mul_hi_u32 s36, s28, s37
	s_mul_i32 s37, s36, s34
	s_sub_i32 s28, s28, s37
	s_add_i32 s47, s36, 1
	s_sub_i32 s37, s28, s34
	s_cmp_ge_u32 s28, s34
	s_cselect_b32 s36, s47, s36
	s_cselect_b32 s28, s37, s28
	s_add_i32 s37, s36, 1
	s_cmp_ge_u32 s28, s34
	s_cselect_b32 s28, s37, s36
	s_xor_b32 s28, s28, s35
	s_sub_i32 s28, s28, s35
	s_mul_i32 s31, s28, s31
	s_sub_i32 s29, s29, s31
	s_add_i32 s30, s30, s29
.Lz257:
	s_ashr_i32 s31, s30, 31
	s_lshl_b64 s[34:35], s[30:31], 19
	s_add_u32 s34, s48, s34
	s_addc_u32 s35, s49, s35
	s_and_b64 s[36:37], s[6:7], exec
	s_cselect_b32 s31, s35, s57
	s_cselect_b32 s47, s34, s56
	s_ashr_i32 s29, s28, 31
	s_lshl_b64 s[36:37], s[28:29], 19
	s_add_u32 s36, s50, s36
	s_addc_u32 s37, s51, s37
	s_and_b64 s[100:101], s[6:7], exec
	s_cselect_b32 s29, s37, s89
	s_cselect_b32 s87, s36, s88
	s_waitcnt vmcnt(8)
	s_waitcnt lgkmcnt(0)
	s_barrier
	s_waitcnt lgkmcnt(0)
	v_mfma_f32_16x16x32_bf16 v[124:127], v[128:131], v[172:175], 0
	v_mfma_f32_16x16x32_bf16 v[120:123], v[136:139], v[172:175], 0
	v_mfma_f32_16x16x32_bf16 v[112:115], v[128:131], v[188:191], 0
	v_mfma_f32_16x16x32_bf16 v[104:107], v[136:139], v[188:191], 0
	v_mfma_f32_16x16x32_bf16 v[96:99], v[128:131], v[206:209], 0
	v_mfma_f32_16x16x32_bf16 v[88:91], v[136:139], v[206:209], 0
	v_mfma_f32_16x16x32_bf16 v[80:83], v[128:131], v[214:217], 0
	v_mfma_f32_16x16x32_bf16 v[72:75], v[136:139], v[214:217], 0
	v_mfma_f32_16x16x32_bf16 v[124:127], v[132:135], v[176:179], v[124:127]
	v_mfma_f32_16x16x32_bf16 v[120:123], v[140:143], v[176:179], v[120:123]
	v_mfma_f32_16x16x32_bf16 v[112:115], v[132:135], v[202:205], v[112:115]
	v_mfma_f32_16x16x32_bf16 v[104:107], v[140:143], v[202:205], v[104:107]
	v_mfma_f32_16x16x32_bf16 v[96:99], v[132:135], v[210:213], v[96:99]
	v_mfma_f32_16x16x32_bf16 v[88:91], v[140:143], v[210:213], v[88:91]
	v_mfma_f32_16x16x32_bf16 v[80:83], v[132:135], v[218:221], v[80:83]
	v_mfma_f32_16x16x32_bf16 v[72:75], v[140:143], v[218:221], v[72:75]
	s_barrier
	s_add_i32 s91, s91, s54
	v_lshl_add_u64 v[184:185], s[38:39], 0, v[192:193]
	s_mov_b32 m0, s91
	ds_read_b128 v[172:175], v187 offset:16384
	ds_read_b128 v[176:179], v187 offset:17408
	ds_read_b128 v[188:191], v187 offset:18432
	ds_read_b128 v[202:205], v187 offset:19456
	ds_read_b128 v[206:209], v187 offset:20480
	ds_read_b128 v[210:213], v187 offset:21504
	ds_read_b128 v[214:217], v187 offset:22528
	ds_read_b128 v[218:221], v187 offset:23552
	global_load_lds_dwordx4 v[184:185], off
	s_add_i32 m0, s91, 0x2000
	s_add_u32 s92, s38, 0x40000
	v_lshl_add_u64 v[222:223], s[38:39], 0, v[152:153]
	s_addc_u32 s93, s39, 0
	s_add_i32 s91, s94, s54
	global_load_lds_dwordx4 v[222:223], off
	v_lshl_add_u64 v[224:225], s[92:93], 0, v[192:193]
	s_mov_b32 m0, s91
	v_lshl_add_u64 v[226:227], s[56:57], 0, v[154:155]
	global_load_lds_dwordx4 v[224:225], off
	v_lshl_add_u64 v[224:225], s[92:93], 0, v[152:153]
	s_add_i32 m0, s91, 0x2000
	s_nop 0
	global_load_lds_dwordx4 v[224:225], off
	v_lshl_add_u64 v[224:225], s[56:57], 0, v[156:157]
	s_mov_b32 m0, s55
	s_nop 0
	global_load_lds_dwordx4 v[224:225], off
	s_mov_b32 m0, s60
	s_nop 0
	global_load_lds_dwordx4 v[226:227], off
	s_waitcnt vmcnt(8)
	s_waitcnt lgkmcnt(0)
	s_barrier
	s_waitcnt lgkmcnt(0)
	v_mfma_f32_16x16x32_bf16 v[60:63], v[128:131], v[172:175], 0
	v_mfma_f32_16x16x32_bf16 v[56:59], v[136:139], v[172:175], 0
	v_mfma_f32_16x16x32_bf16 v[48:51], v[128:131], v[188:191], 0
	v_mfma_f32_16x16x32_bf16 v[40:43], v[136:139], v[188:191], 0
	v_mfma_f32_16x16x32_bf16 v[32:35], v[128:131], v[206:209], 0
	v_mfma_f32_16x16x32_bf16 v[24:27], v[136:139], v[206:209], 0
	v_mfma_f32_16x16x32_bf16 v[16:19], v[128:131], v[214:217], 0
	v_mfma_f32_16x16x32_bf16 v[8:11], v[136:139], v[214:217], 0
	v_mfma_f32_16x16x32_bf16 v[60:63], v[132:135], v[176:179], v[60:63]
	v_mfma_f32_16x16x32_bf16 v[56:59], v[140:143], v[176:179], v[56:59]
	v_mfma_f32_16x16x32_bf16 v[48:51], v[132:135], v[202:205], v[48:51]
	v_mfma_f32_16x16x32_bf16 v[40:43], v[140:143], v[202:205], v[40:43]
	v_mfma_f32_16x16x32_bf16 v[32:35], v[132:135], v[210:213], v[32:35]
	v_mfma_f32_16x16x32_bf16 v[24:27], v[140:143], v[210:213], v[24:27]
	v_mfma_f32_16x16x32_bf16 v[16:19], v[132:135], v[218:221], v[16:19]
	v_mfma_f32_16x16x32_bf16 v[8:11], v[140:143], v[218:221], v[8:11]
	s_barrier
	s_add_i32 s91, 0, 0x18000
	s_add_i32 s92, 0, 0x1c000
	v_add_u32_e32 v140, s91, v183
	v_add_u32_e32 v168, s92, v183
	ds_read_b128 v[128:131], v140
	ds_read_b128 v[132:135], v140 offset:1024
	ds_read_b128 v[136:139], v140 offset:2048
	ds_read_b128 v[140:143], v140 offset:3072
	ds_read_b128 v[144:147], v168
	ds_read_b128 v[148:151], v168 offset:1024
	ds_read_b128 v[164:167], v168 offset:2048
	ds_read_b128 v[168:171], v168 offset:3072
	s_add_u32 s56, s56, 0x40000
	s_addc_u32 s57, s57, 0
	s_mov_b32 m0, s61
	v_lshl_add_u64 v[228:229], s[56:57], 0, v[156:157]
	ds_read_b128 v[172:175], v187 offset:32768
	ds_read_b128 v[176:179], v187 offset:33792
	ds_read_b128 v[188:191], v187 offset:34816
	ds_read_b128 v[202:205], v187 offset:35840
	ds_read_b128 v[206:209], v187 offset:36864
	ds_read_b128 v[210:213], v187 offset:37888
	ds_read_b128 v[214:217], v187 offset:38912
	ds_read_b128 v[218:221], v187 offset:39936
	global_load_lds_dwordx4 v[228:229], off
	v_lshl_add_u64 v[228:229], s[56:57], 0, v[154:155]
	s_mov_b32 m0, s82
	s_nop 0
	global_load_lds_dwordx4 v[228:229], off
	s_waitcnt vmcnt(8)
	s_waitcnt lgkmcnt(0)
	s_barrier
	s_waitcnt lgkmcnt(0)
	v_mfma_f32_16x16x32_bf16 v[124:127], v[128:131], v[172:175], v[124:127]
	v_mfma_f32_16x16x32_bf16 v[120:123], v[136:139], v[172:175], v[120:123]
	v_mfma_f32_16x16x32_bf16 v[112:115], v[128:131], v[188:191], v[112:115]
	v_mfma_f32_16x16x32_bf16 v[104:107], v[136:139], v[188:191], v[104:107]
	v_mfma_f32_16x16x32_bf16 v[96:99], v[128:131], v[206:209], v[96:99]
	v_mfma_f32_16x16x32_bf16 v[88:91], v[136:139], v[206:209], v[88:91]
	v_mfma_f32_16x16x32_bf16 v[80:83], v[128:131], v[214:217], v[80:83]
	v_mfma_f32_16x16x32_bf16 v[72:75], v[136:139], v[214:217], v[72:75]
	v_mfma_f32_16x16x32_bf16 v[124:127], v[132:135], v[176:179], v[124:127]
	v_mfma_f32_16x16x32_bf16 v[120:123], v[140:143], v[176:179], v[120:123]
	v_mfma_f32_16x16x32_bf16 v[112:115], v[132:135], v[202:205], v[112:115]
	v_mfma_f32_16x16x32_bf16 v[104:107], v[140:143], v[202:205], v[104:107]
	v_mfma_f32_16x16x32_bf16 v[96:99], v[132:135], v[210:213], v[96:99]
	v_mfma_f32_16x16x32_bf16 v[88:91], v[140:143], v[210:213], v[88:91]
	v_mfma_f32_16x16x32_bf16 v[80:83], v[132:135], v[218:221], v[80:83]
	v_mfma_f32_16x16x32_bf16 v[72:75], v[140:143], v[218:221], v[72:75]
	s_barrier
	s_add_i32 s56, s91, s54
	v_lshl_add_u64 v[184:185], v[184:185], 0, s[76:77]
	s_mov_b32 m0, s56
	ds_read_b128 v[172:175], v187 offset:49152
	ds_read_b128 v[176:179], v187 offset:50176
	ds_read_b128 v[188:191], v187 offset:51200
	ds_read_b128 v[202:205], v187 offset:52224
	ds_read_b128 v[206:209], v187 offset:53248
	ds_read_b128 v[210:213], v187 offset:54272
	ds_read_b128 v[214:217], v187 offset:55296
	ds_read_b128 v[218:221], v187 offset:56320
	global_load_lds_dwordx4 v[184:185], off
	s_add_i32 m0, s56, 0x2000
	s_add_u32 s38, s38, 0x40080
	v_lshl_add_u64 v[184:185], v[222:223], 0, s[76:77]
	s_addc_u32 s39, s39, 0
	s_add_i32 s56, s92, s54
	global_load_lds_dwordx4 v[184:185], off
	v_lshl_add_u64 v[184:185], s[38:39], 0, v[192:193]
	s_mov_b32 m0, s56
	s_nop 0
	global_load_lds_dwordx4 v[184:185], off
	v_lshl_add_u64 v[184:185], s[38:39], 0, v[152:153]
	s_add_i32 m0, s56, 0x2000
	s_nop 0
	global_load_lds_dwordx4 v[184:185], off
	v_lshl_add_u64 v[184:185], v[224:225], 0, s[76:77]
	s_mov_b32 m0, s68
	s_nop 0
	global_load_lds_dwordx4 v[184:185], off
	v_lshl_add_u64 v[184:185], v[226:227], 0, s[76:77]
	s_mov_b32 m0, s83
	s_nop 0
	global_load_lds_dwordx4 v[184:185], off
	s_waitcnt vmcnt(8)
	s_waitcnt lgkmcnt(0)
	s_barrier
	s_waitcnt lgkmcnt(0)
	v_mfma_f32_16x16x32_bf16 v[60:63], v[128:131], v[172:175], v[60:63]
	v_mfma_f32_16x16x32_bf16 v[56:59], v[136:139], v[172:175], v[56:59]
	v_mfma_f32_16x16x32_bf16 v[48:51], v[128:131], v[188:191], v[48:51]
	v_mfma_f32_16x16x32_bf16 v[40:43], v[136:139], v[188:191], v[40:43]
	v_mfma_f32_16x16x32_bf16 v[32:35], v[128:131], v[206:209], v[32:35]
	v_mfma_f32_16x16x32_bf16 v[24:27], v[136:139], v[206:209], v[24:27]
	v_mfma_f32_16x16x32_bf16 v[16:19], v[128:131], v[214:217], v[16:19]
	v_mfma_f32_16x16x32_bf16 v[8:11], v[136:139], v[214:217], v[8:11]
	v_mfma_f32_16x16x32_bf16 v[60:63], v[132:135], v[176:179], v[60:63]
	v_mfma_f32_16x16x32_bf16 v[56:59], v[140:143], v[176:179], v[56:59]
	v_mfma_f32_16x16x32_bf16 v[48:51], v[132:135], v[202:205], v[48:51]
	v_mfma_f32_16x16x32_bf16 v[40:43], v[140:143], v[202:205], v[40:43]
	v_mfma_f32_16x16x32_bf16 v[32:35], v[132:135], v[210:213], v[32:35]
	v_mfma_f32_16x16x32_bf16 v[24:27], v[140:143], v[210:213], v[24:27]
	v_mfma_f32_16x16x32_bf16 v[16:19], v[132:135], v[218:221], v[16:19]
	v_mfma_f32_16x16x32_bf16 v[8:11], v[140:143], v[218:221], v[8:11]
	s_barrier
	s_add_i32 s90, s90, 2
	s_add_u32 s88, s88, 0x100
	s_addc_u32 s89, s89, 0
	s_add_u32 s8, s8, 0x100
	s_addc_u32 s9, s9, 0
	s_cmp_gt_u32 s90, 13
.Lz258:
	s_add_u32 s38, s8, 0xfffc0080
	s_addc_u32 s39, s9, -1
	s_add_i32 s91, 0, 0x10000
	s_cmp_eq_u32 s90, 12
	s_cselect_b32 s57, s31, s39
	s_cselect_b32 s56, s47, s38
	s_cselect_b32 s39, s29, s89
	s_cselect_b32 s38, s87, s88
	s_add_i32 s94, 0, 0x14000
	v_add_u32_e32 v140, s91, v183
	v_add_u32_e32 v168, s94, v183
	ds_read_b128 v[128:131], v140
	ds_read_b128 v[132:135], v140 offset:1024
	ds_read_b128 v[136:139], v140 offset:2048
	ds_read_b128 v[140:143], v140 offset:3072
	ds_read_b128 v[144:147], v168
	ds_read_b128 v[148:151], v168 offset:1024
	ds_read_b128 v[164:167], v168 offset:2048
	ds_read_b128 v[168:171], v168 offset:3072
	v_lshl_add_u64 v[184:185], s[8:9], 0, v[162:163]
	s_add_i32 m0, s55, 0xc000
	ds_read_b128 v[172:175], v187
	ds_read_b128 v[176:179], v187 offset:1024
	ds_read_b128 v[188:191], v187 offset:2048
	ds_read_b128 v[202:205], v187 offset:3072
	ds_read_b128 v[206:209], v187 offset:4096
	ds_read_b128 v[210:213], v187 offset:5120
	ds_read_b128 v[214:217], v187 offset:6144
	ds_read_b128 v[218:221], v187 offset:7168
	global_load_lds_dwordx4 v[184:185], off
	v_lshl_add_u64 v[184:185], s[8:9], 0, v[160:161]
	s_add_i32 m0, s55, 0xe000
	s_nop 0
	global_load_lds_dwordx4 v[184:185], off
	s_waitcnt vmcnt(8)
	s_waitcnt lgkmcnt(0)
	s_barrier
	s_waitcnt lgkmcnt(0)
	v_mfma_f32_16x16x32_bf16 v[124:127], v[128:131], v[172:175], v[124:127]
	v_mfma_f32_16x16x32_bf16 v[120:123], v[136:139], v[172:175], v[120:123]
	v_mfma_f32_16x16x32_bf16 v[112:115], v[128:131], v[188:191], v[112:115]
	v_mfma_f32_16x16x32_bf16 v[104:107], v[136:139], v[188:191], v[104:107]
	v_mfma_f32_16x16x32_bf16 v[96:99], v[128:131], v[206:209], v[96:99]
	v_mfma_f32_16x16x32_bf16 v[88:91], v[136:139], v[206:209], v[88:91]
	v_mfma_f32_16x16x32_bf16 v[80:83], v[128:131], v[214:217], v[80:83]
	v_mfma_f32_16x16x32_bf16 v[72:75], v[136:139], v[214:217], v[72:75]
	v_mfma_f32_16x16x32_bf16 v[124:127], v[132:135], v[176:179], v[124:127]
	v_mfma_f32_16x16x32_bf16 v[120:123], v[140:143], v[176:179], v[120:123]
	v_mfma_f32_16x16x32_bf16 v[112:115], v[132:135], v[202:205], v[112:115]
	v_mfma_f32_16x16x32_bf16 v[104:107], v[140:143], v[202:205], v[104:107]
	v_mfma_f32_16x16x32_bf16 v[96:99], v[132:135], v[210:213], v[96:99]
	v_mfma_f32_16x16x32_bf16 v[88:91], v[140:143], v[210:213], v[88:91]
	v_mfma_f32_16x16x32_bf16 v[80:83], v[132:135], v[218:221], v[80:83]
	v_mfma_f32_16x16x32_bf16 v[72:75], v[140:143], v[218:221], v[72:75]
	s_barrier
	s_add_i32 s91, s91, s54
	v_lshl_add_u64 v[184:185], s[38:39], 0, v[192:193]
	s_mov_b32 m0, s91
	ds_read_b128 v[172:175], v187 offset:16384
	ds_read_b128 v[176:179], v187 offset:17408
	ds_read_b128 v[188:191], v187 offset:18432
	ds_read_b128 v[202:205], v187 offset:19456
	ds_read_b128 v[206:209], v187 offset:20480
	ds_read_b128 v[210:213], v187 offset:21504
	ds_read_b128 v[214:217], v187 offset:22528
	ds_read_b128 v[218:221], v187 offset:23552
	global_load_lds_dwordx4 v[184:185], off
	s_add_i32 m0, s91, 0x2000
	s_add_u32 s92, s38, 0x40000
	v_lshl_add_u64 v[222:223], s[38:39], 0, v[152:153]
	s_addc_u32 s93, s39, 0
	s_add_i32 s91, s94, s54
	global_load_lds_dwordx4 v[222:223], off
	v_lshl_add_u64 v[224:225], s[92:93], 0, v[192:193]
	s_mov_b32 m0, s91
	v_lshl_add_u64 v[226:227], s[56:57], 0, v[154:155]
	global_load_lds_dwordx4 v[224:225], off
	v_lshl_add_u64 v[224:225], s[92:93], 0, v[152:153]
	s_add_i32 m0, s91, 0x2000
	s_nop 0
	global_load_lds_dwordx4 v[224:225], off
	v_lshl_add_u64 v[224:225], s[56:57], 0, v[156:157]
	s_mov_b32 m0, s55
	s_nop 0
	global_load_lds_dwordx4 v[224:225], off
	s_mov_b32 m0, s60
	s_nop 0
	global_load_lds_dwordx4 v[226:227], off
	s_waitcnt vmcnt(8)
	s_waitcnt lgkmcnt(0)
	s_barrier
	s_waitcnt lgkmcnt(0)
	v_mfma_f32_16x16x32_bf16 v[60:63], v[128:131], v[172:175], v[60:63]
	v_mfma_f32_16x16x32_bf16 v[56:59], v[136:139], v[172:175], v[56:59]
	v_mfma_f32_16x16x32_bf16 v[48:51], v[128:131], v[188:191], v[48:51]
	v_mfma_f32_16x16x32_bf16 v[40:43], v[136:139], v[188:191], v[40:43]
	v_mfma_f32_16x16x32_bf16 v[32:35], v[128:131], v[206:209], v[32:35]
	v_mfma_f32_16x16x32_bf16 v[24:27], v[136:139], v[206:209], v[24:27]
	v_mfma_f32_16x16x32_bf16 v[16:19], v[128:131], v[214:217], v[16:19]
	v_mfma_f32_16x16x32_bf16 v[8:11], v[136:139], v[214:217], v[8:11]
	v_mfma_f32_16x16x32_bf16 v[60:63], v[132:135], v[176:179], v[60:63]
	v_mfma_f32_16x16x32_bf16 v[56:59], v[140:143], v[176:179], v[56:59]
	v_mfma_f32_16x16x32_bf16 v[48:51], v[132:135], v[202:205], v[48:51]
	v_mfma_f32_16x16x32_bf16 v[40:43], v[140:143], v[202:205], v[40:43]
	v_mfma_f32_16x16x32_bf16 v[32:35], v[132:135], v[210:213], v[32:35]
	v_mfma_f32_16x16x32_bf16 v[24:27], v[140:143], v[210:213], v[24:27]
	v_mfma_f32_16x16x32_bf16 v[16:19], v[132:135], v[218:221], v[16:19]
	v_mfma_f32_16x16x32_bf16 v[8:11], v[140:143], v[218:221], v[8:11]
	s_barrier
	s_add_i32 s91, 0, 0x18000
	s_add_i32 s92, 0, 0x1c000
	v_add_u32_e32 v140, s91, v183
	v_add_u32_e32 v168, s92, v183
	ds_read_b128 v[128:131], v140
	ds_read_b128 v[132:135], v140 offset:1024
	ds_read_b128 v[136:139], v140 offset:2048
	ds_read_b128 v[140:143], v140 offset:3072
	ds_read_b128 v[144:147], v168
	ds_read_b128 v[148:151], v168 offset:1024
	ds_read_b128 v[164:167], v168 offset:2048
	ds_read_b128 v[168:171], v168 offset:3072
	s_add_u32 s56, s56, 0x40000
	s_addc_u32 s57, s57, 0
	s_mov_b32 m0, s61
	v_lshl_add_u64 v[228:229], s[56:57], 0, v[156:157]
	ds_read_b128 v[172:175], v187 offset:32768
	ds_read_b128 v[176:179], v187 offset:33792
	ds_read_b128 v[188:191], v187 offset:34816
	ds_read_b128 v[202:205], v187 offset:35840
	ds_read_b128 v[206:209], v187 offset:36864
	ds_read_b128 v[210:213], v187 offset:37888
	ds_read_b128 v[214:217], v187 offset:38912
	ds_read_b128 v[218:221], v187 offset:39936
	global_load_lds_dwordx4 v[228:229], off
	v_lshl_add_u64 v[228:229], s[56:57], 0, v[154:155]
	s_mov_b32 m0, s82
	s_nop 0
	global_load_lds_dwordx4 v[228:229], off
	s_waitcnt vmcnt(8)
	s_waitcnt lgkmcnt(0)
	s_barrier
	s_waitcnt lgkmcnt(0)
	v_mfma_f32_16x16x32_bf16 v[124:127], v[128:131], v[172:175], v[124:127]
	v_mfma_f32_16x16x32_bf16 v[120:123], v[136:139], v[172:175], v[120:123]
	v_mfma_f32_16x16x32_bf16 v[112:115], v[128:131], v[188:191], v[112:115]
	v_mfma_f32_16x16x32_bf16 v[104:107], v[136:139], v[188:191], v[104:107]
	v_mfma_f32_16x16x32_bf16 v[96:99], v[128:131], v[206:209], v[96:99]
	v_mfma_f32_16x16x32_bf16 v[88:91], v[136:139], v[206:209], v[88:91]
	v_mfma_f32_16x16x32_bf16 v[80:83], v[128:131], v[214:217], v[80:83]
	v_mfma_f32_16x16x32_bf16 v[72:75], v[136:139], v[214:217], v[72:75]
	v_mfma_f32_16x16x32_bf16 v[124:127], v[132:135], v[176:179], v[124:127]
	v_mfma_f32_16x16x32_bf16 v[120:123], v[140:143], v[176:179], v[120:123]
	v_mfma_f32_16x16x32_bf16 v[112:115], v[132:135], v[202:205], v[112:115]
	v_mfma_f32_16x16x32_bf16 v[104:107], v[140:143], v[202:205], v[104:107]
	v_mfma_f32_16x16x32_bf16 v[96:99], v[132:135], v[210:213], v[96:99]
	v_mfma_f32_16x16x32_bf16 v[88:91], v[140:143], v[210:213], v[88:91]
	v_mfma_f32_16x16x32_bf16 v[80:83], v[132:135], v[218:221], v[80:83]
	v_mfma_f32_16x16x32_bf16 v[72:75], v[140:143], v[218:221], v[72:75]
	s_barrier
	s_add_i32 s56, s91, s54
	v_lshl_add_u64 v[184:185], v[184:185], 0, s[76:77]
	s_mov_b32 m0, s56
	ds_read_b128 v[172:175], v187 offset:49152
	ds_read_b128 v[176:179], v187 offset:50176
	ds_read_b128 v[188:191], v187 offset:51200
	ds_read_b128 v[202:205], v187 offset:52224
	ds_read_b128 v[206:209], v187 offset:53248
	ds_read_b128 v[210:213], v187 offset:54272
	ds_read_b128 v[214:217], v187 offset:55296
	ds_read_b128 v[218:221], v187 offset:56320
	global_load_lds_dwordx4 v[184:185], off
	s_add_i32 m0, s56, 0x2000
	s_add_u32 s38, s38, 0x40080
	v_lshl_add_u64 v[184:185], v[222:223], 0, s[76:77]
	s_addc_u32 s39, s39, 0
	s_add_i32 s56, s92, s54
	global_load_lds_dwordx4 v[184:185], off
	v_lshl_add_u64 v[184:185], s[38:39], 0, v[192:193]
	s_mov_b32 m0, s56
	s_nop 0
	global_load_lds_dwordx4 v[184:185], off
	v_lshl_add_u64 v[184:185], s[38:39], 0, v[152:153]
	s_add_i32 m0, s56, 0x2000
	s_nop 0
	global_load_lds_dwordx4 v[184:185], off
	v_lshl_add_u64 v[184:185], v[224:225], 0, s[76:77]
	s_mov_b32 m0, s68
	s_nop 0
	global_load_lds_dwordx4 v[184:185], off
	v_lshl_add_u64 v[184:185], v[226:227], 0, s[76:77]
	s_mov_b32 m0, s83
	s_nop 0
	global_load_lds_dwordx4 v[184:185], off
	s_waitcnt vmcnt(8)
	s_waitcnt lgkmcnt(0)
	s_barrier
	s_waitcnt lgkmcnt(0)
	v_mfma_f32_16x16x32_bf16 v[60:63], v[128:131], v[172:175], v[60:63]
	v_mfma_f32_16x16x32_bf16 v[56:59], v[136:139], v[172:175], v[56:59]
	v_mfma_f32_16x16x32_bf16 v[48:51], v[128:131], v[188:191], v[48:51]
	v_mfma_f32_16x16x32_bf16 v[40:43], v[136:139], v[188:191], v[40:43]
	v_mfma_f32_16x16x32_bf16 v[32:35], v[128:131], v[206:209], v[32:35]
	v_mfma_f32_16x16x32_bf16 v[24:27], v[136:139], v[206:209], v[24:27]
	v_mfma_f32_16x16x32_bf16 v[16:19], v[128:131], v[214:217], v[16:19]
	v_mfma_f32_16x16x32_bf16 v[8:11], v[136:139], v[214:217], v[8:11]
	v_mfma_f32_16x16x32_bf16 v[60:63], v[132:135], v[176:179], v[60:63]
	v_mfma_f32_16x16x32_bf16 v[56:59], v[140:143], v[176:179], v[56:59]
	v_mfma_f32_16x16x32_bf16 v[48:51], v[132:135], v[202:205], v[48:51]
	v_mfma_f32_16x16x32_bf16 v[40:43], v[140:143], v[202:205], v[40:43]
	v_mfma_f32_16x16x32_bf16 v[32:35], v[132:135], v[210:213], v[32:35]
	v_mfma_f32_16x16x32_bf16 v[24:27], v[140:143], v[210:213], v[24:27]
	v_mfma_f32_16x16x32_bf16 v[16:19], v[132:135], v[218:221], v[16:19]
	v_mfma_f32_16x16x32_bf16 v[8:11], v[140:143], v[218:221], v[8:11]
	s_barrier
	s_add_i32 s90, s90, 2
	s_add_u32 s88, s88, 0x100
	s_addc_u32 s89, s89, 0
	s_add_u32 s8, s8, 0x100
	s_addc_u32 s9, s9, 0
	s_cmp_gt_u32 s90, 13
	s_cbranch_scc0 .Lz258
	s_branch .LBB0_261

.LBB0_255:
	s_cmp_eq_u32 s86, 14
	s_cbranch_scc1 .Lz255
	s_add_u32 s88, s8, 0x100
	s_addc_u32 s89, s9, 0
	s_add_u32 s8, s38, 0x40080
	s_addc_u32 s9, s39, 0
	s_mov_b32 s90, -2
	s_add_u32 s38, s8, 0xfffc0080
	s_addc_u32 s39, s9, -1
	s_add_i32 s91, 0, 0x10000
	s_cmp_eq_u32 s90, 12
	s_cselect_b32 s57, s31, s39
	s_cselect_b32 s56, s47, s38
	s_cselect_b32 s39, s29, s89
	s_cselect_b32 s38, s87, s88
	s_add_i32 s94, 0, 0x14000
	v_add_u32_e32 v140, s91, v183
	v_add_u32_e32 v168, s94, v183
	ds_read_b128 v[128:131], v140
	ds_read_b128 v[132:135], v140 offset:1024
	ds_read_b128 v[136:139], v140 offset:2048
	ds_read_b128 v[140:143], v140 offset:3072
	ds_read_b128 v[144:147], v168
	ds_read_b128 v[148:151], v168 offset:1024
	ds_read_b128 v[164:167], v168 offset:2048
	ds_read_b128 v[168:171], v168 offset:3072
	v_lshl_add_u64 v[184:185], s[8:9], 0, v[162:163]
	s_add_i32 m0, s55, 0xc000
	ds_read_b128 v[172:175], v187
	ds_read_b128 v[176:179], v187 offset:1024
	ds_read_b128 v[188:191], v187 offset:2048
	ds_read_b128 v[202:205], v187 offset:3072
	ds_read_b128 v[206:209], v187 offset:4096
	ds_read_b128 v[210:213], v187 offset:5120
	ds_read_b128 v[214:217], v187 offset:6144
	ds_read_b128 v[218:221], v187 offset:7168
	global_load_lds_dwordx4 v[184:185], off
	v_lshl_add_u64 v[184:185], s[8:9], 0, v[160:161]
	s_add_i32 m0, s55, 0xe000
	s_nop 0
	global_load_lds_dwordx4 v[184:185], off
	s_waitcnt vmcnt(8)
	s_waitcnt lgkmcnt(0)
	s_barrier
	s_waitcnt lgkmcnt(0)
	v_mfma_f32_16x16x32_bf16 v[124:127], v[128:131], v[172:175], 0
	v_mfma_f32_16x16x32_bf16 v[120:123], v[136:139], v[172:175], 0
	v_mfma_f32_16x16x32_bf16 v[112:115], v[128:131], v[188:191], 0
	v_mfma_f32_16x16x32_bf16 v[104:107], v[136:139], v[188:191], 0
	v_mfma_f32_16x16x32_bf16 v[96:99], v[128:131], v[206:209], 0
	v_mfma_f32_16x16x32_bf16 v[88:91], v[136:139], v[206:209], 0
	v_mfma_f32_16x16x32_bf16 v[80:83], v[128:131], v[214:217], 0
	v_mfma_f32_16x16x32_bf16 v[72:75], v[136:139], v[214:217], 0
	v_mfma_f32_16x16x32_bf16 v[124:127], v[132:135], v[176:179], v[124:127]
	v_mfma_f32_16x16x32_bf16 v[120:123], v[140:143], v[176:179], v[120:123]
	v_mfma_f32_16x16x32_bf16 v[112:115], v[132:135], v[202:205], v[112:115]
	v_mfma_f32_16x16x32_bf16 v[104:107], v[140:143], v[202:205], v[104:107]
	v_mfma_f32_16x16x32_bf16 v[96:99], v[132:135], v[210:213], v[96:99]
	v_mfma_f32_16x16x32_bf16 v[88:91], v[140:143], v[210:213], v[88:91]
	v_mfma_f32_16x16x32_bf16 v[80:83], v[132:135], v[218:221], v[80:83]
	v_mfma_f32_16x16x32_bf16 v[72:75], v[140:143], v[218:221], v[72:75]
	v_mfma_f32_16x16x32_bf16 v[116:119], v[144:147], v[172:175], 0
	v_mfma_f32_16x16x32_bf16 v[108:111], v[164:167], v[172:175], 0
	v_mfma_f32_16x16x32_bf16 v[100:103], v[144:147], v[188:191], 0
	v_mfma_f32_16x16x32_bf16 v[92:95], v[164:167], v[188:191], 0
	v_mfma_f32_16x16x32_bf16 v[84:87], v[144:147], v[206:209], 0
	v_mfma_f32_16x16x32_bf16 v[76:79], v[164:167], v[206:209], 0
	v_mfma_f32_16x16x32_bf16 v[68:71], v[144:147], v[214:217], 0
	v_mfma_f32_16x16x32_bf16 v[64:67], v[164:167], v[214:217], 0
	v_mfma_f32_16x16x32_bf16 v[116:119], v[148:151], v[176:179], v[116:119]
	v_mfma_f32_16x16x32_bf16 v[108:111], v[168:171], v[176:179], v[108:111]
	v_mfma_f32_16x16x32_bf16 v[100:103], v[148:151], v[202:205], v[100:103]
	v_mfma_f32_16x16x32_bf16 v[92:95], v[168:171], v[202:205], v[92:95]
	v_mfma_f32_16x16x32_bf16 v[84:87], v[148:151], v[210:213], v[84:87]
	v_mfma_f32_16x16x32_bf16 v[76:79], v[168:171], v[210:213], v[76:79]
	v_mfma_f32_16x16x32_bf16 v[68:71], v[148:151], v[218:221], v[68:71]
	v_mfma_f32_16x16x32_bf16 v[64:67], v[168:171], v[218:221], v[64:67]
	s_barrier
	s_add_i32 s91, s91, s54
	v_lshl_add_u64 v[184:185], s[38:39], 0, v[192:193]
	s_mov_b32 m0, s91
	ds_read_b128 v[172:175], v187 offset:16384
	ds_read_b128 v[176:179], v187 offset:17408
	ds_read_b128 v[188:191], v187 offset:18432
	ds_read_b128 v[202:205], v187 offset:19456
	ds_read_b128 v[206:209], v187 offset:20480
	ds_read_b128 v[210:213], v187 offset:21504
	ds_read_b128 v[214:217], v187 offset:22528
	ds_read_b128 v[218:221], v187 offset:23552
	global_load_lds_dwordx4 v[184:185], off
	s_add_i32 m0, s91, 0x2000
	s_add_u32 s92, s38, 0x40000
	v_lshl_add_u64 v[222:223], s[38:39], 0, v[152:153]
	s_addc_u32 s93, s39, 0
	s_add_i32 s91, s94, s54
	global_load_lds_dwordx4 v[222:223], off
	v_lshl_add_u64 v[224:225], s[92:93], 0, v[192:193]
	s_mov_b32 m0, s91
	v_lshl_add_u64 v[226:227], s[56:57], 0, v[154:155]
	global_load_lds_dwordx4 v[224:225], off
	v_lshl_add_u64 v[224:225], s[92:93], 0, v[152:153]
	s_add_i32 m0, s91, 0x2000
	s_nop 0
	global_load_lds_dwordx4 v[224:225], off
	v_lshl_add_u64 v[224:225], s[56:57], 0, v[156:157]
	s_mov_b32 m0, s55
	s_nop 0
	global_load_lds_dwordx4 v[224:225], off
	s_mov_b32 m0, s60
	s_nop 0
	global_load_lds_dwordx4 v[226:227], off
	s_add_i32 s85, s85, 1
	s_mul_i32 s6, s85, s43
	s_mul_hi_u32 s7, s85, s42
	s_add_i32 s7, s7, s6
	s_mul_i32 s6, s85, s42
	s_add_u32 s34, s6, s2
	s_addc_u32 s35, s7, s41
	v_mov_b64_e32 v[0:1], 0xf00
	v_cmp_lt_i64_e64 s[6:7], s[34:35], v[0:1]
	v_mov_b64_e32 v[0:1], 0xeff
	v_cmp_gt_i64_e32 vcc, s[34:35], v[0:1]
	s_cbranch_vccnz .LBB0_257
	s_ashr_i32 s28, s34, 31
	s_lshr_b32 s28, s28, 29
	s_add_i32 s28, s34, s28
	s_ashr_i32 s29, s28, 3
	s_and_b32 s28, s28, -8
	s_sub_i32 s28, s34, s28
	s_cmp_lt_i32 s28, 0
	s_movk_i32 s30, 0x1e1
	s_cselect_b32 s30, s30, 0x1e0
	s_mul_i32 s28, s28, s30
	s_add_i32 s28, s28, s29
	s_mul_hi_i32 s29, s28, 0x88888889
	s_add_i32 s29, s29, s28
	s_lshr_b32 s30, s29, 31
	s_ashr_i32 s29, s29, 6
	s_add_i32 s29, s29, s30
	s_lshl_b32 s30, s29, 3
	s_sub_i32 s31, 0x100, s30
	s_min_i32 s31, s31, 8
	s_abs_i32 s34, s31
	v_cvt_f32_u32_e32 v0, s34
	s_sub_i32 s36, 0, s34
	s_mulk_i32 s29, 0x78
	s_sub_i32 s29, s28, s29
	v_rcp_iflag_f32_e32 v0, v0
	s_abs_i32 s28, s29
	s_xor_b32 s35, s29, s31
	s_ashr_i32 s35, s35, 31
	v_mul_f32_e32 v0, 0x4f7ffffe, v0
	v_cvt_u32_f32_e32 v0, v0
	s_nop 0
	v_readfirstlane_b32 s37, v0
	s_mul_i32 s36, s36, s37
	s_mul_hi_u32 s36, s37, s36
	s_add_i32 s37, s37, s36
	s_mul_hi_u32 s36, s28, s37
	s_mul_i32 s37, s36, s34
	s_sub_i32 s28, s28, s37
	s_add_i32 s47, s36, 1
	s_sub_i32 s37, s28, s34
	s_cmp_ge_u32 s28, s34
	s_cselect_b32 s36, s47, s36
	s_cselect_b32 s28, s37, s28
	s_add_i32 s37, s36, 1
	s_cmp_ge_u32 s28, s34
	s_cselect_b32 s28, s37, s36
	s_xor_b32 s28, s28, s35
	s_sub_i32 s28, s28, s35
	s_mul_i32 s31, s28, s31
	s_sub_i32 s29, s29, s31
	s_add_i32 s30, s30, s29
.LBB0_257:
	s_ashr_i32 s31, s30, 31
	s_lshl_b64 s[34:35], s[30:31], 19
	s_add_u32 s34, s48, s34
	s_addc_u32 s35, s49, s35
	s_and_b64 s[36:37], s[6:7], exec
	s_cselect_b32 s31, s35, s57
	s_cselect_b32 s47, s34, s56
	s_ashr_i32 s29, s28, 31
	s_lshl_b64 s[36:37], s[28:29], 19
	s_add_u32 s36, s50, s36
	s_addc_u32 s37, s51, s37
	s_and_b64 s[100:101], s[6:7], exec
	s_cselect_b32 s29, s37, s89
	s_cselect_b32 s87, s36, s88
	s_waitcnt vmcnt(8)
	s_waitcnt lgkmcnt(0)
	s_barrier
	s_waitcnt lgkmcnt(0)
	v_mfma_f32_16x16x32_bf16 v[60:63], v[128:131], v[172:175], 0
	v_mfma_f32_16x16x32_bf16 v[56:59], v[136:139], v[172:175], 0
	v_mfma_f32_16x16x32_bf16 v[48:51], v[128:131], v[188:191], 0
	v_mfma_f32_16x16x32_bf16 v[40:43], v[136:139], v[188:191], 0
	v_mfma_f32_16x16x32_bf16 v[32:35], v[128:131], v[206:209], 0
	v_mfma_f32_16x16x32_bf16 v[24:27], v[136:139], v[206:209], 0
	v_mfma_f32_16x16x32_bf16 v[16:19], v[128:131], v[214:217], 0
	v_mfma_f32_16x16x32_bf16 v[8:11], v[136:139], v[214:217], 0
	v_mfma_f32_16x16x32_bf16 v[60:63], v[132:135], v[176:179], v[60:63]
	v_mfma_f32_16x16x32_bf16 v[56:59], v[140:143], v[176:179], v[56:59]
	v_mfma_f32_16x16x32_bf16 v[48:51], v[132:135], v[202:205], v[48:51]
	v_mfma_f32_16x16x32_bf16 v[40:43], v[140:143], v[202:205], v[40:43]
	v_mfma_f32_16x16x32_bf16 v[32:35], v[132:135], v[210:213], v[32:35]
	v_mfma_f32_16x16x32_bf16 v[24:27], v[140:143], v[210:213], v[24:27]
	v_mfma_f32_16x16x32_bf16 v[16:19], v[132:135], v[218:221], v[16:19]
	v_mfma_f32_16x16x32_bf16 v[8:11], v[140:143], v[218:221], v[8:11]
	v_mfma_f32_16x16x32_bf16 v[52:55], v[144:147], v[172:175], 0
	v_mfma_f32_16x16x32_bf16 v[44:47], v[164:167], v[172:175], 0
	v_mfma_f32_16x16x32_bf16 v[36:39], v[144:147], v[188:191], 0
	v_mfma_f32_16x16x32_bf16 v[28:31], v[164:167], v[188:191], 0
	v_mfma_f32_16x16x32_bf16 v[20:23], v[144:147], v[206:209], 0
	v_mfma_f32_16x16x32_bf16 v[12:15], v[164:167], v[206:209], 0
	v_mfma_f32_16x16x32_bf16 v[4:7], v[144:147], v[214:217], 0
	v_mfma_f32_16x16x32_bf16 v[0:3], v[164:167], v[214:217], 0
	v_mfma_f32_16x16x32_bf16 v[52:55], v[148:151], v[176:179], v[52:55]
	v_mfma_f32_16x16x32_bf16 v[44:47], v[168:171], v[176:179], v[44:47]
	v_mfma_f32_16x16x32_bf16 v[36:39], v[148:151], v[202:205], v[36:39]
	v_mfma_f32_16x16x32_bf16 v[28:31], v[168:171], v[202:205], v[28:31]
	v_mfma_f32_16x16x32_bf16 v[20:23], v[148:151], v[210:213], v[20:23]
	v_mfma_f32_16x16x32_bf16 v[12:15], v[168:171], v[210:213], v[12:15]
	v_mfma_f32_16x16x32_bf16 v[4:7], v[148:151], v[218:221], v[4:7]
	v_mfma_f32_16x16x32_bf16 v[0:3], v[168:171], v[218:221], v[0:3]
	s_barrier
	s_add_i32 s91, 0, 0x18000
	s_add_i32 s92, 0, 0x1c000
	v_add_u32_e32 v140, s91, v183
	v_add_u32_e32 v168, s92, v183
	ds_read_b128 v[128:131], v140
	ds_read_b128 v[132:135], v140 offset:1024
	ds_read_b128 v[136:139], v140 offset:2048
	ds_read_b128 v[140:143], v140 offset:3072
	ds_read_b128 v[144:147], v168
	ds_read_b128 v[148:151], v168 offset:1024
	ds_read_b128 v[164:167], v168 offset:2048
	ds_read_b128 v[168:171], v168 offset:3072
	s_add_u32 s56, s56, 0x40000
	s_addc_u32 s57, s57, 0
	s_mov_b32 m0, s61
	v_lshl_add_u64 v[228:229], s[56:57], 0, v[156:157]
	ds_read_b128 v[172:175], v187 offset:32768
	ds_read_b128 v[176:179], v187 offset:33792
	ds_read_b128 v[188:191], v187 offset:34816
	ds_read_b128 v[202:205], v187 offset:35840
	ds_read_b128 v[206:209], v187 offset:36864
	ds_read_b128 v[210:213], v187 offset:37888
	ds_read_b128 v[214:217], v187 offset:38912
	ds_read_b128 v[218:221], v187 offset:39936
	global_load_lds_dwordx4 v[228:229], off
	v_lshl_add_u64 v[228:229], s[56:57], 0, v[154:155]
	s_mov_b32 m0, s82
	s_nop 0
	global_load_lds_dwordx4 v[228:229], off
	s_waitcnt vmcnt(8)
	s_waitcnt lgkmcnt(0)
	s_barrier
	s_waitcnt lgkmcnt(0)
	v_mfma_f32_16x16x32_bf16 v[124:127], v[128:131], v[172:175], v[124:127]
	v_mfma_f32_16x16x32_bf16 v[120:123], v[136:139], v[172:175], v[120:123]
	v_mfma_f32_16x16x32_bf16 v[112:115], v[128:131], v[188:191], v[112:115]
	v_mfma_f32_16x16x32_bf16 v[104:107], v[136:139], v[188:191], v[104:107]
	v_mfma_f32_16x16x32_bf16 v[96:99], v[128:131], v[206:209], v[96:99]
	v_mfma_f32_16x16x32_bf16 v[88:91], v[136:139], v[206:209], v[88:91]
	v_mfma_f32_16x16x32_bf16 v[80:83], v[128:131], v[214:217], v[80:83]
	v_mfma_f32_16x16x32_bf16 v[72:75], v[136:139], v[214:217], v[72:75]
	v_mfma_f32_16x16x32_bf16 v[124:127], v[132:135], v[176:179], v[124:127]
	v_mfma_f32_16x16x32_bf16 v[120:123], v[140:143], v[176:179], v[120:123]
	v_mfma_f32_16x16x32_bf16 v[112:115], v[132:135], v[202:205], v[112:115]
	v_mfma_f32_16x16x32_bf16 v[104:107], v[140:143], v[202:205], v[104:107]
	v_mfma_f32_16x16x32_bf16 v[96:99], v[132:135], v[210:213], v[96:99]
	v_mfma_f32_16x16x32_bf16 v[88:91], v[140:143], v[210:213], v[88:91]
	v_mfma_f32_16x16x32_bf16 v[80:83], v[132:135], v[218:221], v[80:83]
	v_mfma_f32_16x16x32_bf16 v[72:75], v[140:143], v[218:221], v[72:75]
	v_mfma_f32_16x16x32_bf16 v[116:119], v[144:147], v[172:175], v[116:119]
	v_mfma_f32_16x16x32_bf16 v[108:111], v[164:167], v[172:175], v[108:111]
	v_mfma_f32_16x16x32_bf16 v[100:103], v[144:147], v[188:191], v[100:103]
	v_mfma_f32_16x16x32_bf16 v[92:95], v[164:167], v[188:191], v[92:95]
	v_mfma_f32_16x16x32_bf16 v[84:87], v[144:147], v[206:209], v[84:87]
	v_mfma_f32_16x16x32_bf16 v[76:79], v[164:167], v[206:209], v[76:79]
	v_mfma_f32_16x16x32_bf16 v[68:71], v[144:147], v[214:217], v[68:71]
	v_mfma_f32_16x16x32_bf16 v[64:67], v[164:167], v[214:217], v[64:67]
	v_mfma_f32_16x16x32_bf16 v[116:119], v[148:151], v[176:179], v[116:119]
	v_mfma_f32_16x16x32_bf16 v[108:111], v[168:171], v[176:179], v[108:111]
	v_mfma_f32_16x16x32_bf16 v[100:103], v[148:151], v[202:205], v[100:103]
	v_mfma_f32_16x16x32_bf16 v[92:95], v[168:171], v[202:205], v[92:95]
	v_mfma_f32_16x16x32_bf16 v[84:87], v[148:151], v[210:213], v[84:87]
	v_mfma_f32_16x16x32_bf16 v[76:79], v[168:171], v[210:213], v[76:79]
	v_mfma_f32_16x16x32_bf16 v[68:71], v[148:151], v[218:221], v[68:71]
	v_mfma_f32_16x16x32_bf16 v[64:67], v[168:171], v[218:221], v[64:67]
	s_barrier
	s_add_i32 s56, s91, s54
	v_lshl_add_u64 v[184:185], v[184:185], 0, s[76:77]
	s_mov_b32 m0, s56
	ds_read_b128 v[172:175], v187 offset:49152
	ds_read_b128 v[176:179], v187 offset:50176
	ds_read_b128 v[188:191], v187 offset:51200
	ds_read_b128 v[202:205], v187 offset:52224
	ds_read_b128 v[206:209], v187 offset:53248
	ds_read_b128 v[210:213], v187 offset:54272
	ds_read_b128 v[214:217], v187 offset:55296
	ds_read_b128 v[218:221], v187 offset:56320
	global_load_lds_dwordx4 v[184:185], off
	s_add_i32 m0, s56, 0x2000
	s_add_u32 s38, s38, 0x40080
	v_lshl_add_u64 v[184:185], v[222:223], 0, s[76:77]
	s_addc_u32 s39, s39, 0
	s_add_i32 s56, s92, s54
	global_load_lds_dwordx4 v[184:185], off
	v_lshl_add_u64 v[184:185], s[38:39], 0, v[192:193]
	s_mov_b32 m0, s56
	s_nop 0
	global_load_lds_dwordx4 v[184:185], off
	v_lshl_add_u64 v[184:185], s[38:39], 0, v[152:153]
	s_add_i32 m0, s56, 0x2000
	s_nop 0
	global_load_lds_dwordx4 v[184:185], off
	v_lshl_add_u64 v[184:185], v[224:225], 0, s[76:77]
	s_mov_b32 m0, s68
	s_nop 0
	global_load_lds_dwordx4 v[184:185], off
	v_lshl_add_u64 v[184:185], v[226:227], 0, s[76:77]
	s_mov_b32 m0, s83
	s_nop 0
	global_load_lds_dwordx4 v[184:185], off
	s_waitcnt vmcnt(8)
	s_waitcnt lgkmcnt(0)
	s_barrier
	s_waitcnt lgkmcnt(0)
	v_mfma_f32_16x16x32_bf16 v[60:63], v[128:131], v[172:175], v[60:63]
	v_mfma_f32_16x16x32_bf16 v[56:59], v[136:139], v[172:175], v[56:59]
	v_mfma_f32_16x16x32_bf16 v[48:51], v[128:131], v[188:191], v[48:51]
	v_mfma_f32_16x16x32_bf16 v[40:43], v[136:139], v[188:191], v[40:43]
	v_mfma_f32_16x16x32_bf16 v[32:35], v[128:131], v[206:209], v[32:35]
	v_mfma_f32_16x16x32_bf16 v[24:27], v[136:139], v[206:209], v[24:27]
	v_mfma_f32_16x16x32_bf16 v[16:19], v[128:131], v[214:217], v[16:19]
	v_mfma_f32_16x16x32_bf16 v[8:11], v[136:139], v[214:217], v[8:11]
	v_mfma_f32_16x16x32_bf16 v[60:63], v[132:135], v[176:179], v[60:63]
	v_mfma_f32_16x16x32_bf16 v[56:59], v[140:143], v[176:179], v[56:59]
	v_mfma_f32_16x16x32_bf16 v[48:51], v[132:135], v[202:205], v[48:51]
	v_mfma_f32_16x16x32_bf16 v[40:43], v[140:143], v[202:205], v[40:43]
	v_mfma_f32_16x16x32_bf16 v[32:35], v[132:135], v[210:213], v[32:35]
	v_mfma_f32_16x16x32_bf16 v[24:27], v[140:143], v[210:213], v[24:27]
	v_mfma_f32_16x16x32_bf16 v[16:19], v[132:135], v[218:221], v[16:19]
	v_mfma_f32_16x16x32_bf16 v[8:11], v[140:143], v[218:221], v[8:11]
	v_mfma_f32_16x16x32_bf16 v[52:55], v[144:147], v[172:175], v[52:55]
	v_mfma_f32_16x16x32_bf16 v[44:47], v[164:167], v[172:175], v[44:47]
	v_mfma_f32_16x16x32_bf16 v[36:39], v[144:147], v[188:191], v[36:39]
	v_mfma_f32_16x16x32_bf16 v[28:31], v[164:167], v[188:191], v[28:31]
	v_mfma_f32_16x16x32_bf16 v[20:23], v[144:147], v[206:209], v[20:23]
	v_mfma_f32_16x16x32_bf16 v[12:15], v[164:167], v[206:209], v[12:15]
	v_mfma_f32_16x16x32_bf16 v[4:7], v[144:147], v[214:217], v[4:7]
	v_mfma_f32_16x16x32_bf16 v[0:3], v[164:167], v[214:217], v[0:3]
	v_mfma_f32_16x16x32_bf16 v[52:55], v[148:151], v[176:179], v[52:55]
	v_mfma_f32_16x16x32_bf16 v[44:47], v[168:171], v[176:179], v[44:47]
	v_mfma_f32_16x16x32_bf16 v[36:39], v[148:151], v[202:205], v[36:39]
	v_mfma_f32_16x16x32_bf16 v[28:31], v[168:171], v[202:205], v[28:31]
	v_mfma_f32_16x16x32_bf16 v[20:23], v[148:151], v[210:213], v[20:23]
	v_mfma_f32_16x16x32_bf16 v[12:15], v[168:171], v[210:213], v[12:15]
	v_mfma_f32_16x16x32_bf16 v[4:7], v[148:151], v[218:221], v[4:7]
	v_mfma_f32_16x16x32_bf16 v[0:3], v[168:171], v[218:221], v[0:3]
	s_barrier
	s_add_i32 s90, s90, 2
	s_add_u32 s88, s88, 0x100
	s_addc_u32 s89, s89, 0
	s_add_u32 s8, s8, 0x100
	s_addc_u32 s9, s9, 0
	s_cmp_gt_u32 s90, 13
.LBB0_258:
	s_add_u32 s38, s8, 0xfffc0080
	s_addc_u32 s39, s9, -1
	s_add_i32 s91, 0, 0x10000
	s_cmp_eq_u32 s90, 12
	s_cselect_b32 s57, s31, s39
	s_cselect_b32 s56, s47, s38
	s_cselect_b32 s39, s29, s89
	s_cselect_b32 s38, s87, s88
	s_add_i32 s94, 0, 0x14000
	v_add_u32_e32 v140, s91, v183
	v_add_u32_e32 v168, s94, v183
	ds_read_b128 v[128:131], v140
	ds_read_b128 v[132:135], v140 offset:1024
	ds_read_b128 v[136:139], v140 offset:2048
	ds_read_b128 v[140:143], v140 offset:3072
	ds_read_b128 v[144:147], v168
	ds_read_b128 v[148:151], v168 offset:1024
	ds_read_b128 v[164:167], v168 offset:2048
	ds_read_b128 v[168:171], v168 offset:3072
	v_lshl_add_u64 v[184:185], s[8:9], 0, v[162:163]
	s_add_i32 m0, s55, 0xc000
	ds_read_b128 v[172:175], v187
	ds_read_b128 v[176:179], v187 offset:1024
	ds_read_b128 v[188:191], v187 offset:2048
	ds_read_b128 v[202:205], v187 offset:3072
	ds_read_b128 v[206:209], v187 offset:4096
	ds_read_b128 v[210:213], v187 offset:5120
	ds_read_b128 v[214:217], v187 offset:6144
	ds_read_b128 v[218:221], v187 offset:7168
	global_load_lds_dwordx4 v[184:185], off
	v_lshl_add_u64 v[184:185], s[8:9], 0, v[160:161]
	s_add_i32 m0, s55, 0xe000
	s_nop 0
	global_load_lds_dwordx4 v[184:185], off
	s_waitcnt vmcnt(8)
	s_waitcnt lgkmcnt(0)
	s_barrier
	s_waitcnt lgkmcnt(0)
	v_mfma_f32_16x16x32_bf16 v[124:127], v[128:131], v[172:175], v[124:127]
	v_mfma_f32_16x16x32_bf16 v[120:123], v[136:139], v[172:175], v[120:123]
	v_mfma_f32_16x16x32_bf16 v[112:115], v[128:131], v[188:191], v[112:115]
	v_mfma_f32_16x16x32_bf16 v[104:107], v[136:139], v[188:191], v[104:107]
	v_mfma_f32_16x16x32_bf16 v[96:99], v[128:131], v[206:209], v[96:99]
	v_mfma_f32_16x16x32_bf16 v[88:91], v[136:139], v[206:209], v[88:91]
	v_mfma_f32_16x16x32_bf16 v[80:83], v[128:131], v[214:217], v[80:83]
	v_mfma_f32_16x16x32_bf16 v[72:75], v[136:139], v[214:217], v[72:75]
	v_mfma_f32_16x16x32_bf16 v[124:127], v[132:135], v[176:179], v[124:127]
	v_mfma_f32_16x16x32_bf16 v[120:123], v[140:143], v[176:179], v[120:123]
	v_mfma_f32_16x16x32_bf16 v[112:115], v[132:135], v[202:205], v[112:115]
	v_mfma_f32_16x16x32_bf16 v[104:107], v[140:143], v[202:205], v[104:107]
	v_mfma_f32_16x16x32_bf16 v[96:99], v[132:135], v[210:213], v[96:99]
	v_mfma_f32_16x16x32_bf16 v[88:91], v[140:143], v[210:213], v[88:91]
	v_mfma_f32_16x16x32_bf16 v[80:83], v[132:135], v[218:221], v[80:83]
	v_mfma_f32_16x16x32_bf16 v[72:75], v[140:143], v[218:221], v[72:75]
	v_mfma_f32_16x16x32_bf16 v[116:119], v[144:147], v[172:175], v[116:119]
	v_mfma_f32_16x16x32_bf16 v[108:111], v[164:167], v[172:175], v[108:111]
	v_mfma_f32_16x16x32_bf16 v[100:103], v[144:147], v[188:191], v[100:103]
	v_mfma_f32_16x16x32_bf16 v[92:95], v[164:167], v[188:191], v[92:95]
	v_mfma_f32_16x16x32_bf16 v[84:87], v[144:147], v[206:209], v[84:87]
	v_mfma_f32_16x16x32_bf16 v[76:79], v[164:167], v[206:209], v[76:79]
	v_mfma_f32_16x16x32_bf16 v[68:71], v[144:147], v[214:217], v[68:71]
	v_mfma_f32_16x16x32_bf16 v[64:67], v[164:167], v[214:217], v[64:67]
	v_mfma_f32_16x16x32_bf16 v[116:119], v[148:151], v[176:179], v[116:119]
	v_mfma_f32_16x16x32_bf16 v[108:111], v[168:171], v[176:179], v[108:111]
	v_mfma_f32_16x16x32_bf16 v[100:103], v[148:151], v[202:205], v[100:103]
	v_mfma_f32_16x16x32_bf16 v[92:95], v[168:171], v[202:205], v[92:95]
	v_mfma_f32_16x16x32_bf16 v[84:87], v[148:151], v[210:213], v[84:87]
	v_mfma_f32_16x16x32_bf16 v[76:79], v[168:171], v[210:213], v[76:79]
	v_mfma_f32_16x16x32_bf16 v[68:71], v[148:151], v[218:221], v[68:71]
	v_mfma_f32_16x16x32_bf16 v[64:67], v[168:171], v[218:221], v[64:67]
	s_barrier
	s_add_i32 s91, s91, s54
	v_lshl_add_u64 v[184:185], s[38:39], 0, v[192:193]
	s_mov_b32 m0, s91
	ds_read_b128 v[172:175], v187 offset:16384
	ds_read_b128 v[176:179], v187 offset:17408
	ds_read_b128 v[188:191], v187 offset:18432
	ds_read_b128 v[202:205], v187 offset:19456
	ds_read_b128 v[206:209], v187 offset:20480
	ds_read_b128 v[210:213], v187 offset:21504
	ds_read_b128 v[214:217], v187 offset:22528
	ds_read_b128 v[218:221], v187 offset:23552
	global_load_lds_dwordx4 v[184:185], off
	s_add_i32 m0, s91, 0x2000
	s_add_u32 s92, s38, 0x40000
	v_lshl_add_u64 v[222:223], s[38:39], 0, v[152:153]
	s_addc_u32 s93, s39, 0
	s_add_i32 s91, s94, s54
	global_load_lds_dwordx4 v[222:223], off
	v_lshl_add_u64 v[224:225], s[92:93], 0, v[192:193]
	s_mov_b32 m0, s91
	v_lshl_add_u64 v[226:227], s[56:57], 0, v[154:155]
	global_load_lds_dwordx4 v[224:225], off
	v_lshl_add_u64 v[224:225], s[92:93], 0, v[152:153]
	s_add_i32 m0, s91, 0x2000
	s_nop 0
	global_load_lds_dwordx4 v[224:225], off
	v_lshl_add_u64 v[224:225], s[56:57], 0, v[156:157]
	s_mov_b32 m0, s55
	s_nop 0
	global_load_lds_dwordx4 v[224:225], off
	s_mov_b32 m0, s60
	s_nop 0
	global_load_lds_dwordx4 v[226:227], off
	s_waitcnt vmcnt(8)
	s_waitcnt lgkmcnt(0)
	s_barrier
	s_waitcnt lgkmcnt(0)
	v_mfma_f32_16x16x32_bf16 v[60:63], v[128:131], v[172:175], v[60:63]
	v_mfma_f32_16x16x32_bf16 v[56:59], v[136:139], v[172:175], v[56:59]
	v_mfma_f32_16x16x32_bf16 v[48:51], v[128:131], v[188:191], v[48:51]
	v_mfma_f32_16x16x32_bf16 v[40:43], v[136:139], v[188:191], v[40:43]
	v_mfma_f32_16x16x32_bf16 v[32:35], v[128:131], v[206:209], v[32:35]
	v_mfma_f32_16x16x32_bf16 v[24:27], v[136:139], v[206:209], v[24:27]
	v_mfma_f32_16x16x32_bf16 v[16:19], v[128:131], v[214:217], v[16:19]
	v_mfma_f32_16x16x32_bf16 v[8:11], v[136:139], v[214:217], v[8:11]
	v_mfma_f32_16x16x32_bf16 v[60:63], v[132:135], v[176:179], v[60:63]
	v_mfma_f32_16x16x32_bf16 v[56:59], v[140:143], v[176:179], v[56:59]
	v_mfma_f32_16x16x32_bf16 v[48:51], v[132:135], v[202:205], v[48:51]
	v_mfma_f32_16x16x32_bf16 v[40:43], v[140:143], v[202:205], v[40:43]
	v_mfma_f32_16x16x32_bf16 v[32:35], v[132:135], v[210:213], v[32:35]
	v_mfma_f32_16x16x32_bf16 v[24:27], v[140:143], v[210:213], v[24:27]
	v_mfma_f32_16x16x32_bf16 v[16:19], v[132:135], v[218:221], v[16:19]
	v_mfma_f32_16x16x32_bf16 v[8:11], v[140:143], v[218:221], v[8:11]
	v_mfma_f32_16x16x32_bf16 v[52:55], v[144:147], v[172:175], v[52:55]
	v_mfma_f32_16x16x32_bf16 v[44:47], v[164:167], v[172:175], v[44:47]
	v_mfma_f32_16x16x32_bf16 v[36:39], v[144:147], v[188:191], v[36:39]
	v_mfma_f32_16x16x32_bf16 v[28:31], v[164:167], v[188:191], v[28:31]
	v_mfma_f32_16x16x32_bf16 v[20:23], v[144:147], v[206:209], v[20:23]
	v_mfma_f32_16x16x32_bf16 v[12:15], v[164:167], v[206:209], v[12:15]
	v_mfma_f32_16x16x32_bf16 v[4:7], v[144:147], v[214:217], v[4:7]
	v_mfma_f32_16x16x32_bf16 v[0:3], v[164:167], v[214:217], v[0:3]
	v_mfma_f32_16x16x32_bf16 v[52:55], v[148:151], v[176:179], v[52:55]
	v_mfma_f32_16x16x32_bf16 v[44:47], v[168:171], v[176:179], v[44:47]
	v_mfma_f32_16x16x32_bf16 v[36:39], v[148:151], v[202:205], v[36:39]
	v_mfma_f32_16x16x32_bf16 v[28:31], v[168:171], v[202:205], v[28:31]
	v_mfma_f32_16x16x32_bf16 v[20:23], v[148:151], v[210:213], v[20:23]
	v_mfma_f32_16x16x32_bf16 v[12:15], v[168:171], v[210:213], v[12:15]
	v_mfma_f32_16x16x32_bf16 v[4:7], v[148:151], v[218:221], v[4:7]
	v_mfma_f32_16x16x32_bf16 v[0:3], v[168:171], v[218:221], v[0:3]
	s_barrier
	s_add_i32 s91, 0, 0x18000
	s_add_i32 s92, 0, 0x1c000
	v_add_u32_e32 v140, s91, v183
	v_add_u32_e32 v168, s92, v183
	ds_read_b128 v[128:131], v140
	ds_read_b128 v[132:135], v140 offset:1024
	ds_read_b128 v[136:139], v140 offset:2048
	ds_read_b128 v[140:143], v140 offset:3072
	ds_read_b128 v[144:147], v168
	ds_read_b128 v[148:151], v168 offset:1024
	ds_read_b128 v[164:167], v168 offset:2048
	ds_read_b128 v[168:171], v168 offset:3072
	s_add_u32 s56, s56, 0x40000
	s_addc_u32 s57, s57, 0
	s_mov_b32 m0, s61
	v_lshl_add_u64 v[228:229], s[56:57], 0, v[156:157]
	ds_read_b128 v[172:175], v187 offset:32768
	ds_read_b128 v[176:179], v187 offset:33792
	ds_read_b128 v[188:191], v187 offset:34816
	ds_read_b128 v[202:205], v187 offset:35840
	ds_read_b128 v[206:209], v187 offset:36864
	ds_read_b128 v[210:213], v187 offset:37888
	ds_read_b128 v[214:217], v187 offset:38912
	ds_read_b128 v[218:221], v187 offset:39936
	global_load_lds_dwordx4 v[228:229], off
	v_lshl_add_u64 v[228:229], s[56:57], 0, v[154:155]
	s_mov_b32 m0, s82
	s_nop 0
	global_load_lds_dwordx4 v[228:229], off
	s_waitcnt vmcnt(8)
	s_waitcnt lgkmcnt(0)
	s_barrier
	s_waitcnt lgkmcnt(0)
	v_mfma_f32_16x16x32_bf16 v[124:127], v[128:131], v[172:175], v[124:127]
	v_mfma_f32_16x16x32_bf16 v[120:123], v[136:139], v[172:175], v[120:123]
	v_mfma_f32_16x16x32_bf16 v[112:115], v[128:131], v[188:191], v[112:115]
	v_mfma_f32_16x16x32_bf16 v[104:107], v[136:139], v[188:191], v[104:107]
	v_mfma_f32_16x16x32_bf16 v[96:99], v[128:131], v[206:209], v[96:99]
	v_mfma_f32_16x16x32_bf16 v[88:91], v[136:139], v[206:209], v[88:91]
	v_mfma_f32_16x16x32_bf16 v[80:83], v[128:131], v[214:217], v[80:83]
	v_mfma_f32_16x16x32_bf16 v[72:75], v[136:139], v[214:217], v[72:75]
	v_mfma_f32_16x16x32_bf16 v[124:127], v[132:135], v[176:179], v[124:127]
	v_mfma_f32_16x16x32_bf16 v[120:123], v[140:143], v[176:179], v[120:123]
	v_mfma_f32_16x16x32_bf16 v[112:115], v[132:135], v[202:205], v[112:115]
	v_mfma_f32_16x16x32_bf16 v[104:107], v[140:143], v[202:205], v[104:107]
	v_mfma_f32_16x16x32_bf16 v[96:99], v[132:135], v[210:213], v[96:99]
	v_mfma_f32_16x16x32_bf16 v[88:91], v[140:143], v[210:213], v[88:91]
	v_mfma_f32_16x16x32_bf16 v[80:83], v[132:135], v[218:221], v[80:83]
	v_mfma_f32_16x16x32_bf16 v[72:75], v[140:143], v[218:221], v[72:75]
	v_mfma_f32_16x16x32_bf16 v[116:119], v[144:147], v[172:175], v[116:119]
	v_mfma_f32_16x16x32_bf16 v[108:111], v[164:167], v[172:175], v[108:111]
	v_mfma_f32_16x16x32_bf16 v[100:103], v[144:147], v[188:191], v[100:103]
	v_mfma_f32_16x16x32_bf16 v[92:95], v[164:167], v[188:191], v[92:95]
	v_mfma_f32_16x16x32_bf16 v[84:87], v[144:147], v[206:209], v[84:87]
	v_mfma_f32_16x16x32_bf16 v[76:79], v[164:167], v[206:209], v[76:79]
	v_mfma_f32_16x16x32_bf16 v[68:71], v[144:147], v[214:217], v[68:71]
	v_mfma_f32_16x16x32_bf16 v[64:67], v[164:167], v[214:217], v[64:67]
	v_mfma_f32_16x16x32_bf16 v[116:119], v[148:151], v[176:179], v[116:119]
	v_mfma_f32_16x16x32_bf16 v[108:111], v[168:171], v[176:179], v[108:111]
	v_mfma_f32_16x16x32_bf16 v[100:103], v[148:151], v[202:205], v[100:103]
	v_mfma_f32_16x16x32_bf16 v[92:95], v[168:171], v[202:205], v[92:95]
	v_mfma_f32_16x16x32_bf16 v[84:87], v[148:151], v[210:213], v[84:87]
	v_mfma_f32_16x16x32_bf16 v[76:79], v[168:171], v[210:213], v[76:79]
	v_mfma_f32_16x16x32_bf16 v[68:71], v[148:151], v[218:221], v[68:71]
	v_mfma_f32_16x16x32_bf16 v[64:67], v[168:171], v[218:221], v[64:67]
	s_barrier
	s_add_i32 s56, s91, s54
	v_lshl_add_u64 v[184:185], v[184:185], 0, s[76:77]
	s_mov_b32 m0, s56
	ds_read_b128 v[172:175], v187 offset:49152
	ds_read_b128 v[176:179], v187 offset:50176
	ds_read_b128 v[188:191], v187 offset:51200
	ds_read_b128 v[202:205], v187 offset:52224
	ds_read_b128 v[206:209], v187 offset:53248
	ds_read_b128 v[210:213], v187 offset:54272
	ds_read_b128 v[214:217], v187 offset:55296
	ds_read_b128 v[218:221], v187 offset:56320
	global_load_lds_dwordx4 v[184:185], off
	s_add_i32 m0, s56, 0x2000
	s_add_u32 s38, s38, 0x40080
	v_lshl_add_u64 v[184:185], v[222:223], 0, s[76:77]
	s_addc_u32 s39, s39, 0
	s_add_i32 s56, s92, s54
	global_load_lds_dwordx4 v[184:185], off
	v_lshl_add_u64 v[184:185], s[38:39], 0, v[192:193]
	s_mov_b32 m0, s56
	s_nop 0
	global_load_lds_dwordx4 v[184:185], off
	v_lshl_add_u64 v[184:185], s[38:39], 0, v[152:153]
	s_add_i32 m0, s56, 0x2000
	s_nop 0
	global_load_lds_dwordx4 v[184:185], off
	v_lshl_add_u64 v[184:185], v[224:225], 0, s[76:77]
	s_mov_b32 m0, s68
	s_nop 0
	global_load_lds_dwordx4 v[184:185], off
	v_lshl_add_u64 v[184:185], v[226:227], 0, s[76:77]
	s_mov_b32 m0, s83
	s_nop 0
	global_load_lds_dwordx4 v[184:185], off
	s_waitcnt vmcnt(8)
	s_waitcnt lgkmcnt(0)
	s_barrier
	s_waitcnt lgkmcnt(0)
	v_mfma_f32_16x16x32_bf16 v[60:63], v[128:131], v[172:175], v[60:63]
	v_mfma_f32_16x16x32_bf16 v[56:59], v[136:139], v[172:175], v[56:59]
	v_mfma_f32_16x16x32_bf16 v[48:51], v[128:131], v[188:191], v[48:51]
	v_mfma_f32_16x16x32_bf16 v[40:43], v[136:139], v[188:191], v[40:43]
	v_mfma_f32_16x16x32_bf16 v[32:35], v[128:131], v[206:209], v[32:35]
	v_mfma_f32_16x16x32_bf16 v[24:27], v[136:139], v[206:209], v[24:27]
	v_mfma_f32_16x16x32_bf16 v[16:19], v[128:131], v[214:217], v[16:19]
	v_mfma_f32_16x16x32_bf16 v[8:11], v[136:139], v[214:217], v[8:11]
	v_mfma_f32_16x16x32_bf16 v[60:63], v[132:135], v[176:179], v[60:63]
	v_mfma_f32_16x16x32_bf16 v[56:59], v[140:143], v[176:179], v[56:59]
	v_mfma_f32_16x16x32_bf16 v[48:51], v[132:135], v[202:205], v[48:51]
	v_mfma_f32_16x16x32_bf16 v[40:43], v[140:143], v[202:205], v[40:43]
	v_mfma_f32_16x16x32_bf16 v[32:35], v[132:135], v[210:213], v[32:35]
	v_mfma_f32_16x16x32_bf16 v[24:27], v[140:143], v[210:213], v[24:27]
	v_mfma_f32_16x16x32_bf16 v[16:19], v[132:135], v[218:221], v[16:19]
	v_mfma_f32_16x16x32_bf16 v[8:11], v[140:143], v[218:221], v[8:11]
	v_mfma_f32_16x16x32_bf16 v[52:55], v[144:147], v[172:175], v[52:55]
	v_mfma_f32_16x16x32_bf16 v[44:47], v[164:167], v[172:175], v[44:47]
	v_mfma_f32_16x16x32_bf16 v[36:39], v[144:147], v[188:191], v[36:39]
	v_mfma_f32_16x16x32_bf16 v[28:31], v[164:167], v[188:191], v[28:31]
	v_mfma_f32_16x16x32_bf16 v[20:23], v[144:147], v[206:209], v[20:23]
	v_mfma_f32_16x16x32_bf16 v[12:15], v[164:167], v[206:209], v[12:15]
	v_mfma_f32_16x16x32_bf16 v[4:7], v[144:147], v[214:217], v[4:7]
	v_mfma_f32_16x16x32_bf16 v[0:3], v[164:167], v[214:217], v[0:3]
	v_mfma_f32_16x16x32_bf16 v[52:55], v[148:151], v[176:179], v[52:55]
	v_mfma_f32_16x16x32_bf16 v[44:47], v[168:171], v[176:179], v[44:47]
	v_mfma_f32_16x16x32_bf16 v[36:39], v[148:151], v[202:205], v[36:39]
	v_mfma_f32_16x16x32_bf16 v[28:31], v[168:171], v[202:205], v[28:31]
	v_mfma_f32_16x16x32_bf16 v[20:23], v[148:151], v[210:213], v[20:23]
	v_mfma_f32_16x16x32_bf16 v[12:15], v[168:171], v[210:213], v[12:15]
	v_mfma_f32_16x16x32_bf16 v[4:7], v[148:151], v[218:221], v[4:7]
	v_mfma_f32_16x16x32_bf16 v[0:3], v[168:171], v[218:221], v[0:3]
	s_barrier
	s_add_i32 s90, s90, 2
	s_add_u32 s88, s88, 0x100
	s_addc_u32 s89, s89, 0
	s_add_u32 s8, s8, 0x100
	s_addc_u32 s9, s9, 0
	s_cmp_gt_u32 s90, 13
	s_cbranch_scc0 .LBB0_258

.LBB0_470:
	s_setprio 0
	s_waitcnt vmcnt(0)
	s_movk_i32 s82, 0x180
	s_barrier

.LBB0_849:
	s_add_u32 s12, s6, 0x6900000
	s_addc_u32 s13, s7, 0
	v_bfe_u32 v15, v14, 4, 2
	s_add_u32 s14, s6, 0x3d000000
	v_and_b32_e32 v16, 15, v14
	v_lshlrev_b32_e32 v18, 4, v15
	v_lshlrev_b32_e32 v14, 2, v14
	s_addc_u32 s15, s7, 0
	s_and_b32 s51, s18, 3
	v_lshl_or_b32 v247, s9, 6, v16
	v_lshl_or_b32 v16, v16, 6, v18
	s_lshl_b32 s6, s9, 13
	v_and_b32_e32 v14, 32, v14
	s_add_i32 m0, s47, 0x18000
	v_lshl_add_u64 v[6:7], v[6:7], 0, s[76:77]
	v_bitop3_b32 v18, v16, s6, v14 bitop3:0xde
	s_lshl_b32 s6, s51, 12
	s_waitcnt vmcnt(2)
	s_barrier
	global_load_lds_dwordx4 v[6:7], off
	v_lshl_add_u64 v[4:5], v[4:5], 0, s[76:77]
	s_add_i32 m0, s47, 0x1a000
	s_add_i32 s54, s47, 0x8000
	s_add_i32 s55, s47, 0xa000
	v_bitop3_b32 v248, v16, s6, v14 bitop3:0xde
	global_load_lds_dwordx4 v[4:5], off
	v_lshl_add_u64 v[0:1], v[0:1], 0, s[76:77]
	s_mov_b32 m0, s54
	s_add_u32 s6, s28, 0x40080
	global_load_lds_dwordx4 v[0:1], off
	v_lshl_add_u64 v[0:1], v[2:3], 0, s[76:77]
	s_mov_b32 m0, s55
	s_addc_u32 s7, s29, 0
	global_load_lds_dwordx4 v[0:1], off
	s_add_i32 m0, s47, 0x1c000
	v_lshl_add_u64 v[0:1], s[6:7], 0, v[192:193]
	global_load_lds_dwordx4 v[0:1], off
	v_lshl_add_u64 v[0:1], s[6:7], 0, v[202:203]
	s_add_i32 m0, s47, 0x1e000
	v_lshlrev_b32_e32 v17, 3, v15
	global_load_lds_dwordx4 v[0:1], off
	v_lshlrev_b32_e32 v0, 14, v8
	v_and_b32_e32 v0, 0xffff8000, v0
	v_lshl_add_u32 v0, v9, 11, v0
	v_and_b32_e32 v1, 1, v8
	v_lshl_or_b32 v0, v1, 6, v0
	v_lshl_add_u32 v208, v10, 1, v0
	v_lshlrev_b32_e32 v0, 14, v12
	v_and_b32_e32 v0, 0xffff8000, v0
	s_waitcnt vmcnt(6)
	v_lshl_add_u32 v0, v11, 11, v0
	v_and_b32_e32 v1, 1, v12
	s_cmpk_lt_u32 s8, 0x100
	v_lshl_or_b32 v0, v1, 6, v0
	v_readlane_b32 s8, v255, 38
	v_lshl_or_b32 v249, s51, 5, v17
	s_cselect_b64 s[18:19], -1, 0
	s_mov_b32 s56, 0
	v_cmp_eq_u32_e64 s[6:7], 0, v15
	v_mov_b32_e32 v209, v193
	v_lshl_add_u32 v210, v13, 1, v0
	v_mov_b32_e32 v211, v193
	v_add_u32_e32 v250, 0, v18
	v_readlane_b32 s57, v255, 19
	s_mov_b32 s60, s8
	s_barrier
	v_readlane_b32 s9, v255, 39
	s_cmp_lt_u32 s33, 0x100
	s_cbranch_scc1 .Lsp1
	s_setprio 1
.Lsp1:
	s_branch .LBB0_852
.LBB0_850:
	s_mov_b64 s[8:9], 0

.LBB0_852:
	s_add_u32 s82, s28, 0x100
	s_addc_u32 s83, s29, 0
	s_add_u32 s28, s30, 0x40080
	s_addc_u32 s29, s31, 0
	s_mov_b32 s85, -2
	s_waitcnt lgkmcnt(0)
	s_add_u32 s30, s28, 0xfffc0080
	s_addc_u32 s31, s29, -1
	s_add_i32 s86, 0, 0x10000
	s_cmp_eq_u32 s85, 12
	s_cselect_b32 s35, s23, s31
	s_cselect_b32 s34, s61, s30
	s_cselect_b32 s31, s21, s83
	s_cselect_b32 s30, s68, s82
	s_add_i32 s88, 0, 0x14000
	v_add_u32_e32 v124, s86, v248
	v_add_u32_e32 v156, s88, v248
	ds_read_b128 v[88:91], v124
	ds_read_b128 v[100:103], v124 offset:1024
	ds_read_b128 v[112:115], v124 offset:2048
	ds_read_b128 v[124:127], v124 offset:3072
	ds_read_b128 v[136:139], v156
	ds_read_b128 v[140:143], v156 offset:1024
	ds_read_b128 v[148:151], v156 offset:2048
	ds_read_b128 v[156:159], v156 offset:3072
	v_lshl_add_u64 v[212:213], s[28:29], 0, v[210:211]
	s_add_i32 m0, s47, 0xc000
	ds_read_b128 v[160:163], v250
	ds_read_b128 v[164:167], v250 offset:1024
	ds_read_b128 v[168:171], v250 offset:2048
	ds_read_b128 v[172:175], v250 offset:3072
	ds_read_b128 v[176:179], v250 offset:4096
	ds_read_b128 v[180:183], v250 offset:5120
	ds_read_b128 v[184:187], v250 offset:6144
	ds_read_b128 v[188:191], v250 offset:7168
	global_load_lds_dwordx4 v[212:213], off
	v_lshl_add_u64 v[212:213], s[28:29], 0, v[208:209]
	s_add_i32 m0, s47, 0xe000
	s_nop 0
	global_load_lds_dwordx4 v[212:213], off
	s_waitcnt vmcnt(8)
	s_waitcnt lgkmcnt(0)
	s_barrier
	s_waitcnt lgkmcnt(0)
	v_mfma_f32_16x16x32_bf16 v[152:155], v[88:91], v[160:163], 0
	v_mfma_f32_16x16x32_bf16 v[144:147], v[112:115], v[160:163], 0
	v_mfma_f32_16x16x32_bf16 v[120:123], v[88:91], v[168:171], 0
	v_mfma_f32_16x16x32_bf16 v[116:119], v[112:115], v[168:171], 0
	v_mfma_f32_16x16x32_bf16 v[96:99], v[88:91], v[176:179], 0
	v_mfma_f32_16x16x32_bf16 v[92:95], v[112:115], v[176:179], 0
	v_mfma_f32_16x16x32_bf16 v[76:79], v[88:91], v[184:187], 0
	v_mfma_f32_16x16x32_bf16 v[72:75], v[112:115], v[184:187], 0
	v_mfma_f32_16x16x32_bf16 v[152:155], v[100:103], v[164:167], v[152:155]
	v_mfma_f32_16x16x32_bf16 v[144:147], v[124:127], v[164:167], v[144:147]
	v_mfma_f32_16x16x32_bf16 v[120:123], v[100:103], v[172:175], v[120:123]
	v_mfma_f32_16x16x32_bf16 v[116:119], v[124:127], v[172:175], v[116:119]
	v_mfma_f32_16x16x32_bf16 v[96:99], v[100:103], v[180:183], v[96:99]
	v_mfma_f32_16x16x32_bf16 v[92:95], v[124:127], v[180:183], v[92:95]
	v_mfma_f32_16x16x32_bf16 v[76:79], v[100:103], v[188:191], v[76:79]
	v_mfma_f32_16x16x32_bf16 v[72:75], v[124:127], v[188:191], v[72:75]
	v_mfma_f32_16x16x32_bf16 v[132:135], v[136:139], v[160:163], 0
	v_mfma_f32_16x16x32_bf16 v[128:131], v[148:151], v[160:163], 0
	v_mfma_f32_16x16x32_bf16 v[108:111], v[136:139], v[168:171], 0
	v_mfma_f32_16x16x32_bf16 v[104:107], v[148:151], v[168:171], 0
	v_mfma_f32_16x16x32_bf16 v[84:87], v[136:139], v[176:179], 0
	v_mfma_f32_16x16x32_bf16 v[80:83], v[148:151], v[176:179], 0
	v_mfma_f32_16x16x32_bf16 v[68:71], v[136:139], v[184:187], 0
	v_mfma_f32_16x16x32_bf16 v[64:67], v[148:151], v[184:187], 0
	v_mfma_f32_16x16x32_bf16 v[132:135], v[140:143], v[164:167], v[132:135]
	v_mfma_f32_16x16x32_bf16 v[128:131], v[156:159], v[164:167], v[128:131]
	v_mfma_f32_16x16x32_bf16 v[108:111], v[140:143], v[172:175], v[108:111]
	v_mfma_f32_16x16x32_bf16 v[104:107], v[156:159], v[172:175], v[104:107]
	v_mfma_f32_16x16x32_bf16 v[84:87], v[140:143], v[180:183], v[84:87]
	v_mfma_f32_16x16x32_bf16 v[80:83], v[156:159], v[180:183], v[80:83]
	v_mfma_f32_16x16x32_bf16 v[68:71], v[140:143], v[188:191], v[68:71]
	v_mfma_f32_16x16x32_bf16 v[64:67], v[156:159], v[188:191], v[64:67]
	s_barrier
	s_add_i32 s86, s86, s46
	v_lshl_add_u64 v[212:213], s[30:31], 0, v[192:193]
	s_mov_b32 m0, s86
	ds_read_b128 v[160:163], v250 offset:16384
	ds_read_b128 v[164:167], v250 offset:17408
	ds_read_b128 v[168:171], v250 offset:18432
	ds_read_b128 v[172:175], v250 offset:19456
	ds_read_b128 v[176:179], v250 offset:20480
	ds_read_b128 v[180:183], v250 offset:21504
	ds_read_b128 v[184:187], v250 offset:22528
	ds_read_b128 v[188:191], v250 offset:23552
	global_load_lds_dwordx4 v[212:213], off
	s_add_i32 m0, s86, 0x2000
	s_add_u32 s86, s30, 0x40000
	v_lshl_add_u64 v[214:215], s[30:31], 0, v[202:203]
	s_addc_u32 s87, s31, 0
	s_add_i32 s88, s88, s46
	global_load_lds_dwordx4 v[214:215], off
	v_lshl_add_u64 v[216:217], s[86:87], 0, v[192:193]
	s_mov_b32 m0, s88
	v_lshl_add_u64 v[218:219], s[34:35], 0, v[204:205]
	global_load_lds_dwordx4 v[216:217], off
	v_lshl_add_u64 v[216:217], s[86:87], 0, v[202:203]
	s_add_i32 m0, s88, 0x2000
	s_nop 0
	global_load_lds_dwordx4 v[216:217], off
	v_lshl_add_u64 v[216:217], s[34:35], 0, v[206:207]
	s_mov_b32 m0, s47
	s_nop 0
	global_load_lds_dwordx4 v[216:217], off
	s_mov_b32 m0, s48
	s_nop 0
	global_load_lds_dwordx4 v[218:219], off
	s_add_i32 s56, s56, 1
	s_mul_i32 s8, s56, s43
	s_mul_hi_u32 s9, s56, s42
	s_add_i32 s9, s9, s8
	s_mul_i32 s8, s56, s42
	s_add_u32 s24, s8, s2
	s_addc_u32 s25, s9, s41
	v_cmp_gt_i64_e32 vcc, s[24:25], v[196:197]
	v_cmp_lt_i64_e64 s[8:9], s[24:25], v[194:195]
	s_cbranch_vccnz .LBB0_858
	s_ashr_i32 s20, s24, 31
	s_lshr_b32 s20, s20, 29
	s_add_i32 s22, s24, s20
	s_and_b32 s20, s22, -8
	s_sub_i32 s23, s24, s20
	s_cmp_gt_i32 s23, -1
	s_mov_b64 s[20:21], -1
	s_cbranch_scc0 .LBB0_855
	s_lshl_b32 s24, s23, 7
	s_mov_b64 s[20:21], 0

.LBB0_858:
	s_ashr_i32 s23, s22, 31
	s_lshl_b64 s[24:25], s[22:23], 19
	s_add_u32 s24, s36, s24
	s_addc_u32 s25, s37, s25
	s_and_b64 s[26:27], s[8:9], exec
	s_cselect_b32 s23, s25, s35
	s_cselect_b32 s61, s24, s34
	s_ashr_i32 s21, s20, 31
	s_lshl_b64 s[26:27], s[20:21], 19
	s_add_u32 s26, s38, s26
	s_addc_u32 s27, s39, s27
	s_and_b64 s[100:101], s[8:9], exec
	s_cselect_b32 s21, s27, s83
	s_cselect_b32 s68, s26, s82
	s_waitcnt vmcnt(8)
	s_waitcnt lgkmcnt(0)
	s_barrier
	s_waitcnt lgkmcnt(0)
	v_mfma_f32_16x16x32_bf16 v[60:63], v[88:91], v[160:163], 0
	v_mfma_f32_16x16x32_bf16 v[56:59], v[112:115], v[160:163], 0
	v_mfma_f32_16x16x32_bf16 v[44:47], v[88:91], v[168:171], 0
	v_mfma_f32_16x16x32_bf16 v[40:43], v[112:115], v[168:171], 0
	v_mfma_f32_16x16x32_bf16 v[28:31], v[88:91], v[176:179], 0
	v_mfma_f32_16x16x32_bf16 v[24:27], v[112:115], v[176:179], 0
	v_mfma_f32_16x16x32_bf16 v[12:15], v[88:91], v[184:187], 0
	v_mfma_f32_16x16x32_bf16 v[8:11], v[112:115], v[184:187], 0
	v_mfma_f32_16x16x32_bf16 v[60:63], v[100:103], v[164:167], v[60:63]
	v_mfma_f32_16x16x32_bf16 v[56:59], v[124:127], v[164:167], v[56:59]
	v_mfma_f32_16x16x32_bf16 v[44:47], v[100:103], v[172:175], v[44:47]
	v_mfma_f32_16x16x32_bf16 v[40:43], v[124:127], v[172:175], v[40:43]
	v_mfma_f32_16x16x32_bf16 v[28:31], v[100:103], v[180:183], v[28:31]
	v_mfma_f32_16x16x32_bf16 v[24:27], v[124:127], v[180:183], v[24:27]
	v_mfma_f32_16x16x32_bf16 v[12:15], v[100:103], v[188:191], v[12:15]
	v_mfma_f32_16x16x32_bf16 v[8:11], v[124:127], v[188:191], v[8:11]
	v_mfma_f32_16x16x32_bf16 v[52:55], v[136:139], v[160:163], 0
	v_mfma_f32_16x16x32_bf16 v[48:51], v[148:151], v[160:163], 0
	v_mfma_f32_16x16x32_bf16 v[36:39], v[136:139], v[168:171], 0
	v_mfma_f32_16x16x32_bf16 v[32:35], v[148:151], v[168:171], 0
	v_mfma_f32_16x16x32_bf16 v[20:23], v[136:139], v[176:179], 0
	v_mfma_f32_16x16x32_bf16 v[16:19], v[148:151], v[176:179], 0
	v_mfma_f32_16x16x32_bf16 v[4:7], v[136:139], v[184:187], 0
	v_mfma_f32_16x16x32_bf16 v[0:3], v[148:151], v[184:187], 0
	v_mfma_f32_16x16x32_bf16 v[52:55], v[140:143], v[164:167], v[52:55]
	v_mfma_f32_16x16x32_bf16 v[48:51], v[156:159], v[164:167], v[48:51]
	v_mfma_f32_16x16x32_bf16 v[36:39], v[140:143], v[172:175], v[36:39]
	v_mfma_f32_16x16x32_bf16 v[32:35], v[156:159], v[172:175], v[32:35]
	v_mfma_f32_16x16x32_bf16 v[20:23], v[140:143], v[180:183], v[20:23]
	v_mfma_f32_16x16x32_bf16 v[16:19], v[156:159], v[180:183], v[16:19]
	v_mfma_f32_16x16x32_bf16 v[4:7], v[140:143], v[188:191], v[4:7]
	v_mfma_f32_16x16x32_bf16 v[0:3], v[156:159], v[188:191], v[0:3]
	s_barrier
	s_add_i32 s86, 0, 0x18000
	s_add_i32 s87, 0, 0x1c000
	v_add_u32_e32 v124, s86, v248
	v_add_u32_e32 v156, s87, v248
	ds_read_b128 v[88:91], v124
	ds_read_b128 v[100:103], v124 offset:1024
	ds_read_b128 v[112:115], v124 offset:2048
	ds_read_b128 v[124:127], v124 offset:3072
	ds_read_b128 v[136:139], v156
	ds_read_b128 v[140:143], v156 offset:1024
	ds_read_b128 v[148:151], v156 offset:2048
	ds_read_b128 v[156:159], v156 offset:3072
	s_add_u32 s34, s34, 0x40000
	s_addc_u32 s35, s35, 0
	s_mov_b32 m0, s49
	v_lshl_add_u64 v[220:221], s[34:35], 0, v[206:207]
	ds_read_b128 v[160:163], v250 offset:32768
	ds_read_b128 v[164:167], v250 offset:33792
	ds_read_b128 v[168:171], v250 offset:34816
	ds_read_b128 v[172:175], v250 offset:35840
	ds_read_b128 v[176:179], v250 offset:36864
	ds_read_b128 v[180:183], v250 offset:37888
	ds_read_b128 v[184:187], v250 offset:38912
	ds_read_b128 v[188:191], v250 offset:39936
	global_load_lds_dwordx4 v[220:221], off
	v_lshl_add_u64 v[220:221], s[34:35], 0, v[204:205]
	s_mov_b32 m0, s50
	s_nop 0
	global_load_lds_dwordx4 v[220:221], off
	s_waitcnt vmcnt(8)
	s_waitcnt lgkmcnt(0)
	s_barrier
	s_waitcnt lgkmcnt(0)
	v_mfma_f32_16x16x32_bf16 v[152:155], v[88:91], v[160:163], v[152:155]
	v_mfma_f32_16x16x32_bf16 v[144:147], v[112:115], v[160:163], v[144:147]
	v_mfma_f32_16x16x32_bf16 v[120:123], v[88:91], v[168:171], v[120:123]
	v_mfma_f32_16x16x32_bf16 v[116:119], v[112:115], v[168:171], v[116:119]
	v_mfma_f32_16x16x32_bf16 v[96:99], v[88:91], v[176:179], v[96:99]
	v_mfma_f32_16x16x32_bf16 v[92:95], v[112:115], v[176:179], v[92:95]
	v_mfma_f32_16x16x32_bf16 v[76:79], v[88:91], v[184:187], v[76:79]
	v_mfma_f32_16x16x32_bf16 v[72:75], v[112:115], v[184:187], v[72:75]
	v_mfma_f32_16x16x32_bf16 v[152:155], v[100:103], v[164:167], v[152:155]
	v_mfma_f32_16x16x32_bf16 v[144:147], v[124:127], v[164:167], v[144:147]
	v_mfma_f32_16x16x32_bf16 v[120:123], v[100:103], v[172:175], v[120:123]
	v_mfma_f32_16x16x32_bf16 v[116:119], v[124:127], v[172:175], v[116:119]
	v_mfma_f32_16x16x32_bf16 v[96:99], v[100:103], v[180:183], v[96:99]
	v_mfma_f32_16x16x32_bf16 v[92:95], v[124:127], v[180:183], v[92:95]
	v_mfma_f32_16x16x32_bf16 v[76:79], v[100:103], v[188:191], v[76:79]
	v_mfma_f32_16x16x32_bf16 v[72:75], v[124:127], v[188:191], v[72:75]
	v_mfma_f32_16x16x32_bf16 v[132:135], v[136:139], v[160:163], v[132:135]
	v_mfma_f32_16x16x32_bf16 v[128:131], v[148:151], v[160:163], v[128:131]
	v_mfma_f32_16x16x32_bf16 v[108:111], v[136:139], v[168:171], v[108:111]
	v_mfma_f32_16x16x32_bf16 v[104:107], v[148:151], v[168:171], v[104:107]
	v_mfma_f32_16x16x32_bf16 v[84:87], v[136:139], v[176:179], v[84:87]
	v_mfma_f32_16x16x32_bf16 v[80:83], v[148:151], v[176:179], v[80:83]
	v_mfma_f32_16x16x32_bf16 v[68:71], v[136:139], v[184:187], v[68:71]
	v_mfma_f32_16x16x32_bf16 v[64:67], v[148:151], v[184:187], v[64:67]
	v_mfma_f32_16x16x32_bf16 v[132:135], v[140:143], v[164:167], v[132:135]
	v_mfma_f32_16x16x32_bf16 v[128:131], v[156:159], v[164:167], v[128:131]
	v_mfma_f32_16x16x32_bf16 v[108:111], v[140:143], v[172:175], v[108:111]
	v_mfma_f32_16x16x32_bf16 v[104:107], v[156:159], v[172:175], v[104:107]
	v_mfma_f32_16x16x32_bf16 v[84:87], v[140:143], v[180:183], v[84:87]
	v_mfma_f32_16x16x32_bf16 v[80:83], v[156:159], v[180:183], v[80:83]
	v_mfma_f32_16x16x32_bf16 v[68:71], v[140:143], v[188:191], v[68:71]
	v_mfma_f32_16x16x32_bf16 v[64:67], v[156:159], v[188:191], v[64:67]
	s_barrier
	s_add_i32 s34, s86, s46
	v_lshl_add_u64 v[212:213], v[212:213], 0, s[76:77]
	s_mov_b32 m0, s34
	ds_read_b128 v[160:163], v250 offset:49152
	ds_read_b128 v[164:167], v250 offset:50176
	ds_read_b128 v[168:171], v250 offset:51200
	ds_read_b128 v[172:175], v250 offset:52224
	ds_read_b128 v[176:179], v250 offset:53248
	ds_read_b128 v[180:183], v250 offset:54272
	ds_read_b128 v[184:187], v250 offset:55296
	ds_read_b128 v[188:191], v250 offset:56320
	global_load_lds_dwordx4 v[212:213], off
	s_add_i32 m0, s34, 0x2000
	s_add_u32 s30, s30, 0x40080
	v_lshl_add_u64 v[212:213], v[214:215], 0, s[76:77]
	s_addc_u32 s31, s31, 0
	s_add_i32 s34, s87, s46
	global_load_lds_dwordx4 v[212:213], off
	v_lshl_add_u64 v[212:213], s[30:31], 0, v[192:193]
	s_mov_b32 m0, s34
	s_nop 0
	global_load_lds_dwordx4 v[212:213], off
	v_lshl_add_u64 v[212:213], s[30:31], 0, v[202:203]
	s_add_i32 m0, s34, 0x2000
	s_nop 0
	global_load_lds_dwordx4 v[212:213], off
	v_lshl_add_u64 v[212:213], v[216:217], 0, s[76:77]
	s_mov_b32 m0, s54
	s_nop 0
	global_load_lds_dwordx4 v[212:213], off
	v_lshl_add_u64 v[212:213], v[218:219], 0, s[76:77]
	s_mov_b32 m0, s55
	s_nop 0
	global_load_lds_dwordx4 v[212:213], off
	s_waitcnt vmcnt(8)
	s_waitcnt lgkmcnt(0)
	s_barrier
	s_waitcnt lgkmcnt(0)
	v_mfma_f32_16x16x32_bf16 v[60:63], v[88:91], v[160:163], v[60:63]
	v_mfma_f32_16x16x32_bf16 v[56:59], v[112:115], v[160:163], v[56:59]
	v_mfma_f32_16x16x32_bf16 v[44:47], v[88:91], v[168:171], v[44:47]
	v_mfma_f32_16x16x32_bf16 v[40:43], v[112:115], v[168:171], v[40:43]
	v_mfma_f32_16x16x32_bf16 v[28:31], v[88:91], v[176:179], v[28:31]
	v_mfma_f32_16x16x32_bf16 v[24:27], v[112:115], v[176:179], v[24:27]
	v_mfma_f32_16x16x32_bf16 v[12:15], v[88:91], v[184:187], v[12:15]
	v_mfma_f32_16x16x32_bf16 v[8:11], v[112:115], v[184:187], v[8:11]
	v_mfma_f32_16x16x32_bf16 v[60:63], v[100:103], v[164:167], v[60:63]
	v_mfma_f32_16x16x32_bf16 v[56:59], v[124:127], v[164:167], v[56:59]
	v_mfma_f32_16x16x32_bf16 v[44:47], v[100:103], v[172:175], v[44:47]
	v_mfma_f32_16x16x32_bf16 v[40:43], v[124:127], v[172:175], v[40:43]
	v_mfma_f32_16x16x32_bf16 v[28:31], v[100:103], v[180:183], v[28:31]
	v_mfma_f32_16x16x32_bf16 v[24:27], v[124:127], v[180:183], v[24:27]
	v_mfma_f32_16x16x32_bf16 v[12:15], v[100:103], v[188:191], v[12:15]
	v_mfma_f32_16x16x32_bf16 v[8:11], v[124:127], v[188:191], v[8:11]
	v_mfma_f32_16x16x32_bf16 v[52:55], v[136:139], v[160:163], v[52:55]
	v_mfma_f32_16x16x32_bf16 v[48:51], v[148:151], v[160:163], v[48:51]
	v_mfma_f32_16x16x32_bf16 v[36:39], v[136:139], v[168:171], v[36:39]
	v_mfma_f32_16x16x32_bf16 v[32:35], v[148:151], v[168:171], v[32:35]
	v_mfma_f32_16x16x32_bf16 v[20:23], v[136:139], v[176:179], v[20:23]
	v_mfma_f32_16x16x32_bf16 v[16:19], v[148:151], v[176:179], v[16:19]
	v_mfma_f32_16x16x32_bf16 v[4:7], v[136:139], v[184:187], v[4:7]
	v_mfma_f32_16x16x32_bf16 v[0:3], v[148:151], v[184:187], v[0:3]
	v_mfma_f32_16x16x32_bf16 v[52:55], v[140:143], v[164:167], v[52:55]
	v_mfma_f32_16x16x32_bf16 v[48:51], v[156:159], v[164:167], v[48:51]
	v_mfma_f32_16x16x32_bf16 v[36:39], v[140:143], v[172:175], v[36:39]
	v_mfma_f32_16x16x32_bf16 v[32:35], v[156:159], v[172:175], v[32:35]
	v_mfma_f32_16x16x32_bf16 v[20:23], v[140:143], v[180:183], v[20:23]
	v_mfma_f32_16x16x32_bf16 v[16:19], v[156:159], v[180:183], v[16:19]
	v_mfma_f32_16x16x32_bf16 v[4:7], v[140:143], v[188:191], v[4:7]
	v_mfma_f32_16x16x32_bf16 v[0:3], v[156:159], v[188:191], v[0:3]
	s_barrier
	s_add_i32 s85, s85, 2
	s_add_u32 s82, s82, 0x100
	s_addc_u32 s83, s83, 0
	s_add_u32 s28, s28, 0x100
	s_addc_u32 s29, s29, 0
	s_cmp_gt_u32 s85, 13
.LBB0_859:
	s_add_u32 s30, s28, 0xfffc0080
	s_addc_u32 s31, s29, -1
	s_add_i32 s86, 0, 0x10000
	s_cmp_eq_u32 s85, 12
	s_cselect_b32 s35, s23, s31
	s_cselect_b32 s34, s61, s30
	s_cselect_b32 s31, s21, s83
	s_cselect_b32 s30, s68, s82
	s_add_i32 s88, 0, 0x14000
	v_add_u32_e32 v124, s86, v248
	v_add_u32_e32 v156, s88, v248
	ds_read_b128 v[88:91], v124
	ds_read_b128 v[100:103], v124 offset:1024
	ds_read_b128 v[112:115], v124 offset:2048
	ds_read_b128 v[124:127], v124 offset:3072
	ds_read_b128 v[136:139], v156
	ds_read_b128 v[140:143], v156 offset:1024
	ds_read_b128 v[148:151], v156 offset:2048
	ds_read_b128 v[156:159], v156 offset:3072
	v_lshl_add_u64 v[212:213], s[28:29], 0, v[210:211]
	s_add_i32 m0, s47, 0xc000
	ds_read_b128 v[160:163], v250
	ds_read_b128 v[164:167], v250 offset:1024
	ds_read_b128 v[168:171], v250 offset:2048
	ds_read_b128 v[172:175], v250 offset:3072
	ds_read_b128 v[176:179], v250 offset:4096
	ds_read_b128 v[180:183], v250 offset:5120
	ds_read_b128 v[184:187], v250 offset:6144
	ds_read_b128 v[188:191], v250 offset:7168
	global_load_lds_dwordx4 v[212:213], off
	v_lshl_add_u64 v[212:213], s[28:29], 0, v[208:209]
	s_add_i32 m0, s47, 0xe000
	s_nop 0
	global_load_lds_dwordx4 v[212:213], off
	s_waitcnt vmcnt(8)
	s_waitcnt lgkmcnt(0)
	s_barrier
	s_waitcnt lgkmcnt(0)
	v_mfma_f32_16x16x32_bf16 v[152:155], v[88:91], v[160:163], v[152:155]
	v_mfma_f32_16x16x32_bf16 v[144:147], v[112:115], v[160:163], v[144:147]
	v_mfma_f32_16x16x32_bf16 v[120:123], v[88:91], v[168:171], v[120:123]
	v_mfma_f32_16x16x32_bf16 v[116:119], v[112:115], v[168:171], v[116:119]
	v_mfma_f32_16x16x32_bf16 v[96:99], v[88:91], v[176:179], v[96:99]
	v_mfma_f32_16x16x32_bf16 v[92:95], v[112:115], v[176:179], v[92:95]
	v_mfma_f32_16x16x32_bf16 v[76:79], v[88:91], v[184:187], v[76:79]
	v_mfma_f32_16x16x32_bf16 v[72:75], v[112:115], v[184:187], v[72:75]
	v_mfma_f32_16x16x32_bf16 v[152:155], v[100:103], v[164:167], v[152:155]
	v_mfma_f32_16x16x32_bf16 v[144:147], v[124:127], v[164:167], v[144:147]
	v_mfma_f32_16x16x32_bf16 v[120:123], v[100:103], v[172:175], v[120:123]
	v_mfma_f32_16x16x32_bf16 v[116:119], v[124:127], v[172:175], v[116:119]
	v_mfma_f32_16x16x32_bf16 v[96:99], v[100:103], v[180:183], v[96:99]
	v_mfma_f32_16x16x32_bf16 v[92:95], v[124:127], v[180:183], v[92:95]
	v_mfma_f32_16x16x32_bf16 v[76:79], v[100:103], v[188:191], v[76:79]
	v_mfma_f32_16x16x32_bf16 v[72:75], v[124:127], v[188:191], v[72:75]
	v_mfma_f32_16x16x32_bf16 v[132:135], v[136:139], v[160:163], v[132:135]
	v_mfma_f32_16x16x32_bf16 v[128:131], v[148:151], v[160:163], v[128:131]
	v_mfma_f32_16x16x32_bf16 v[108:111], v[136:139], v[168:171], v[108:111]
	v_mfma_f32_16x16x32_bf16 v[104:107], v[148:151], v[168:171], v[104:107]
	v_mfma_f32_16x16x32_bf16 v[84:87], v[136:139], v[176:179], v[84:87]
	v_mfma_f32_16x16x32_bf16 v[80:83], v[148:151], v[176:179], v[80:83]
	v_mfma_f32_16x16x32_bf16 v[68:71], v[136:139], v[184:187], v[68:71]
	v_mfma_f32_16x16x32_bf16 v[64:67], v[148:151], v[184:187], v[64:67]
	v_mfma_f32_16x16x32_bf16 v[132:135], v[140:143], v[164:167], v[132:135]
	v_mfma_f32_16x16x32_bf16 v[128:131], v[156:159], v[164:167], v[128:131]
	v_mfma_f32_16x16x32_bf16 v[108:111], v[140:143], v[172:175], v[108:111]
	v_mfma_f32_16x16x32_bf16 v[104:107], v[156:159], v[172:175], v[104:107]
	v_mfma_f32_16x16x32_bf16 v[84:87], v[140:143], v[180:183], v[84:87]
	v_mfma_f32_16x16x32_bf16 v[80:83], v[156:159], v[180:183], v[80:83]
	v_mfma_f32_16x16x32_bf16 v[68:71], v[140:143], v[188:191], v[68:71]
	v_mfma_f32_16x16x32_bf16 v[64:67], v[156:159], v[188:191], v[64:67]
	s_barrier
	s_add_i32 s86, s86, s46
	v_lshl_add_u64 v[212:213], s[30:31], 0, v[192:193]
	s_mov_b32 m0, s86
	ds_read_b128 v[160:163], v250 offset:16384
	ds_read_b128 v[164:167], v250 offset:17408
	ds_read_b128 v[168:171], v250 offset:18432
	ds_read_b128 v[172:175], v250 offset:19456
	ds_read_b128 v[176:179], v250 offset:20480
	ds_read_b128 v[180:183], v250 offset:21504
	ds_read_b128 v[184:187], v250 offset:22528
	ds_read_b128 v[188:191], v250 offset:23552
	global_load_lds_dwordx4 v[212:213], off
	s_add_i32 m0, s86, 0x2000
	s_add_u32 s86, s30, 0x40000
	v_lshl_add_u64 v[214:215], s[30:31], 0, v[202:203]
	s_addc_u32 s87, s31, 0
	s_add_i32 s88, s88, s46
	global_load_lds_dwordx4 v[214:215], off
	v_lshl_add_u64 v[216:217], s[86:87], 0, v[192:193]
	s_mov_b32 m0, s88
	v_lshl_add_u64 v[218:219], s[34:35], 0, v[204:205]
	global_load_lds_dwordx4 v[216:217], off
	v_lshl_add_u64 v[216:217], s[86:87], 0, v[202:203]
	s_add_i32 m0, s88, 0x2000
	s_nop 0
	global_load_lds_dwordx4 v[216:217], off
	v_lshl_add_u64 v[216:217], s[34:35], 0, v[206:207]
	s_mov_b32 m0, s47
	s_nop 0
	global_load_lds_dwordx4 v[216:217], off
	s_mov_b32 m0, s48
	s_nop 0
	global_load_lds_dwordx4 v[218:219], off
	s_waitcnt vmcnt(8)
	s_waitcnt lgkmcnt(0)
	s_barrier
	s_waitcnt lgkmcnt(0)
	v_mfma_f32_16x16x32_bf16 v[60:63], v[88:91], v[160:163], v[60:63]
	v_mfma_f32_16x16x32_bf16 v[56:59], v[112:115], v[160:163], v[56:59]
	v_mfma_f32_16x16x32_bf16 v[44:47], v[88:91], v[168:171], v[44:47]
	v_mfma_f32_16x16x32_bf16 v[40:43], v[112:115], v[168:171], v[40:43]
	v_mfma_f32_16x16x32_bf16 v[28:31], v[88:91], v[176:179], v[28:31]
	v_mfma_f32_16x16x32_bf16 v[24:27], v[112:115], v[176:179], v[24:27]
	v_mfma_f32_16x16x32_bf16 v[12:15], v[88:91], v[184:187], v[12:15]
	v_mfma_f32_16x16x32_bf16 v[8:11], v[112:115], v[184:187], v[8:11]
	v_mfma_f32_16x16x32_bf16 v[60:63], v[100:103], v[164:167], v[60:63]
	v_mfma_f32_16x16x32_bf16 v[56:59], v[124:127], v[164:167], v[56:59]
	v_mfma_f32_16x16x32_bf16 v[44:47], v[100:103], v[172:175], v[44:47]
	v_mfma_f32_16x16x32_bf16 v[40:43], v[124:127], v[172:175], v[40:43]
	v_mfma_f32_16x16x32_bf16 v[28:31], v[100:103], v[180:183], v[28:31]
	v_mfma_f32_16x16x32_bf16 v[24:27], v[124:127], v[180:183], v[24:27]
	v_mfma_f32_16x16x32_bf16 v[12:15], v[100:103], v[188:191], v[12:15]
	v_mfma_f32_16x16x32_bf16 v[8:11], v[124:127], v[188:191], v[8:11]
	v_mfma_f32_16x16x32_bf16 v[52:55], v[136:139], v[160:163], v[52:55]
	v_mfma_f32_16x16x32_bf16 v[48:51], v[148:151], v[160:163], v[48:51]
	v_mfma_f32_16x16x32_bf16 v[36:39], v[136:139], v[168:171], v[36:39]
	v_mfma_f32_16x16x32_bf16 v[32:35], v[148:151], v[168:171], v[32:35]
	v_mfma_f32_16x16x32_bf16 v[20:23], v[136:139], v[176:179], v[20:23]
	v_mfma_f32_16x16x32_bf16 v[16:19], v[148:151], v[176:179], v[16:19]
	v_mfma_f32_16x16x32_bf16 v[4:7], v[136:139], v[184:187], v[4:7]
	v_mfma_f32_16x16x32_bf16 v[0:3], v[148:151], v[184:187], v[0:3]
	v_mfma_f32_16x16x32_bf16 v[52:55], v[140:143], v[164:167], v[52:55]
	v_mfma_f32_16x16x32_bf16 v[48:51], v[156:159], v[164:167], v[48:51]
	v_mfma_f32_16x16x32_bf16 v[36:39], v[140:143], v[172:175], v[36:39]
	v_mfma_f32_16x16x32_bf16 v[32:35], v[156:159], v[172:175], v[32:35]
	v_mfma_f32_16x16x32_bf16 v[20:23], v[140:143], v[180:183], v[20:23]
	v_mfma_f32_16x16x32_bf16 v[16:19], v[156:159], v[180:183], v[16:19]
	v_mfma_f32_16x16x32_bf16 v[4:7], v[140:143], v[188:191], v[4:7]
	v_mfma_f32_16x16x32_bf16 v[0:3], v[156:159], v[188:191], v[0:3]
	s_barrier
	s_add_i32 s86, 0, 0x18000
	s_add_i32 s87, 0, 0x1c000
	v_add_u32_e32 v124, s86, v248
	v_add_u32_e32 v156, s87, v248
	ds_read_b128 v[88:91], v124
	ds_read_b128 v[100:103], v124 offset:1024
	ds_read_b128 v[112:115], v124 offset:2048
	ds_read_b128 v[124:127], v124 offset:3072
	ds_read_b128 v[136:139], v156
	ds_read_b128 v[140:143], v156 offset:1024
	ds_read_b128 v[148:151], v156 offset:2048
	ds_read_b128 v[156:159], v156 offset:3072
	s_add_u32 s34, s34, 0x40000
	s_addc_u32 s35, s35, 0
	s_mov_b32 m0, s49
	v_lshl_add_u64 v[220:221], s[34:35], 0, v[206:207]
	ds_read_b128 v[160:163], v250 offset:32768
	ds_read_b128 v[164:167], v250 offset:33792
	ds_read_b128 v[168:171], v250 offset:34816
	ds_read_b128 v[172:175], v250 offset:35840
	ds_read_b128 v[176:179], v250 offset:36864
	ds_read_b128 v[180:183], v250 offset:37888
	ds_read_b128 v[184:187], v250 offset:38912
	ds_read_b128 v[188:191], v250 offset:39936
	global_load_lds_dwordx4 v[220:221], off
	v_lshl_add_u64 v[220:221], s[34:35], 0, v[204:205]
	s_mov_b32 m0, s50
	s_nop 0
	global_load_lds_dwordx4 v[220:221], off
	s_waitcnt vmcnt(8)
	s_waitcnt lgkmcnt(0)
	s_barrier
	s_waitcnt lgkmcnt(0)
	v_mfma_f32_16x16x32_bf16 v[152:155], v[88:91], v[160:163], v[152:155]
	v_mfma_f32_16x16x32_bf16 v[144:147], v[112:115], v[160:163], v[144:147]
	v_mfma_f32_16x16x32_bf16 v[120:123], v[88:91], v[168:171], v[120:123]
	v_mfma_f32_16x16x32_bf16 v[116:119], v[112:115], v[168:171], v[116:119]
	v_mfma_f32_16x16x32_bf16 v[96:99], v[88:91], v[176:179], v[96:99]
	v_mfma_f32_16x16x32_bf16 v[92:95], v[112:115], v[176:179], v[92:95]
	v_mfma_f32_16x16x32_bf16 v[76:79], v[88:91], v[184:187], v[76:79]
	v_mfma_f32_16x16x32_bf16 v[72:75], v[112:115], v[184:187], v[72:75]
	v_mfma_f32_16x16x32_bf16 v[152:155], v[100:103], v[164:167], v[152:155]
	v_mfma_f32_16x16x32_bf16 v[144:147], v[124:127], v[164:167], v[144:147]
	v_mfma_f32_16x16x32_bf16 v[120:123], v[100:103], v[172:175], v[120:123]
	v_mfma_f32_16x16x32_bf16 v[116:119], v[124:127], v[172:175], v[116:119]
	v_mfma_f32_16x16x32_bf16 v[96:99], v[100:103], v[180:183], v[96:99]
	v_mfma_f32_16x16x32_bf16 v[92:95], v[124:127], v[180:183], v[92:95]
	v_mfma_f32_16x16x32_bf16 v[76:79], v[100:103], v[188:191], v[76:79]
	v_mfma_f32_16x16x32_bf16 v[72:75], v[124:127], v[188:191], v[72:75]
	v_mfma_f32_16x16x32_bf16 v[132:135], v[136:139], v[160:163], v[132:135]
	v_mfma_f32_16x16x32_bf16 v[128:131], v[148:151], v[160:163], v[128:131]
	v_mfma_f32_16x16x32_bf16 v[108:111], v[136:139], v[168:171], v[108:111]
	v_mfma_f32_16x16x32_bf16 v[104:107], v[148:151], v[168:171], v[104:107]
	v_mfma_f32_16x16x32_bf16 v[84:87], v[136:139], v[176:179], v[84:87]
	v_mfma_f32_16x16x32_bf16 v[80:83], v[148:151], v[176:179], v[80:83]
	v_mfma_f32_16x16x32_bf16 v[68:71], v[136:139], v[184:187], v[68:71]
	v_mfma_f32_16x16x32_bf16 v[64:67], v[148:151], v[184:187], v[64:67]
	v_mfma_f32_16x16x32_bf16 v[132:135], v[140:143], v[164:167], v[132:135]
	v_mfma_f32_16x16x32_bf16 v[128:131], v[156:159], v[164:167], v[128:131]
	v_mfma_f32_16x16x32_bf16 v[108:111], v[140:143], v[172:175], v[108:111]
	v_mfma_f32_16x16x32_bf16 v[104:107], v[156:159], v[172:175], v[104:107]
	v_mfma_f32_16x16x32_bf16 v[84:87], v[140:143], v[180:183], v[84:87]
	v_mfma_f32_16x16x32_bf16 v[80:83], v[156:159], v[180:183], v[80:83]
	v_mfma_f32_16x16x32_bf16 v[68:71], v[140:143], v[188:191], v[68:71]
	v_mfma_f32_16x16x32_bf16 v[64:67], v[156:159], v[188:191], v[64:67]
	s_barrier
	s_add_i32 s34, s86, s46
	v_lshl_add_u64 v[212:213], v[212:213], 0, s[76:77]
	s_mov_b32 m0, s34
	ds_read_b128 v[160:163], v250 offset:49152
	ds_read_b128 v[164:167], v250 offset:50176
	ds_read_b128 v[168:171], v250 offset:51200
	ds_read_b128 v[172:175], v250 offset:52224
	ds_read_b128 v[176:179], v250 offset:53248
	ds_read_b128 v[180:183], v250 offset:54272
	ds_read_b128 v[184:187], v250 offset:55296
	ds_read_b128 v[188:191], v250 offset:56320
	global_load_lds_dwordx4 v[212:213], off
	s_add_i32 m0, s34, 0x2000
	s_add_u32 s30, s30, 0x40080
	v_lshl_add_u64 v[212:213], v[214:215], 0, s[76:77]
	s_addc_u32 s31, s31, 0
	s_add_i32 s34, s87, s46
	global_load_lds_dwordx4 v[212:213], off
	v_lshl_add_u64 v[212:213], s[30:31], 0, v[192:193]
	s_mov_b32 m0, s34
	s_nop 0
	global_load_lds_dwordx4 v[212:213], off
	v_lshl_add_u64 v[212:213], s[30:31], 0, v[202:203]
	s_add_i32 m0, s34, 0x2000
	s_nop 0
	global_load_lds_dwordx4 v[212:213], off
	v_lshl_add_u64 v[212:213], v[216:217], 0, s[76:77]
	s_mov_b32 m0, s54
	s_nop 0
	global_load_lds_dwordx4 v[212:213], off
	v_lshl_add_u64 v[212:213], v[218:219], 0, s[76:77]
	s_mov_b32 m0, s55
	s_nop 0
	global_load_lds_dwordx4 v[212:213], off
	s_waitcnt vmcnt(8)
	s_waitcnt lgkmcnt(0)
	s_barrier
	s_waitcnt lgkmcnt(0)
	v_mfma_f32_16x16x32_bf16 v[60:63], v[88:91], v[160:163], v[60:63]
	v_mfma_f32_16x16x32_bf16 v[56:59], v[112:115], v[160:163], v[56:59]
	v_mfma_f32_16x16x32_bf16 v[44:47], v[88:91], v[168:171], v[44:47]
	v_mfma_f32_16x16x32_bf16 v[40:43], v[112:115], v[168:171], v[40:43]
	v_mfma_f32_16x16x32_bf16 v[28:31], v[88:91], v[176:179], v[28:31]
	v_mfma_f32_16x16x32_bf16 v[24:27], v[112:115], v[176:179], v[24:27]
	v_mfma_f32_16x16x32_bf16 v[12:15], v[88:91], v[184:187], v[12:15]
	v_mfma_f32_16x16x32_bf16 v[8:11], v[112:115], v[184:187], v[8:11]
	v_mfma_f32_16x16x32_bf16 v[60:63], v[100:103], v[164:167], v[60:63]
	v_mfma_f32_16x16x32_bf16 v[56:59], v[124:127], v[164:167], v[56:59]
	v_mfma_f32_16x16x32_bf16 v[44:47], v[100:103], v[172:175], v[44:47]
	v_mfma_f32_16x16x32_bf16 v[40:43], v[124:127], v[172:175], v[40:43]
	v_mfma_f32_16x16x32_bf16 v[28:31], v[100:103], v[180:183], v[28:31]
	v_mfma_f32_16x16x32_bf16 v[24:27], v[124:127], v[180:183], v[24:27]
	v_mfma_f32_16x16x32_bf16 v[12:15], v[100:103], v[188:191], v[12:15]
	v_mfma_f32_16x16x32_bf16 v[8:11], v[124:127], v[188:191], v[8:11]
	v_mfma_f32_16x16x32_bf16 v[52:55], v[136:139], v[160:163], v[52:55]
	v_mfma_f32_16x16x32_bf16 v[48:51], v[148:151], v[160:163], v[48:51]
	v_mfma_f32_16x16x32_bf16 v[36:39], v[136:139], v[168:171], v[36:39]
	v_mfma_f32_16x16x32_bf16 v[32:35], v[148:151], v[168:171], v[32:35]
	v_mfma_f32_16x16x32_bf16 v[20:23], v[136:139], v[176:179], v[20:23]
	v_mfma_f32_16x16x32_bf16 v[16:19], v[148:151], v[176:179], v[16:19]
	v_mfma_f32_16x16x32_bf16 v[4:7], v[136:139], v[184:187], v[4:7]
	v_mfma_f32_16x16x32_bf16 v[0:3], v[148:151], v[184:187], v[0:3]
	v_mfma_f32_16x16x32_bf16 v[52:55], v[140:143], v[164:167], v[52:55]
	v_mfma_f32_16x16x32_bf16 v[48:51], v[156:159], v[164:167], v[48:51]
	v_mfma_f32_16x16x32_bf16 v[36:39], v[140:143], v[172:175], v[36:39]
	v_mfma_f32_16x16x32_bf16 v[32:35], v[156:159], v[172:175], v[32:35]
	v_mfma_f32_16x16x32_bf16 v[20:23], v[140:143], v[180:183], v[20:23]
	v_mfma_f32_16x16x32_bf16 v[16:19], v[156:159], v[180:183], v[16:19]
	v_mfma_f32_16x16x32_bf16 v[4:7], v[140:143], v[188:191], v[4:7]
	v_mfma_f32_16x16x32_bf16 v[0:3], v[156:159], v[188:191], v[0:3]
	s_barrier
	s_add_i32 s85, s85, 2
	s_add_u32 s82, s82, 0x100
	s_addc_u32 s83, s83, 0
	s_add_u32 s28, s28, 0x100
	s_addc_u32 s29, s29, 0
	s_cmp_gt_u32 s85, 13
	s_cbranch_scc0 .LBB0_859

.LBB0_881:
	s_setprio 0
	s_waitcnt vmcnt(0)
	s_barrier

.LBB0_929:
	s_add_u32 s12, s6, 0xec00000
	s_addc_u32 s13, s7, 0
	v_bfe_u32 v18, v14, 4, 2
	s_lshl_b32 s15, s15, 5
	v_and_b32_e32 v15, 15, v14
	v_lshlrev_b32_e32 v16, 4, v18
	v_lshlrev_b32_e32 v14, 2, v14
	s_and_b32 s20, s15, 0x60
	s_add_i32 m0, s37, 0x18000
	v_lshl_add_u64 v[6:7], v[6:7], 0, s[76:77]
	v_lshl_or_b32 v183, s18, 6, v15
	v_lshl_or_b32 v15, v15, 6, v16
	s_lshl_b32 s18, s18, 13
	v_and_b32_e32 v14, 32, v14
	s_lshl_b32 s15, s20, 7
	s_waitcnt vmcnt(2)
	s_barrier
	global_load_lds_dwordx4 v[6:7], off
	v_lshl_add_u64 v[4:5], v[4:5], 0, s[76:77]
	s_add_i32 m0, s37, 0x1a000
	s_add_i32 s47, s37, 0x8000
	s_add_i32 s48, s37, 0xa000
	v_bitop3_b32 v19, v15, s18, v14 bitop3:0xde
	global_load_lds_dwordx4 v[4:5], off
	v_lshl_add_u64 v[0:1], v[0:1], 0, s[76:77]
	s_mov_b32 m0, s47
	s_add_u32 s18, s8, 0x40080
	global_load_lds_dwordx4 v[0:1], off
	v_lshl_add_u64 v[0:1], v[2:3], 0, s[76:77]
	s_mov_b32 m0, s48
	s_addc_u32 s19, s9, 0
	global_load_lds_dwordx4 v[0:1], off
	s_add_i32 m0, s37, 0x1c000
	v_lshl_add_u64 v[0:1], s[18:19], 0, v[192:193]
	global_load_lds_dwordx4 v[0:1], off
	v_lshl_add_u64 v[0:1], s[18:19], 0, v[152:153]
	s_add_i32 m0, s37, 0x1e000
	v_mov_b32_e32 v17, v193
	global_load_lds_dwordx4 v[0:1], off
	v_lshl_add_u64 v[0:1], s[6:7], 0, v[16:17]
	s_mov_b64 s[6:7], 0x3d000000
	v_lshl_add_u64 v[158:159], v[0:1], 0, s[6:7]
	v_lshlrev_b32_e32 v0, 14, v8
	v_and_b32_e32 v0, 0xffff8000, v0
	v_lshl_add_u32 v0, v9, 11, v0
	v_and_b32_e32 v1, 1, v8
	v_lshl_or_b32 v0, v1, 6, v0
	v_lshl_add_u32 v160, v10, 1, v0
	v_lshlrev_b32_e32 v0, 14, v12
	v_and_b32_e32 v0, 0xffff8000, v0
	s_waitcnt vmcnt(6)
	v_lshl_add_u32 v0, v11, 11, v0
	v_and_b32_e32 v1, 1, v12
	s_cmpk_lt_u32 s14, 0x100
	v_lshl_or_b32 v0, v1, 6, v0
	v_readlane_b32 s6, v255, 30
	v_bitop3_b32 v185, v15, s15, v14 bitop3:0xde
	s_cselect_b64 s[14:15], -1, 0
	v_lshl_or_b32 v188, v18, 3, s20
	v_mov_b32_e32 v161, v193
	v_lshl_add_u32 v162, v13, 1, v0
	v_mov_b32_e32 v163, v193
	s_mov_b32 s49, 0
	v_add_u32_e32 v189, 0, v19
	v_readlane_b32 s50, v255, 20
	s_mov_b32 s51, s6
	s_barrier
	v_readlane_b32 s7, v255, 31
	s_cmp_lt_u32 s33, 0x100
	s_cbranch_scc1 .Lsp2
	s_setprio 1
.Lsp2:
	s_branch .LBB0_932
.LBB0_930:
	s_mov_b64 s[8:9], 0

.LBB0_932:
	s_mov_b64 s[86:87], s[26:27]
	s_mov_b64 s[88:89], s[8:9]
	s_add_u32 s56, s8, 0x100
	s_addc_u32 s57, s9, 0
	s_add_u32 s8, s26, 0x40080
	s_addc_u32 s9, s27, 0
	s_mov_b32 s60, -2
	s_add_u32 s26, s8, 0xfffc0080
	s_addc_u32 s27, s9, -1
	s_add_i32 s61, 0, 0x10000
	s_cmp_eq_u32 s60, 12
	s_cselect_b32 s29, s21, s27
	s_cselect_b32 s28, s54, s26
	s_cselect_b32 s27, s19, s57
	s_cselect_b32 s26, s55, s56
	s_add_i32 s68, 0, 0x14000
	v_add_u32_e32 v140, s61, v185
	v_add_u32_e32 v168, s68, v185
	ds_read_b128 v[128:131], v140
	ds_read_b128 v[132:135], v140 offset:1024
	ds_read_b128 v[136:139], v140 offset:2048
	ds_read_b128 v[140:143], v140 offset:3072
	ds_read_b128 v[144:147], v168
	ds_read_b128 v[148:151], v168 offset:1024
	ds_read_b128 v[164:167], v168 offset:2048
	ds_read_b128 v[168:171], v168 offset:3072
	v_lshl_add_u64 v[180:181], s[8:9], 0, v[162:163]
	s_add_i32 m0, s37, 0xc000
	ds_read_b128 v[172:175], v189
	ds_read_b128 v[176:179], v189 offset:1024
	ds_read_b128 v[202:205], v189 offset:2048
	ds_read_b128 v[206:209], v189 offset:3072
	ds_read_b128 v[210:213], v189 offset:4096
	ds_read_b128 v[214:217], v189 offset:5120
	ds_read_b128 v[218:221], v189 offset:6144
	ds_read_b128 v[222:225], v189 offset:7168
	global_load_lds_dwordx4 v[180:181], off
	v_lshl_add_u64 v[180:181], s[8:9], 0, v[160:161]
	s_add_i32 m0, s37, 0xe000
	s_nop 0
	global_load_lds_dwordx4 v[180:181], off
	s_waitcnt vmcnt(8)
	s_waitcnt lgkmcnt(0)
	s_barrier
	s_waitcnt lgkmcnt(0)
	v_mfma_f32_16x16x32_bf16 v[124:127], v[128:131], v[172:175], 0
	v_mfma_f32_16x16x32_bf16 v[116:119], v[136:139], v[172:175], 0
	v_mfma_f32_16x16x32_bf16 v[108:111], v[128:131], v[202:205], 0
	v_mfma_f32_16x16x32_bf16 v[100:103], v[136:139], v[202:205], 0
	v_mfma_f32_16x16x32_bf16 v[92:95], v[128:131], v[210:213], 0
	v_mfma_f32_16x16x32_bf16 v[84:87], v[136:139], v[210:213], 0
	v_mfma_f32_16x16x32_bf16 v[76:79], v[128:131], v[218:221], 0
	v_mfma_f32_16x16x32_bf16 v[68:71], v[136:139], v[218:221], 0
	v_mfma_f32_16x16x32_bf16 v[124:127], v[132:135], v[176:179], v[124:127]
	v_mfma_f32_16x16x32_bf16 v[116:119], v[140:143], v[176:179], v[116:119]
	v_mfma_f32_16x16x32_bf16 v[108:111], v[132:135], v[206:209], v[108:111]
	v_mfma_f32_16x16x32_bf16 v[100:103], v[140:143], v[206:209], v[100:103]
	v_mfma_f32_16x16x32_bf16 v[92:95], v[132:135], v[214:217], v[92:95]
	v_mfma_f32_16x16x32_bf16 v[84:87], v[140:143], v[214:217], v[84:87]
	v_mfma_f32_16x16x32_bf16 v[76:79], v[132:135], v[222:225], v[76:79]
	v_mfma_f32_16x16x32_bf16 v[68:71], v[140:143], v[222:225], v[68:71]
	v_mfma_f32_16x16x32_bf16 v[120:123], v[144:147], v[172:175], 0
	v_mfma_f32_16x16x32_bf16 v[112:115], v[164:167], v[172:175], 0
	v_mfma_f32_16x16x32_bf16 v[104:107], v[144:147], v[202:205], 0
	v_mfma_f32_16x16x32_bf16 v[96:99], v[164:167], v[202:205], 0
	v_mfma_f32_16x16x32_bf16 v[88:91], v[144:147], v[210:213], 0
	v_mfma_f32_16x16x32_bf16 v[80:83], v[164:167], v[210:213], 0
	v_mfma_f32_16x16x32_bf16 v[72:75], v[144:147], v[218:221], 0
	v_mfma_f32_16x16x32_bf16 v[64:67], v[164:167], v[218:221], 0
	v_mfma_f32_16x16x32_bf16 v[120:123], v[148:151], v[176:179], v[120:123]
	v_mfma_f32_16x16x32_bf16 v[112:115], v[168:171], v[176:179], v[112:115]
	v_mfma_f32_16x16x32_bf16 v[104:107], v[148:151], v[206:209], v[104:107]
	v_mfma_f32_16x16x32_bf16 v[96:99], v[168:171], v[206:209], v[96:99]
	v_mfma_f32_16x16x32_bf16 v[88:91], v[148:151], v[214:217], v[88:91]
	v_mfma_f32_16x16x32_bf16 v[80:83], v[168:171], v[214:217], v[80:83]
	v_mfma_f32_16x16x32_bf16 v[72:75], v[148:151], v[222:225], v[72:75]
	v_mfma_f32_16x16x32_bf16 v[64:67], v[168:171], v[222:225], v[64:67]
	s_barrier
	s_add_i32 s61, s61, s36
	v_lshl_add_u64 v[180:181], s[26:27], 0, v[192:193]
	s_mov_b32 m0, s61
	ds_read_b128 v[172:175], v189 offset:16384
	ds_read_b128 v[176:179], v189 offset:17408
	ds_read_b128 v[202:205], v189 offset:18432
	ds_read_b128 v[206:209], v189 offset:19456
	ds_read_b128 v[210:213], v189 offset:20480
	ds_read_b128 v[214:217], v189 offset:21504
	ds_read_b128 v[218:221], v189 offset:22528
	ds_read_b128 v[222:225], v189 offset:23552
	global_load_lds_dwordx4 v[180:181], off
	s_add_i32 m0, s61, 0x2000
	s_add_u32 s82, s26, 0x40000
	v_lshl_add_u64 v[186:187], s[26:27], 0, v[152:153]
	s_addc_u32 s83, s27, 0
	s_add_i32 s61, s68, s36
	global_load_lds_dwordx4 v[186:187], off
	v_lshl_add_u64 v[190:191], s[82:83], 0, v[192:193]
	s_mov_b32 m0, s61
	v_lshl_add_u64 v[226:227], s[28:29], 0, v[154:155]
	global_load_lds_dwordx4 v[190:191], off
	v_lshl_add_u64 v[190:191], s[82:83], 0, v[152:153]
	s_add_i32 m0, s61, 0x2000
	s_nop 0
	global_load_lds_dwordx4 v[190:191], off
	v_lshl_add_u64 v[190:191], s[28:29], 0, v[156:157]
	s_mov_b32 m0, s37
	s_nop 0
	global_load_lds_dwordx4 v[190:191], off
	s_mov_b32 m0, s38
	s_nop 0
	global_load_lds_dwordx4 v[226:227], off
	s_add_i32 s49, s49, 1
	s_mul_i32 s6, s49, s43
	s_mul_hi_u32 s7, s49, s42
	s_add_i32 s7, s7, s6
	s_mul_i32 s6, s49, s42
	s_add_u32 s22, s6, s2
	s_addc_u32 s23, s7, s41
	v_cmp_gt_i64_e32 vcc, s[22:23], v[200:201]
	v_cmp_lt_i64_e64 s[6:7], s[22:23], v[198:199]
	s_cbranch_vccnz .LBB0_934
	s_ashr_i32 s18, s22, 31
	s_lshr_b32 s18, s18, 29
	s_add_i32 s18, s22, s18
	s_ashr_i32 s19, s18, 3
	s_and_b32 s18, s18, -8
	s_sub_i32 s18, s22, s18
	s_cmp_lt_i32 s18, 0
	s_movk_i32 s20, 0x2c1
	s_cselect_b32 s20, s20, 0x2c0
	s_mul_i32 s18, s18, s20
	s_add_i32 s18, s18, s19
	s_mul_hi_i32 s19, s18, 0x2e8ba2e9
	s_lshr_b32 s20, s19, 31
	s_ashr_i32 s19, s19, 5
	s_add_i32 s19, s19, s20
	s_lshl_b32 s20, s19, 3
	s_sub_i32 s21, 0x100, s20
	s_min_i32 s21, s21, 8
	s_abs_i32 s22, s21
	v_cvt_f32_u32_e32 v0, s22
	s_sub_i32 s24, 0, s22
	s_mulk_i32 s19, 0xb0
	s_sub_i32 s19, s18, s19
	v_rcp_iflag_f32_e32 v0, v0
	s_abs_i32 s18, s19
	s_xor_b32 s23, s19, s21
	s_ashr_i32 s23, s23, 31
	v_mul_f32_e32 v0, 0x4f7ffffe, v0
	v_cvt_u32_f32_e32 v0, v0
	s_nop 0
	v_readfirstlane_b32 s25, v0
	s_mul_i32 s24, s24, s25
	s_mul_hi_u32 s24, s25, s24
	s_add_i32 s25, s25, s24
	s_mul_hi_u32 s24, s18, s25
	s_mul_i32 s25, s24, s22
	s_sub_i32 s18, s18, s25
	s_add_i32 s32, s24, 1
	s_sub_i32 s25, s18, s22
	s_cmp_ge_u32 s18, s22
	s_cselect_b32 s24, s32, s24
	s_cselect_b32 s18, s25, s18
	s_add_i32 s25, s24, 1
	s_cmp_ge_u32 s18, s22
	s_cselect_b32 s18, s25, s24
	s_xor_b32 s18, s18, s23
	s_sub_i32 s18, s18, s23
	s_mul_i32 s21, s18, s21
	s_sub_i32 s19, s19, s21
	s_add_i32 s20, s20, s19
.LBB0_934:
	s_ashr_i32 s21, s20, 31
	s_lshl_b64 s[22:23], s[20:21], 19
	s_add_u32 s22, s30, s22
	s_addc_u32 s23, s31, s23
	s_and_b64 s[24:25], s[6:7], exec
	s_cselect_b32 s21, s23, s87
	s_cselect_b32 s54, s22, s86
	s_ashr_i32 s19, s18, 31
	s_lshl_b64 s[24:25], s[18:19], 19
	s_add_u32 s24, s34, s24
	s_addc_u32 s25, s35, s25
	s_and_b64 s[100:101], s[6:7], exec
	s_cselect_b32 s19, s25, s89
	s_cselect_b32 s55, s24, s88
	s_waitcnt vmcnt(8)
	s_waitcnt lgkmcnt(0)
	s_barrier
	s_waitcnt lgkmcnt(0)
	v_mfma_f32_16x16x32_bf16 v[60:63], v[128:131], v[172:175], 0
	v_mfma_f32_16x16x32_bf16 v[52:55], v[136:139], v[172:175], 0
	v_mfma_f32_16x16x32_bf16 v[44:47], v[128:131], v[202:205], 0
	v_mfma_f32_16x16x32_bf16 v[36:39], v[136:139], v[202:205], 0
	v_mfma_f32_16x16x32_bf16 v[28:31], v[128:131], v[210:213], 0
	v_mfma_f32_16x16x32_bf16 v[20:23], v[136:139], v[210:213], 0
	v_mfma_f32_16x16x32_bf16 v[12:15], v[128:131], v[218:221], 0
	v_mfma_f32_16x16x32_bf16 v[4:7], v[136:139], v[218:221], 0
	v_mfma_f32_16x16x32_bf16 v[60:63], v[132:135], v[176:179], v[60:63]
	v_mfma_f32_16x16x32_bf16 v[52:55], v[140:143], v[176:179], v[52:55]
	v_mfma_f32_16x16x32_bf16 v[44:47], v[132:135], v[206:209], v[44:47]
	v_mfma_f32_16x16x32_bf16 v[36:39], v[140:143], v[206:209], v[36:39]
	v_mfma_f32_16x16x32_bf16 v[28:31], v[132:135], v[214:217], v[28:31]
	v_mfma_f32_16x16x32_bf16 v[20:23], v[140:143], v[214:217], v[20:23]
	v_mfma_f32_16x16x32_bf16 v[12:15], v[132:135], v[222:225], v[12:15]
	v_mfma_f32_16x16x32_bf16 v[4:7], v[140:143], v[222:225], v[4:7]
	v_mfma_f32_16x16x32_bf16 v[56:59], v[144:147], v[172:175], 0
	v_mfma_f32_16x16x32_bf16 v[48:51], v[164:167], v[172:175], 0
	v_mfma_f32_16x16x32_bf16 v[40:43], v[144:147], v[202:205], 0
	v_mfma_f32_16x16x32_bf16 v[32:35], v[164:167], v[202:205], 0
	v_mfma_f32_16x16x32_bf16 v[24:27], v[144:147], v[210:213], 0
	v_mfma_f32_16x16x32_bf16 v[16:19], v[164:167], v[210:213], 0
	v_mfma_f32_16x16x32_bf16 v[8:11], v[144:147], v[218:221], 0
	v_mfma_f32_16x16x32_bf16 v[0:3], v[164:167], v[218:221], 0
	v_mfma_f32_16x16x32_bf16 v[56:59], v[148:151], v[176:179], v[56:59]
	v_mfma_f32_16x16x32_bf16 v[48:51], v[168:171], v[176:179], v[48:51]
	v_mfma_f32_16x16x32_bf16 v[40:43], v[148:151], v[206:209], v[40:43]
	v_mfma_f32_16x16x32_bf16 v[32:35], v[168:171], v[206:209], v[32:35]
	v_mfma_f32_16x16x32_bf16 v[24:27], v[148:151], v[214:217], v[24:27]
	v_mfma_f32_16x16x32_bf16 v[16:19], v[168:171], v[214:217], v[16:19]
	v_mfma_f32_16x16x32_bf16 v[8:11], v[148:151], v[222:225], v[8:11]
	v_mfma_f32_16x16x32_bf16 v[0:3], v[168:171], v[222:225], v[0:3]
	s_barrier
	s_add_i32 s61, 0, 0x18000
	s_add_i32 s68, 0, 0x1c000
	v_add_u32_e32 v140, s61, v185
	v_add_u32_e32 v168, s68, v185
	ds_read_b128 v[128:131], v140
	ds_read_b128 v[132:135], v140 offset:1024
	ds_read_b128 v[136:139], v140 offset:2048
	ds_read_b128 v[140:143], v140 offset:3072
	ds_read_b128 v[144:147], v168
	ds_read_b128 v[148:151], v168 offset:1024
	ds_read_b128 v[164:167], v168 offset:2048
	ds_read_b128 v[168:171], v168 offset:3072
	s_add_u32 s28, s28, 0x40000
	s_addc_u32 s29, s29, 0
	s_mov_b32 m0, s39
	v_lshl_add_u64 v[228:229], s[28:29], 0, v[156:157]
	ds_read_b128 v[172:175], v189 offset:32768
	ds_read_b128 v[176:179], v189 offset:33792
	ds_read_b128 v[202:205], v189 offset:34816
	ds_read_b128 v[206:209], v189 offset:35840
	ds_read_b128 v[210:213], v189 offset:36864
	ds_read_b128 v[214:217], v189 offset:37888
	ds_read_b128 v[218:221], v189 offset:38912
	ds_read_b128 v[222:225], v189 offset:39936
	global_load_lds_dwordx4 v[228:229], off
	v_lshl_add_u64 v[228:229], s[28:29], 0, v[154:155]
	s_mov_b32 m0, s46
	s_nop 0
	global_load_lds_dwordx4 v[228:229], off
	s_waitcnt vmcnt(8)
	s_waitcnt lgkmcnt(0)
	s_barrier
	s_waitcnt lgkmcnt(0)
	v_mfma_f32_16x16x32_bf16 v[124:127], v[128:131], v[172:175], v[124:127]
	v_mfma_f32_16x16x32_bf16 v[116:119], v[136:139], v[172:175], v[116:119]
	v_mfma_f32_16x16x32_bf16 v[108:111], v[128:131], v[202:205], v[108:111]
	v_mfma_f32_16x16x32_bf16 v[100:103], v[136:139], v[202:205], v[100:103]
	v_mfma_f32_16x16x32_bf16 v[92:95], v[128:131], v[210:213], v[92:95]
	v_mfma_f32_16x16x32_bf16 v[84:87], v[136:139], v[210:213], v[84:87]
	v_mfma_f32_16x16x32_bf16 v[76:79], v[128:131], v[218:221], v[76:79]
	v_mfma_f32_16x16x32_bf16 v[68:71], v[136:139], v[218:221], v[68:71]
	v_mfma_f32_16x16x32_bf16 v[124:127], v[132:135], v[176:179], v[124:127]
	v_mfma_f32_16x16x32_bf16 v[116:119], v[140:143], v[176:179], v[116:119]
	v_mfma_f32_16x16x32_bf16 v[108:111], v[132:135], v[206:209], v[108:111]
	v_mfma_f32_16x16x32_bf16 v[100:103], v[140:143], v[206:209], v[100:103]
	v_mfma_f32_16x16x32_bf16 v[92:95], v[132:135], v[214:217], v[92:95]
	v_mfma_f32_16x16x32_bf16 v[84:87], v[140:143], v[214:217], v[84:87]
	v_mfma_f32_16x16x32_bf16 v[76:79], v[132:135], v[222:225], v[76:79]
	v_mfma_f32_16x16x32_bf16 v[68:71], v[140:143], v[222:225], v[68:71]
	v_mfma_f32_16x16x32_bf16 v[120:123], v[144:147], v[172:175], v[120:123]
	v_mfma_f32_16x16x32_bf16 v[112:115], v[164:167], v[172:175], v[112:115]
	v_mfma_f32_16x16x32_bf16 v[104:107], v[144:147], v[202:205], v[104:107]
	v_mfma_f32_16x16x32_bf16 v[96:99], v[164:167], v[202:205], v[96:99]
	v_mfma_f32_16x16x32_bf16 v[88:91], v[144:147], v[210:213], v[88:91]
	v_mfma_f32_16x16x32_bf16 v[80:83], v[164:167], v[210:213], v[80:83]
	v_mfma_f32_16x16x32_bf16 v[72:75], v[144:147], v[218:221], v[72:75]
	v_mfma_f32_16x16x32_bf16 v[64:67], v[164:167], v[218:221], v[64:67]
	v_mfma_f32_16x16x32_bf16 v[120:123], v[148:151], v[176:179], v[120:123]
	v_mfma_f32_16x16x32_bf16 v[112:115], v[168:171], v[176:179], v[112:115]
	v_mfma_f32_16x16x32_bf16 v[104:107], v[148:151], v[206:209], v[104:107]
	v_mfma_f32_16x16x32_bf16 v[96:99], v[168:171], v[206:209], v[96:99]
	v_mfma_f32_16x16x32_bf16 v[88:91], v[148:151], v[214:217], v[88:91]
	v_mfma_f32_16x16x32_bf16 v[80:83], v[168:171], v[214:217], v[80:83]
	v_mfma_f32_16x16x32_bf16 v[72:75], v[148:151], v[222:225], v[72:75]
	v_mfma_f32_16x16x32_bf16 v[64:67], v[168:171], v[222:225], v[64:67]
	s_barrier
	s_add_i32 s28, s61, s36
	v_lshl_add_u64 v[180:181], v[180:181], 0, s[76:77]
	s_mov_b32 m0, s28
	ds_read_b128 v[172:175], v189 offset:49152
	ds_read_b128 v[176:179], v189 offset:50176
	ds_read_b128 v[202:205], v189 offset:51200
	ds_read_b128 v[206:209], v189 offset:52224
	ds_read_b128 v[210:213], v189 offset:53248
	ds_read_b128 v[214:217], v189 offset:54272
	ds_read_b128 v[218:221], v189 offset:55296
	ds_read_b128 v[222:225], v189 offset:56320
	global_load_lds_dwordx4 v[180:181], off
	s_add_i32 m0, s28, 0x2000
	s_add_u32 s26, s26, 0x40080
	v_lshl_add_u64 v[180:181], v[186:187], 0, s[76:77]
	s_addc_u32 s27, s27, 0
	s_add_i32 s28, s68, s36
	global_load_lds_dwordx4 v[180:181], off
	v_lshl_add_u64 v[180:181], s[26:27], 0, v[192:193]
	s_mov_b32 m0, s28
	s_nop 0
	global_load_lds_dwordx4 v[180:181], off
	v_lshl_add_u64 v[180:181], s[26:27], 0, v[152:153]
	s_add_i32 m0, s28, 0x2000
	s_nop 0
	global_load_lds_dwordx4 v[180:181], off
	v_lshl_add_u64 v[180:181], v[190:191], 0, s[76:77]
	s_mov_b32 m0, s47
	s_nop 0
	global_load_lds_dwordx4 v[180:181], off
	v_lshl_add_u64 v[180:181], v[226:227], 0, s[76:77]
	s_mov_b32 m0, s48
	s_nop 0
	global_load_lds_dwordx4 v[180:181], off
	s_waitcnt vmcnt(8)
	s_waitcnt lgkmcnt(0)
	s_barrier
	s_waitcnt lgkmcnt(0)
	v_mfma_f32_16x16x32_bf16 v[60:63], v[128:131], v[172:175], v[60:63]
	v_mfma_f32_16x16x32_bf16 v[52:55], v[136:139], v[172:175], v[52:55]
	v_mfma_f32_16x16x32_bf16 v[44:47], v[128:131], v[202:205], v[44:47]
	v_mfma_f32_16x16x32_bf16 v[36:39], v[136:139], v[202:205], v[36:39]
	v_mfma_f32_16x16x32_bf16 v[28:31], v[128:131], v[210:213], v[28:31]
	v_mfma_f32_16x16x32_bf16 v[20:23], v[136:139], v[210:213], v[20:23]
	v_mfma_f32_16x16x32_bf16 v[12:15], v[128:131], v[218:221], v[12:15]
	v_mfma_f32_16x16x32_bf16 v[4:7], v[136:139], v[218:221], v[4:7]
	v_mfma_f32_16x16x32_bf16 v[60:63], v[132:135], v[176:179], v[60:63]
	v_mfma_f32_16x16x32_bf16 v[52:55], v[140:143], v[176:179], v[52:55]
	v_mfma_f32_16x16x32_bf16 v[44:47], v[132:135], v[206:209], v[44:47]
	v_mfma_f32_16x16x32_bf16 v[36:39], v[140:143], v[206:209], v[36:39]
	v_mfma_f32_16x16x32_bf16 v[28:31], v[132:135], v[214:217], v[28:31]
	v_mfma_f32_16x16x32_bf16 v[20:23], v[140:143], v[214:217], v[20:23]
	v_mfma_f32_16x16x32_bf16 v[12:15], v[132:135], v[222:225], v[12:15]
	v_mfma_f32_16x16x32_bf16 v[4:7], v[140:143], v[222:225], v[4:7]
	v_mfma_f32_16x16x32_bf16 v[56:59], v[144:147], v[172:175], v[56:59]
	v_mfma_f32_16x16x32_bf16 v[48:51], v[164:167], v[172:175], v[48:51]
	v_mfma_f32_16x16x32_bf16 v[40:43], v[144:147], v[202:205], v[40:43]
	v_mfma_f32_16x16x32_bf16 v[32:35], v[164:167], v[202:205], v[32:35]
	v_mfma_f32_16x16x32_bf16 v[24:27], v[144:147], v[210:213], v[24:27]
	v_mfma_f32_16x16x32_bf16 v[16:19], v[164:167], v[210:213], v[16:19]
	v_mfma_f32_16x16x32_bf16 v[8:11], v[144:147], v[218:221], v[8:11]
	v_mfma_f32_16x16x32_bf16 v[0:3], v[164:167], v[218:221], v[0:3]
	v_mfma_f32_16x16x32_bf16 v[56:59], v[148:151], v[176:179], v[56:59]
	v_mfma_f32_16x16x32_bf16 v[48:51], v[168:171], v[176:179], v[48:51]
	v_mfma_f32_16x16x32_bf16 v[40:43], v[148:151], v[206:209], v[40:43]
	v_mfma_f32_16x16x32_bf16 v[32:35], v[168:171], v[206:209], v[32:35]
	v_mfma_f32_16x16x32_bf16 v[24:27], v[148:151], v[214:217], v[24:27]
	v_mfma_f32_16x16x32_bf16 v[16:19], v[168:171], v[214:217], v[16:19]
	v_mfma_f32_16x16x32_bf16 v[8:11], v[148:151], v[222:225], v[8:11]
	v_mfma_f32_16x16x32_bf16 v[0:3], v[168:171], v[222:225], v[0:3]
	s_barrier
	s_add_i32 s60, s60, 2
	s_add_u32 s56, s56, 0x100
	s_addc_u32 s57, s57, 0
	s_add_u32 s8, s8, 0x100
	s_addc_u32 s9, s9, 0
	s_cmp_gt_u32 s60, 13
.LBB0_935:
	s_add_u32 s26, s8, 0xfffc0080
	s_addc_u32 s27, s9, -1
	s_add_i32 s61, 0, 0x10000
	s_cmp_eq_u32 s60, 12
	s_cselect_b32 s29, s21, s27
	s_cselect_b32 s28, s54, s26
	s_cselect_b32 s27, s19, s57
	s_cselect_b32 s26, s55, s56
	s_add_i32 s68, 0, 0x14000
	v_add_u32_e32 v140, s61, v185
	v_add_u32_e32 v168, s68, v185
	ds_read_b128 v[128:131], v140
	ds_read_b128 v[132:135], v140 offset:1024
	ds_read_b128 v[136:139], v140 offset:2048
	ds_read_b128 v[140:143], v140 offset:3072
	ds_read_b128 v[144:147], v168
	ds_read_b128 v[148:151], v168 offset:1024
	ds_read_b128 v[164:167], v168 offset:2048
	ds_read_b128 v[168:171], v168 offset:3072
	v_lshl_add_u64 v[180:181], s[8:9], 0, v[162:163]
	s_add_i32 m0, s37, 0xc000
	ds_read_b128 v[172:175], v189
	ds_read_b128 v[176:179], v189 offset:1024
	ds_read_b128 v[202:205], v189 offset:2048
	ds_read_b128 v[206:209], v189 offset:3072
	ds_read_b128 v[210:213], v189 offset:4096
	ds_read_b128 v[214:217], v189 offset:5120
	ds_read_b128 v[218:221], v189 offset:6144
	ds_read_b128 v[222:225], v189 offset:7168
	global_load_lds_dwordx4 v[180:181], off
	v_lshl_add_u64 v[180:181], s[8:9], 0, v[160:161]
	s_add_i32 m0, s37, 0xe000
	s_nop 0
	global_load_lds_dwordx4 v[180:181], off
	s_waitcnt vmcnt(8)
	s_waitcnt lgkmcnt(0)
	s_barrier
	s_waitcnt lgkmcnt(0)
	v_mfma_f32_16x16x32_bf16 v[124:127], v[128:131], v[172:175], v[124:127]
	v_mfma_f32_16x16x32_bf16 v[116:119], v[136:139], v[172:175], v[116:119]
	v_mfma_f32_16x16x32_bf16 v[108:111], v[128:131], v[202:205], v[108:111]
	v_mfma_f32_16x16x32_bf16 v[100:103], v[136:139], v[202:205], v[100:103]
	v_mfma_f32_16x16x32_bf16 v[92:95], v[128:131], v[210:213], v[92:95]
	v_mfma_f32_16x16x32_bf16 v[84:87], v[136:139], v[210:213], v[84:87]
	v_mfma_f32_16x16x32_bf16 v[76:79], v[128:131], v[218:221], v[76:79]
	v_mfma_f32_16x16x32_bf16 v[68:71], v[136:139], v[218:221], v[68:71]
	v_mfma_f32_16x16x32_bf16 v[124:127], v[132:135], v[176:179], v[124:127]
	v_mfma_f32_16x16x32_bf16 v[116:119], v[140:143], v[176:179], v[116:119]
	v_mfma_f32_16x16x32_bf16 v[108:111], v[132:135], v[206:209], v[108:111]
	v_mfma_f32_16x16x32_bf16 v[100:103], v[140:143], v[206:209], v[100:103]
	v_mfma_f32_16x16x32_bf16 v[92:95], v[132:135], v[214:217], v[92:95]
	v_mfma_f32_16x16x32_bf16 v[84:87], v[140:143], v[214:217], v[84:87]
	v_mfma_f32_16x16x32_bf16 v[76:79], v[132:135], v[222:225], v[76:79]
	v_mfma_f32_16x16x32_bf16 v[68:71], v[140:143], v[222:225], v[68:71]
	v_mfma_f32_16x16x32_bf16 v[120:123], v[144:147], v[172:175], v[120:123]
	v_mfma_f32_16x16x32_bf16 v[112:115], v[164:167], v[172:175], v[112:115]
	v_mfma_f32_16x16x32_bf16 v[104:107], v[144:147], v[202:205], v[104:107]
	v_mfma_f32_16x16x32_bf16 v[96:99], v[164:167], v[202:205], v[96:99]
	v_mfma_f32_16x16x32_bf16 v[88:91], v[144:147], v[210:213], v[88:91]
	v_mfma_f32_16x16x32_bf16 v[80:83], v[164:167], v[210:213], v[80:83]
	v_mfma_f32_16x16x32_bf16 v[72:75], v[144:147], v[218:221], v[72:75]
	v_mfma_f32_16x16x32_bf16 v[64:67], v[164:167], v[218:221], v[64:67]
	v_mfma_f32_16x16x32_bf16 v[120:123], v[148:151], v[176:179], v[120:123]
	v_mfma_f32_16x16x32_bf16 v[112:115], v[168:171], v[176:179], v[112:115]
	v_mfma_f32_16x16x32_bf16 v[104:107], v[148:151], v[206:209], v[104:107]
	v_mfma_f32_16x16x32_bf16 v[96:99], v[168:171], v[206:209], v[96:99]
	v_mfma_f32_16x16x32_bf16 v[88:91], v[148:151], v[214:217], v[88:91]
	v_mfma_f32_16x16x32_bf16 v[80:83], v[168:171], v[214:217], v[80:83]
	v_mfma_f32_16x16x32_bf16 v[72:75], v[148:151], v[222:225], v[72:75]
	v_mfma_f32_16x16x32_bf16 v[64:67], v[168:171], v[222:225], v[64:67]
	s_barrier
	s_add_i32 s61, s61, s36
	v_lshl_add_u64 v[180:181], s[26:27], 0, v[192:193]
	s_mov_b32 m0, s61
	ds_read_b128 v[172:175], v189 offset:16384
	ds_read_b128 v[176:179], v189 offset:17408
	ds_read_b128 v[202:205], v189 offset:18432
	ds_read_b128 v[206:209], v189 offset:19456
	ds_read_b128 v[210:213], v189 offset:20480
	ds_read_b128 v[214:217], v189 offset:21504
	ds_read_b128 v[218:221], v189 offset:22528
	ds_read_b128 v[222:225], v189 offset:23552
	global_load_lds_dwordx4 v[180:181], off
	s_add_i32 m0, s61, 0x2000
	s_add_u32 s82, s26, 0x40000
	v_lshl_add_u64 v[186:187], s[26:27], 0, v[152:153]
	s_addc_u32 s83, s27, 0
	s_add_i32 s61, s68, s36
	global_load_lds_dwordx4 v[186:187], off
	v_lshl_add_u64 v[190:191], s[82:83], 0, v[192:193]
	s_mov_b32 m0, s61
	v_lshl_add_u64 v[226:227], s[28:29], 0, v[154:155]
	global_load_lds_dwordx4 v[190:191], off
	v_lshl_add_u64 v[190:191], s[82:83], 0, v[152:153]
	s_add_i32 m0, s61, 0x2000
	s_nop 0
	global_load_lds_dwordx4 v[190:191], off
	v_lshl_add_u64 v[190:191], s[28:29], 0, v[156:157]
	s_mov_b32 m0, s37
	s_nop 0
	global_load_lds_dwordx4 v[190:191], off
	s_mov_b32 m0, s38
	s_nop 0
	global_load_lds_dwordx4 v[226:227], off
	s_waitcnt vmcnt(8)
	s_waitcnt lgkmcnt(0)
	s_barrier
	s_waitcnt lgkmcnt(0)
	v_mfma_f32_16x16x32_bf16 v[60:63], v[128:131], v[172:175], v[60:63]
	v_mfma_f32_16x16x32_bf16 v[52:55], v[136:139], v[172:175], v[52:55]
	v_mfma_f32_16x16x32_bf16 v[44:47], v[128:131], v[202:205], v[44:47]
	v_mfma_f32_16x16x32_bf16 v[36:39], v[136:139], v[202:205], v[36:39]
	v_mfma_f32_16x16x32_bf16 v[28:31], v[128:131], v[210:213], v[28:31]
	v_mfma_f32_16x16x32_bf16 v[20:23], v[136:139], v[210:213], v[20:23]
	v_mfma_f32_16x16x32_bf16 v[12:15], v[128:131], v[218:221], v[12:15]
	v_mfma_f32_16x16x32_bf16 v[4:7], v[136:139], v[218:221], v[4:7]
	v_mfma_f32_16x16x32_bf16 v[60:63], v[132:135], v[176:179], v[60:63]
	v_mfma_f32_16x16x32_bf16 v[52:55], v[140:143], v[176:179], v[52:55]
	v_mfma_f32_16x16x32_bf16 v[44:47], v[132:135], v[206:209], v[44:47]
	v_mfma_f32_16x16x32_bf16 v[36:39], v[140:143], v[206:209], v[36:39]
	v_mfma_f32_16x16x32_bf16 v[28:31], v[132:135], v[214:217], v[28:31]
	v_mfma_f32_16x16x32_bf16 v[20:23], v[140:143], v[214:217], v[20:23]
	v_mfma_f32_16x16x32_bf16 v[12:15], v[132:135], v[222:225], v[12:15]
	v_mfma_f32_16x16x32_bf16 v[4:7], v[140:143], v[222:225], v[4:7]
	v_mfma_f32_16x16x32_bf16 v[56:59], v[144:147], v[172:175], v[56:59]
	v_mfma_f32_16x16x32_bf16 v[48:51], v[164:167], v[172:175], v[48:51]
	v_mfma_f32_16x16x32_bf16 v[40:43], v[144:147], v[202:205], v[40:43]
	v_mfma_f32_16x16x32_bf16 v[32:35], v[164:167], v[202:205], v[32:35]
	v_mfma_f32_16x16x32_bf16 v[24:27], v[144:147], v[210:213], v[24:27]
	v_mfma_f32_16x16x32_bf16 v[16:19], v[164:167], v[210:213], v[16:19]
	v_mfma_f32_16x16x32_bf16 v[8:11], v[144:147], v[218:221], v[8:11]
	v_mfma_f32_16x16x32_bf16 v[0:3], v[164:167], v[218:221], v[0:3]
	v_mfma_f32_16x16x32_bf16 v[56:59], v[148:151], v[176:179], v[56:59]
	v_mfma_f32_16x16x32_bf16 v[48:51], v[168:171], v[176:179], v[48:51]
	v_mfma_f32_16x16x32_bf16 v[40:43], v[148:151], v[206:209], v[40:43]
	v_mfma_f32_16x16x32_bf16 v[32:35], v[168:171], v[206:209], v[32:35]
	v_mfma_f32_16x16x32_bf16 v[24:27], v[148:151], v[214:217], v[24:27]
	v_mfma_f32_16x16x32_bf16 v[16:19], v[168:171], v[214:217], v[16:19]
	v_mfma_f32_16x16x32_bf16 v[8:11], v[148:151], v[222:225], v[8:11]
	v_mfma_f32_16x16x32_bf16 v[0:3], v[168:171], v[222:225], v[0:3]
	s_barrier
	s_add_i32 s61, 0, 0x18000
	s_add_i32 s68, 0, 0x1c000
	v_add_u32_e32 v140, s61, v185
	v_add_u32_e32 v168, s68, v185
	ds_read_b128 v[128:131], v140
	ds_read_b128 v[132:135], v140 offset:1024
	ds_read_b128 v[136:139], v140 offset:2048
	ds_read_b128 v[140:143], v140 offset:3072
	ds_read_b128 v[144:147], v168
	ds_read_b128 v[148:151], v168 offset:1024
	ds_read_b128 v[164:167], v168 offset:2048
	ds_read_b128 v[168:171], v168 offset:3072
	s_add_u32 s28, s28, 0x40000
	s_addc_u32 s29, s29, 0
	s_mov_b32 m0, s39
	v_lshl_add_u64 v[228:229], s[28:29], 0, v[156:157]
	ds_read_b128 v[172:175], v189 offset:32768
	ds_read_b128 v[176:179], v189 offset:33792
	ds_read_b128 v[202:205], v189 offset:34816
	ds_read_b128 v[206:209], v189 offset:35840
	ds_read_b128 v[210:213], v189 offset:36864
	ds_read_b128 v[214:217], v189 offset:37888
	ds_read_b128 v[218:221], v189 offset:38912
	ds_read_b128 v[222:225], v189 offset:39936
	global_load_lds_dwordx4 v[228:229], off
	v_lshl_add_u64 v[228:229], s[28:29], 0, v[154:155]
	s_mov_b32 m0, s46
	s_nop 0
	global_load_lds_dwordx4 v[228:229], off
	s_waitcnt vmcnt(8)
	s_waitcnt lgkmcnt(0)
	s_barrier
	s_waitcnt lgkmcnt(0)
	v_mfma_f32_16x16x32_bf16 v[124:127], v[128:131], v[172:175], v[124:127]
	v_mfma_f32_16x16x32_bf16 v[116:119], v[136:139], v[172:175], v[116:119]
	v_mfma_f32_16x16x32_bf16 v[108:111], v[128:131], v[202:205], v[108:111]
	v_mfma_f32_16x16x32_bf16 v[100:103], v[136:139], v[202:205], v[100:103]
	v_mfma_f32_16x16x32_bf16 v[92:95], v[128:131], v[210:213], v[92:95]
	v_mfma_f32_16x16x32_bf16 v[84:87], v[136:139], v[210:213], v[84:87]
	v_mfma_f32_16x16x32_bf16 v[76:79], v[128:131], v[218:221], v[76:79]
	v_mfma_f32_16x16x32_bf16 v[68:71], v[136:139], v[218:221], v[68:71]
	v_mfma_f32_16x16x32_bf16 v[124:127], v[132:135], v[176:179], v[124:127]
	v_mfma_f32_16x16x32_bf16 v[116:119], v[140:143], v[176:179], v[116:119]
	v_mfma_f32_16x16x32_bf16 v[108:111], v[132:135], v[206:209], v[108:111]
	v_mfma_f32_16x16x32_bf16 v[100:103], v[140:143], v[206:209], v[100:103]
	v_mfma_f32_16x16x32_bf16 v[92:95], v[132:135], v[214:217], v[92:95]
	v_mfma_f32_16x16x32_bf16 v[84:87], v[140:143], v[214:217], v[84:87]
	v_mfma_f32_16x16x32_bf16 v[76:79], v[132:135], v[222:225], v[76:79]
	v_mfma_f32_16x16x32_bf16 v[68:71], v[140:143], v[222:225], v[68:71]
	v_mfma_f32_16x16x32_bf16 v[120:123], v[144:147], v[172:175], v[120:123]
	v_mfma_f32_16x16x32_bf16 v[112:115], v[164:167], v[172:175], v[112:115]
	v_mfma_f32_16x16x32_bf16 v[104:107], v[144:147], v[202:205], v[104:107]
	v_mfma_f32_16x16x32_bf16 v[96:99], v[164:167], v[202:205], v[96:99]
	v_mfma_f32_16x16x32_bf16 v[88:91], v[144:147], v[210:213], v[88:91]
	v_mfma_f32_16x16x32_bf16 v[80:83], v[164:167], v[210:213], v[80:83]
	v_mfma_f32_16x16x32_bf16 v[72:75], v[144:147], v[218:221], v[72:75]
	v_mfma_f32_16x16x32_bf16 v[64:67], v[164:167], v[218:221], v[64:67]
	v_mfma_f32_16x16x32_bf16 v[120:123], v[148:151], v[176:179], v[120:123]
	v_mfma_f32_16x16x32_bf16 v[112:115], v[168:171], v[176:179], v[112:115]
	v_mfma_f32_16x16x32_bf16 v[104:107], v[148:151], v[206:209], v[104:107]
	v_mfma_f32_16x16x32_bf16 v[96:99], v[168:171], v[206:209], v[96:99]
	v_mfma_f32_16x16x32_bf16 v[88:91], v[148:151], v[214:217], v[88:91]
	v_mfma_f32_16x16x32_bf16 v[80:83], v[168:171], v[214:217], v[80:83]
	v_mfma_f32_16x16x32_bf16 v[72:75], v[148:151], v[222:225], v[72:75]
	v_mfma_f32_16x16x32_bf16 v[64:67], v[168:171], v[222:225], v[64:67]
	s_barrier
	s_add_i32 s28, s61, s36
	v_lshl_add_u64 v[180:181], v[180:181], 0, s[76:77]
	s_mov_b32 m0, s28
	ds_read_b128 v[172:175], v189 offset:49152
	ds_read_b128 v[176:179], v189 offset:50176
	ds_read_b128 v[202:205], v189 offset:51200
	ds_read_b128 v[206:209], v189 offset:52224
	ds_read_b128 v[210:213], v189 offset:53248
	ds_read_b128 v[214:217], v189 offset:54272
	ds_read_b128 v[218:221], v189 offset:55296
	ds_read_b128 v[222:225], v189 offset:56320
	global_load_lds_dwordx4 v[180:181], off
	s_add_i32 m0, s28, 0x2000
	s_add_u32 s26, s26, 0x40080
	v_lshl_add_u64 v[180:181], v[186:187], 0, s[76:77]
	s_addc_u32 s27, s27, 0
	s_add_i32 s28, s68, s36
	global_load_lds_dwordx4 v[180:181], off
	v_lshl_add_u64 v[180:181], s[26:27], 0, v[192:193]
	s_mov_b32 m0, s28
	s_nop 0
	global_load_lds_dwordx4 v[180:181], off
	v_lshl_add_u64 v[180:181], s[26:27], 0, v[152:153]
	s_add_i32 m0, s28, 0x2000
	s_nop 0
	global_load_lds_dwordx4 v[180:181], off
	v_lshl_add_u64 v[180:181], v[190:191], 0, s[76:77]
	s_mov_b32 m0, s47
	s_nop 0
	global_load_lds_dwordx4 v[180:181], off
	v_lshl_add_u64 v[180:181], v[226:227], 0, s[76:77]
	s_mov_b32 m0, s48
	s_nop 0
	global_load_lds_dwordx4 v[180:181], off
	s_waitcnt vmcnt(8)
	s_waitcnt lgkmcnt(0)
	s_barrier
	s_waitcnt lgkmcnt(0)
	v_mfma_f32_16x16x32_bf16 v[60:63], v[128:131], v[172:175], v[60:63]
	v_mfma_f32_16x16x32_bf16 v[52:55], v[136:139], v[172:175], v[52:55]
	v_mfma_f32_16x16x32_bf16 v[44:47], v[128:131], v[202:205], v[44:47]
	v_mfma_f32_16x16x32_bf16 v[36:39], v[136:139], v[202:205], v[36:39]
	v_mfma_f32_16x16x32_bf16 v[28:31], v[128:131], v[210:213], v[28:31]
	v_mfma_f32_16x16x32_bf16 v[20:23], v[136:139], v[210:213], v[20:23]
	v_mfma_f32_16x16x32_bf16 v[12:15], v[128:131], v[218:221], v[12:15]
	v_mfma_f32_16x16x32_bf16 v[4:7], v[136:139], v[218:221], v[4:7]
	v_mfma_f32_16x16x32_bf16 v[60:63], v[132:135], v[176:179], v[60:63]
	v_mfma_f32_16x16x32_bf16 v[52:55], v[140:143], v[176:179], v[52:55]
	v_mfma_f32_16x16x32_bf16 v[44:47], v[132:135], v[206:209], v[44:47]
	v_mfma_f32_16x16x32_bf16 v[36:39], v[140:143], v[206:209], v[36:39]
	v_mfma_f32_16x16x32_bf16 v[28:31], v[132:135], v[214:217], v[28:31]
	v_mfma_f32_16x16x32_bf16 v[20:23], v[140:143], v[214:217], v[20:23]
	v_mfma_f32_16x16x32_bf16 v[12:15], v[132:135], v[222:225], v[12:15]
	v_mfma_f32_16x16x32_bf16 v[4:7], v[140:143], v[222:225], v[4:7]
	v_mfma_f32_16x16x32_bf16 v[56:59], v[144:147], v[172:175], v[56:59]
	v_mfma_f32_16x16x32_bf16 v[48:51], v[164:167], v[172:175], v[48:51]
	v_mfma_f32_16x16x32_bf16 v[40:43], v[144:147], v[202:205], v[40:43]
	v_mfma_f32_16x16x32_bf16 v[32:35], v[164:167], v[202:205], v[32:35]
	v_mfma_f32_16x16x32_bf16 v[24:27], v[144:147], v[210:213], v[24:27]
	v_mfma_f32_16x16x32_bf16 v[16:19], v[164:167], v[210:213], v[16:19]
	v_mfma_f32_16x16x32_bf16 v[8:11], v[144:147], v[218:221], v[8:11]
	v_mfma_f32_16x16x32_bf16 v[0:3], v[164:167], v[218:221], v[0:3]
	v_mfma_f32_16x16x32_bf16 v[56:59], v[148:151], v[176:179], v[56:59]
	v_mfma_f32_16x16x32_bf16 v[48:51], v[168:171], v[176:179], v[48:51]
	v_mfma_f32_16x16x32_bf16 v[40:43], v[148:151], v[206:209], v[40:43]
	v_mfma_f32_16x16x32_bf16 v[32:35], v[168:171], v[206:209], v[32:35]
	v_mfma_f32_16x16x32_bf16 v[24:27], v[148:151], v[214:217], v[24:27]
	v_mfma_f32_16x16x32_bf16 v[16:19], v[168:171], v[214:217], v[16:19]
	v_mfma_f32_16x16x32_bf16 v[8:11], v[148:151], v[222:225], v[8:11]
	v_mfma_f32_16x16x32_bf16 v[0:3], v[168:171], v[222:225], v[0:3]
	s_barrier
	s_add_i32 s60, s60, 2
	s_add_u32 s56, s56, 0x100
	s_addc_u32 s57, s57, 0
	s_add_u32 s8, s8, 0x100
	s_addc_u32 s9, s9, 0
	s_cmp_gt_u32 s60, 13
	s_cbranch_scc0 .LBB0_935

.LBB0_990:
	s_add_u32 s12, s6, 0x6900000
	s_addc_u32 s13, s7, 0
	v_bfe_u32 v17, v16, 4, 2
	s_add_u32 s14, s6, 0x3cc00000
	v_and_b32_e32 v18, 15, v16
	v_lshlrev_b32_e32 v20, 4, v17
	v_lshlrev_b32_e32 v16, 2, v16
	s_addc_u32 s15, s7, 0
	s_and_b32 s46, s8, 3
	v_lshl_or_b32 v247, s5, 6, v18
	v_lshl_or_b32 v18, v18, 6, v20
	s_lshl_b32 s5, s5, 13
	v_and_b32_e32 v16, 32, v16
	s_add_i32 m0, s36, 0x18000
	v_lshl_add_u64 v[6:7], v[6:7], 0, s[76:77]
	v_bitop3_b32 v20, v18, s5, v16 bitop3:0xde
	s_lshl_b32 s5, s46, 12
	s_waitcnt vmcnt(2)
	s_barrier
	global_load_lds_dwordx4 v[6:7], off
	v_lshl_add_u64 v[4:5], v[4:5], 0, s[76:77]
	s_add_i32 m0, s36, 0x1a000
	s_add_i32 s47, s36, 0x8000
	s_add_i32 s48, s36, 0xa000
	global_load_lds_dwordx4 v[4:5], off
	v_lshl_add_u64 v[0:1], v[0:1], 0, s[76:77]
	s_mov_b32 m0, s47
	s_add_u32 s6, s24, 0xb0080
	global_load_lds_dwordx4 v[0:1], off
	v_lshl_add_u64 v[0:1], v[2:3], 0, s[76:77]
	s_mov_b32 m0, s48
	s_addc_u32 s7, s25, 0
	global_load_lds_dwordx4 v[0:1], off
	s_add_i32 m0, s36, 0x1c000
	v_lshl_add_u64 v[0:1], s[6:7], 0, v[192:193]
	global_load_lds_dwordx4 v[0:1], off
	v_lshl_add_u64 v[0:1], s[6:7], 0, v[202:203]
	s_add_i32 m0, s36, 0x1e000
	s_movk_i32 s8, 0xb00
	global_load_lds_dwordx4 v[0:1], off
	v_lshrrev_b32_e32 v1, 1, v8
	v_mul_lo_u32 v0, v9, s8
	s_mov_b32 s9, 0xb000
	v_mad_u64_u32 v[0:1], s[6:7], v1, s9, v[0:1]
	v_or_b32_e32 v0, v0, v10
	v_add_lshl_u32 v0, v0, v11, 1
	v_mov_b32_e32 v1, v193
	s_mov_b64 s[20:21], 0xb0080
	v_lshl_add_u64 v[208:209], v[0:1], 0, s[20:21]
	v_lshrrev_b32_e32 v1, 1, v13
	v_mul_lo_u32 v0, v12, s8
	v_mad_u64_u32 v[0:1], s[6:7], v1, s9, v[0:1]
	s_waitcnt vmcnt(6)
	v_or_b32_e32 v0, v0, v14
	v_lshlrev_b32_e32 v19, 3, v17
	s_cmpk_lt_u32 s4, 0x100
	v_add_lshl_u32 v0, v0, v15, 1
	v_mov_b32_e32 v1, v193
	v_readlane_b32 s6, v255, 38
	v_bitop3_b32 v248, v18, s5, v16 bitop3:0xde
	v_lshl_or_b32 v249, s46, 5, v19
	s_cselect_b64 s[18:19], -1, 0
	s_mov_b32 s49, 0
	v_cmp_eq_u32_e64 s[4:5], 0, v17
	v_lshl_add_u64 v[210:211], v[0:1], 0, s[20:21]
	v_add_u32_e32 v250, 0, v20
	v_readlane_b32 s54, v255, 19
	s_mov_b32 s55, s6
	s_barrier
	v_readlane_b32 s7, v255, 39
	s_cmp_lt_u32 s33, 0x100
	s_cbranch_scc1 .Lsp3
	s_setprio 1
.Lsp3:
	s_branch .LBB0_993
.LBB0_991:
	s_mov_b64 s[6:7], 0

.LBB0_1003:
	s_add_u32 s56, s24, 0x100
	s_addc_u32 s57, s25, 0
	s_mov_b32 s60, -2
	s_waitcnt lgkmcnt(0)
	s_add_u32 s24, s22, 0x100
	s_addc_u32 s25, s23, 0
	s_add_i32 s61, 0, 0x10000
	s_cmp_eq_u32 s60, 40
	s_cselect_b32 s29, s9, s25
	s_cselect_b32 s28, s8, s24
	s_cselect_b32 s27, s21, s57
	s_cselect_b32 s26, s20, s56
	s_add_i32 s68, 0, 0x14000
	v_add_u32_e32 v124, s61, v248
	v_add_u32_e32 v156, s68, v248
	ds_read_b128 v[88:91], v124
	ds_read_b128 v[100:103], v124 offset:1024
	ds_read_b128 v[112:115], v124 offset:2048
	ds_read_b128 v[124:127], v124 offset:3072
	ds_read_b128 v[136:139], v156
	ds_read_b128 v[140:143], v156 offset:1024
	ds_read_b128 v[148:151], v156 offset:2048
	ds_read_b128 v[156:159], v156 offset:3072
	v_lshl_add_u64 v[212:213], s[22:23], 0, v[210:211]
	s_add_i32 m0, s36, 0xc000
	ds_read_b128 v[160:163], v250
	ds_read_b128 v[164:167], v250 offset:1024
	ds_read_b128 v[168:171], v250 offset:2048
	ds_read_b128 v[172:175], v250 offset:3072
	ds_read_b128 v[176:179], v250 offset:4096
	ds_read_b128 v[180:183], v250 offset:5120
	ds_read_b128 v[184:187], v250 offset:6144
	ds_read_b128 v[188:191], v250 offset:7168
	global_load_lds_dwordx4 v[212:213], off
	v_lshl_add_u64 v[212:213], s[22:23], 0, v[208:209]
	s_add_i32 m0, s36, 0xe000
	s_nop 0
	global_load_lds_dwordx4 v[212:213], off
	s_waitcnt vmcnt(8)
	s_waitcnt lgkmcnt(0)
	s_barrier
	s_waitcnt lgkmcnt(0)
	v_mfma_f32_16x16x32_bf16 v[152:155], v[88:91], v[160:163], 0
	v_mfma_f32_16x16x32_bf16 v[144:147], v[112:115], v[160:163], 0
	v_mfma_f32_16x16x32_bf16 v[120:123], v[88:91], v[168:171], 0
	v_mfma_f32_16x16x32_bf16 v[116:119], v[112:115], v[168:171], 0
	v_mfma_f32_16x16x32_bf16 v[96:99], v[88:91], v[176:179], 0
	v_mfma_f32_16x16x32_bf16 v[92:95], v[112:115], v[176:179], 0
	v_mfma_f32_16x16x32_bf16 v[76:79], v[88:91], v[184:187], 0
	v_mfma_f32_16x16x32_bf16 v[72:75], v[112:115], v[184:187], 0
	v_mfma_f32_16x16x32_bf16 v[152:155], v[100:103], v[164:167], v[152:155]
	v_mfma_f32_16x16x32_bf16 v[144:147], v[124:127], v[164:167], v[144:147]
	v_mfma_f32_16x16x32_bf16 v[120:123], v[100:103], v[172:175], v[120:123]
	v_mfma_f32_16x16x32_bf16 v[116:119], v[124:127], v[172:175], v[116:119]
	v_mfma_f32_16x16x32_bf16 v[96:99], v[100:103], v[180:183], v[96:99]
	v_mfma_f32_16x16x32_bf16 v[92:95], v[124:127], v[180:183], v[92:95]
	v_mfma_f32_16x16x32_bf16 v[76:79], v[100:103], v[188:191], v[76:79]
	v_mfma_f32_16x16x32_bf16 v[72:75], v[124:127], v[188:191], v[72:75]
	v_mfma_f32_16x16x32_bf16 v[132:135], v[136:139], v[160:163], 0
	v_mfma_f32_16x16x32_bf16 v[128:131], v[148:151], v[160:163], 0
	v_mfma_f32_16x16x32_bf16 v[108:111], v[136:139], v[168:171], 0
	v_mfma_f32_16x16x32_bf16 v[104:107], v[148:151], v[168:171], 0
	v_mfma_f32_16x16x32_bf16 v[84:87], v[136:139], v[176:179], 0
	v_mfma_f32_16x16x32_bf16 v[80:83], v[148:151], v[176:179], 0
	v_mfma_f32_16x16x32_bf16 v[68:71], v[136:139], v[184:187], 0
	v_mfma_f32_16x16x32_bf16 v[64:67], v[148:151], v[184:187], 0
	v_mfma_f32_16x16x32_bf16 v[132:135], v[140:143], v[164:167], v[132:135]
	v_mfma_f32_16x16x32_bf16 v[128:131], v[156:159], v[164:167], v[128:131]
	v_mfma_f32_16x16x32_bf16 v[108:111], v[140:143], v[172:175], v[108:111]
	v_mfma_f32_16x16x32_bf16 v[104:107], v[156:159], v[172:175], v[104:107]
	v_mfma_f32_16x16x32_bf16 v[84:87], v[140:143], v[180:183], v[84:87]
	v_mfma_f32_16x16x32_bf16 v[80:83], v[156:159], v[180:183], v[80:83]
	v_mfma_f32_16x16x32_bf16 v[68:71], v[140:143], v[188:191], v[68:71]
	v_mfma_f32_16x16x32_bf16 v[64:67], v[156:159], v[188:191], v[64:67]
	s_barrier
	s_add_i32 s22, s61, s35
	v_lshl_add_u64 v[212:213], s[26:27], 0, v[192:193]
	s_mov_b32 m0, s22
	ds_read_b128 v[160:163], v250 offset:16384
	ds_read_b128 v[164:167], v250 offset:17408
	ds_read_b128 v[168:171], v250 offset:18432
	ds_read_b128 v[172:175], v250 offset:19456
	ds_read_b128 v[176:179], v250 offset:20480
	ds_read_b128 v[180:183], v250 offset:21504
	ds_read_b128 v[184:187], v250 offset:22528
	ds_read_b128 v[188:191], v250 offset:23552
	global_load_lds_dwordx4 v[212:213], off
	s_add_i32 m0, s22, 0x2000
	s_add_u32 s22, s26, 0xb0000
	v_lshl_add_u64 v[214:215], s[26:27], 0, v[202:203]
	s_addc_u32 s23, s27, 0
	s_add_i32 s61, s68, s35
	global_load_lds_dwordx4 v[214:215], off
	v_lshl_add_u64 v[216:217], s[22:23], 0, v[192:193]
	s_mov_b32 m0, s61
	v_lshl_add_u64 v[218:219], s[28:29], 0, v[204:205]
	global_load_lds_dwordx4 v[216:217], off
	v_lshl_add_u64 v[216:217], s[22:23], 0, v[202:203]
	s_add_i32 m0, s61, 0x2000
	s_nop 0
	global_load_lds_dwordx4 v[216:217], off
	v_lshl_add_u64 v[216:217], s[28:29], 0, v[206:207]
	s_mov_b32 m0, s36
	s_nop 0
	global_load_lds_dwordx4 v[216:217], off
	s_mov_b32 m0, s37
	s_nop 0
	global_load_lds_dwordx4 v[218:219], off
	s_waitcnt vmcnt(8)
	s_waitcnt lgkmcnt(0)
	s_barrier
	s_waitcnt lgkmcnt(0)
	v_mfma_f32_16x16x32_bf16 v[60:63], v[88:91], v[160:163], 0
	v_mfma_f32_16x16x32_bf16 v[56:59], v[112:115], v[160:163], 0
	v_mfma_f32_16x16x32_bf16 v[44:47], v[88:91], v[168:171], 0
	v_mfma_f32_16x16x32_bf16 v[40:43], v[112:115], v[168:171], 0
	v_mfma_f32_16x16x32_bf16 v[28:31], v[88:91], v[176:179], 0
	v_mfma_f32_16x16x32_bf16 v[24:27], v[112:115], v[176:179], 0
	v_mfma_f32_16x16x32_bf16 v[12:15], v[88:91], v[184:187], 0
	v_mfma_f32_16x16x32_bf16 v[8:11], v[112:115], v[184:187], 0
	v_mfma_f32_16x16x32_bf16 v[60:63], v[100:103], v[164:167], v[60:63]
	v_mfma_f32_16x16x32_bf16 v[56:59], v[124:127], v[164:167], v[56:59]
	v_mfma_f32_16x16x32_bf16 v[44:47], v[100:103], v[172:175], v[44:47]
	v_mfma_f32_16x16x32_bf16 v[40:43], v[124:127], v[172:175], v[40:43]
	v_mfma_f32_16x16x32_bf16 v[28:31], v[100:103], v[180:183], v[28:31]
	v_mfma_f32_16x16x32_bf16 v[24:27], v[124:127], v[180:183], v[24:27]
	v_mfma_f32_16x16x32_bf16 v[12:15], v[100:103], v[188:191], v[12:15]
	v_mfma_f32_16x16x32_bf16 v[8:11], v[124:127], v[188:191], v[8:11]
	v_mfma_f32_16x16x32_bf16 v[52:55], v[136:139], v[160:163], 0
	v_mfma_f32_16x16x32_bf16 v[48:51], v[148:151], v[160:163], 0
	v_mfma_f32_16x16x32_bf16 v[36:39], v[136:139], v[168:171], 0
	v_mfma_f32_16x16x32_bf16 v[32:35], v[148:151], v[168:171], 0
	v_mfma_f32_16x16x32_bf16 v[20:23], v[136:139], v[176:179], 0
	v_mfma_f32_16x16x32_bf16 v[16:19], v[148:151], v[176:179], 0
	v_mfma_f32_16x16x32_bf16 v[4:7], v[136:139], v[184:187], 0
	v_mfma_f32_16x16x32_bf16 v[0:3], v[148:151], v[184:187], 0
	v_mfma_f32_16x16x32_bf16 v[52:55], v[140:143], v[164:167], v[52:55]
	v_mfma_f32_16x16x32_bf16 v[48:51], v[156:159], v[164:167], v[48:51]
	v_mfma_f32_16x16x32_bf16 v[36:39], v[140:143], v[172:175], v[36:39]
	v_mfma_f32_16x16x32_bf16 v[32:35], v[156:159], v[172:175], v[32:35]
	v_mfma_f32_16x16x32_bf16 v[20:23], v[140:143], v[180:183], v[20:23]
	v_mfma_f32_16x16x32_bf16 v[16:19], v[156:159], v[180:183], v[16:19]
	v_mfma_f32_16x16x32_bf16 v[4:7], v[140:143], v[188:191], v[4:7]
	v_mfma_f32_16x16x32_bf16 v[0:3], v[156:159], v[188:191], v[0:3]
	s_barrier
	s_add_i32 s61, 0, 0x18000
	s_add_i32 s68, 0, 0x1c000
	v_add_u32_e32 v124, s61, v248
	v_add_u32_e32 v156, s68, v248
	ds_read_b128 v[88:91], v124
	ds_read_b128 v[100:103], v124 offset:1024
	ds_read_b128 v[112:115], v124 offset:2048
	ds_read_b128 v[124:127], v124 offset:3072
	ds_read_b128 v[136:139], v156
	ds_read_b128 v[140:143], v156 offset:1024
	ds_read_b128 v[148:151], v156 offset:2048
	ds_read_b128 v[156:159], v156 offset:3072
	s_add_u32 s22, s28, 0xb0000
	s_addc_u32 s23, s29, 0
	s_mov_b32 m0, s38
	v_lshl_add_u64 v[220:221], s[22:23], 0, v[206:207]
	ds_read_b128 v[160:163], v250 offset:32768
	ds_read_b128 v[164:167], v250 offset:33792
	ds_read_b128 v[168:171], v250 offset:34816
	ds_read_b128 v[172:175], v250 offset:35840
	ds_read_b128 v[176:179], v250 offset:36864
	ds_read_b128 v[180:183], v250 offset:37888
	ds_read_b128 v[184:187], v250 offset:38912
	ds_read_b128 v[188:191], v250 offset:39936
	global_load_lds_dwordx4 v[220:221], off
	v_lshl_add_u64 v[220:221], s[22:23], 0, v[204:205]
	s_mov_b32 m0, s39
	s_nop 0
	global_load_lds_dwordx4 v[220:221], off
	s_waitcnt vmcnt(8)
	s_waitcnt lgkmcnt(0)
	s_barrier
	s_waitcnt lgkmcnt(0)
	v_mfma_f32_16x16x32_bf16 v[152:155], v[88:91], v[160:163], v[152:155]
	v_mfma_f32_16x16x32_bf16 v[144:147], v[112:115], v[160:163], v[144:147]
	v_mfma_f32_16x16x32_bf16 v[120:123], v[88:91], v[168:171], v[120:123]
	v_mfma_f32_16x16x32_bf16 v[116:119], v[112:115], v[168:171], v[116:119]
	v_mfma_f32_16x16x32_bf16 v[96:99], v[88:91], v[176:179], v[96:99]
	v_mfma_f32_16x16x32_bf16 v[92:95], v[112:115], v[176:179], v[92:95]
	v_mfma_f32_16x16x32_bf16 v[76:79], v[88:91], v[184:187], v[76:79]
	v_mfma_f32_16x16x32_bf16 v[72:75], v[112:115], v[184:187], v[72:75]
	v_mfma_f32_16x16x32_bf16 v[152:155], v[100:103], v[164:167], v[152:155]
	v_mfma_f32_16x16x32_bf16 v[144:147], v[124:127], v[164:167], v[144:147]
	v_mfma_f32_16x16x32_bf16 v[120:123], v[100:103], v[172:175], v[120:123]
	v_mfma_f32_16x16x32_bf16 v[116:119], v[124:127], v[172:175], v[116:119]
	v_mfma_f32_16x16x32_bf16 v[96:99], v[100:103], v[180:183], v[96:99]
	v_mfma_f32_16x16x32_bf16 v[92:95], v[124:127], v[180:183], v[92:95]
	v_mfma_f32_16x16x32_bf16 v[76:79], v[100:103], v[188:191], v[76:79]
	v_mfma_f32_16x16x32_bf16 v[72:75], v[124:127], v[188:191], v[72:75]
	v_mfma_f32_16x16x32_bf16 v[132:135], v[136:139], v[160:163], v[132:135]
	v_mfma_f32_16x16x32_bf16 v[128:131], v[148:151], v[160:163], v[128:131]
	v_mfma_f32_16x16x32_bf16 v[108:111], v[136:139], v[168:171], v[108:111]
	v_mfma_f32_16x16x32_bf16 v[104:107], v[148:151], v[168:171], v[104:107]
	v_mfma_f32_16x16x32_bf16 v[84:87], v[136:139], v[176:179], v[84:87]
	v_mfma_f32_16x16x32_bf16 v[80:83], v[148:151], v[176:179], v[80:83]
	v_mfma_f32_16x16x32_bf16 v[68:71], v[136:139], v[184:187], v[68:71]
	v_mfma_f32_16x16x32_bf16 v[64:67], v[148:151], v[184:187], v[64:67]
	v_mfma_f32_16x16x32_bf16 v[132:135], v[140:143], v[164:167], v[132:135]
	v_mfma_f32_16x16x32_bf16 v[128:131], v[156:159], v[164:167], v[128:131]
	v_mfma_f32_16x16x32_bf16 v[108:111], v[140:143], v[172:175], v[108:111]
	v_mfma_f32_16x16x32_bf16 v[104:107], v[156:159], v[172:175], v[104:107]
	v_mfma_f32_16x16x32_bf16 v[84:87], v[140:143], v[180:183], v[84:87]
	v_mfma_f32_16x16x32_bf16 v[80:83], v[156:159], v[180:183], v[80:83]
	v_mfma_f32_16x16x32_bf16 v[68:71], v[140:143], v[188:191], v[68:71]
	v_mfma_f32_16x16x32_bf16 v[64:67], v[156:159], v[188:191], v[64:67]
	s_barrier
	s_add_i32 s22, s61, s35
	v_lshl_add_u64 v[212:213], v[212:213], 0, s[76:77]
	s_mov_b32 m0, s22
	ds_read_b128 v[160:163], v250 offset:49152
	ds_read_b128 v[164:167], v250 offset:50176
	ds_read_b128 v[168:171], v250 offset:51200
	ds_read_b128 v[172:175], v250 offset:52224
	ds_read_b128 v[176:179], v250 offset:53248
	ds_read_b128 v[180:183], v250 offset:54272
	ds_read_b128 v[184:187], v250 offset:55296
	ds_read_b128 v[188:191], v250 offset:56320
	global_load_lds_dwordx4 v[212:213], off
	s_add_i32 m0, s22, 0x2000
	s_add_u32 s22, s26, 0xb0080
	v_lshl_add_u64 v[212:213], v[214:215], 0, s[76:77]
	s_addc_u32 s23, s27, 0
	s_add_i32 s26, s68, s35
	global_load_lds_dwordx4 v[212:213], off
	v_lshl_add_u64 v[212:213], s[22:23], 0, v[192:193]
	s_mov_b32 m0, s26
	s_nop 0
	global_load_lds_dwordx4 v[212:213], off
	v_lshl_add_u64 v[212:213], s[22:23], 0, v[202:203]
	s_add_i32 m0, s26, 0x2000
	s_nop 0
	global_load_lds_dwordx4 v[212:213], off
	v_lshl_add_u64 v[212:213], v[216:217], 0, s[76:77]
	s_mov_b32 m0, s47
	s_nop 0
	global_load_lds_dwordx4 v[212:213], off
	v_lshl_add_u64 v[212:213], v[218:219], 0, s[76:77]
	s_mov_b32 m0, s48
	s_nop 0
	global_load_lds_dwordx4 v[212:213], off
	s_waitcnt vmcnt(8)
	s_waitcnt lgkmcnt(0)
	s_barrier
	s_waitcnt lgkmcnt(0)
	v_mfma_f32_16x16x32_bf16 v[60:63], v[88:91], v[160:163], v[60:63]
	v_mfma_f32_16x16x32_bf16 v[56:59], v[112:115], v[160:163], v[56:59]
	v_mfma_f32_16x16x32_bf16 v[44:47], v[88:91], v[168:171], v[44:47]
	v_mfma_f32_16x16x32_bf16 v[40:43], v[112:115], v[168:171], v[40:43]
	v_mfma_f32_16x16x32_bf16 v[28:31], v[88:91], v[176:179], v[28:31]
	v_mfma_f32_16x16x32_bf16 v[24:27], v[112:115], v[176:179], v[24:27]
	v_mfma_f32_16x16x32_bf16 v[12:15], v[88:91], v[184:187], v[12:15]
	v_mfma_f32_16x16x32_bf16 v[8:11], v[112:115], v[184:187], v[8:11]
	v_mfma_f32_16x16x32_bf16 v[60:63], v[100:103], v[164:167], v[60:63]
	v_mfma_f32_16x16x32_bf16 v[56:59], v[124:127], v[164:167], v[56:59]
	v_mfma_f32_16x16x32_bf16 v[44:47], v[100:103], v[172:175], v[44:47]
	v_mfma_f32_16x16x32_bf16 v[40:43], v[124:127], v[172:175], v[40:43]
	v_mfma_f32_16x16x32_bf16 v[28:31], v[100:103], v[180:183], v[28:31]
	v_mfma_f32_16x16x32_bf16 v[24:27], v[124:127], v[180:183], v[24:27]
	v_mfma_f32_16x16x32_bf16 v[12:15], v[100:103], v[188:191], v[12:15]
	v_mfma_f32_16x16x32_bf16 v[8:11], v[124:127], v[188:191], v[8:11]
	v_mfma_f32_16x16x32_bf16 v[52:55], v[136:139], v[160:163], v[52:55]
	v_mfma_f32_16x16x32_bf16 v[48:51], v[148:151], v[160:163], v[48:51]
	v_mfma_f32_16x16x32_bf16 v[36:39], v[136:139], v[168:171], v[36:39]
	v_mfma_f32_16x16x32_bf16 v[32:35], v[148:151], v[168:171], v[32:35]
	v_mfma_f32_16x16x32_bf16 v[20:23], v[136:139], v[176:179], v[20:23]
	v_mfma_f32_16x16x32_bf16 v[16:19], v[148:151], v[176:179], v[16:19]
	v_mfma_f32_16x16x32_bf16 v[4:7], v[136:139], v[184:187], v[4:7]
	v_mfma_f32_16x16x32_bf16 v[0:3], v[148:151], v[184:187], v[0:3]
	v_mfma_f32_16x16x32_bf16 v[52:55], v[140:143], v[164:167], v[52:55]
	v_mfma_f32_16x16x32_bf16 v[48:51], v[156:159], v[164:167], v[48:51]
	v_mfma_f32_16x16x32_bf16 v[36:39], v[140:143], v[172:175], v[36:39]
	v_mfma_f32_16x16x32_bf16 v[32:35], v[156:159], v[172:175], v[32:35]
	v_mfma_f32_16x16x32_bf16 v[20:23], v[140:143], v[180:183], v[20:23]
	v_mfma_f32_16x16x32_bf16 v[16:19], v[156:159], v[180:183], v[16:19]
	v_mfma_f32_16x16x32_bf16 v[4:7], v[140:143], v[188:191], v[4:7]
	v_mfma_f32_16x16x32_bf16 v[0:3], v[156:159], v[188:191], v[0:3]
	s_barrier
	s_add_i32 s60, s60, 2
	s_add_u32 s56, s56, 0x100
	s_addc_u32 s57, s57, 0
	s_cmp_gt_u32 s60, 41
	s_mov_b64 s[22:23], s[24:25]
.LBB0_1004:
	s_add_u32 s24, s22, 0x100
	s_addc_u32 s25, s23, 0
	s_add_i32 s61, 0, 0x10000
	s_cmp_eq_u32 s60, 40
	s_cselect_b32 s29, s9, s25
	s_cselect_b32 s28, s8, s24
	s_cselect_b32 s27, s21, s57
	s_cselect_b32 s26, s20, s56
	s_add_i32 s68, 0, 0x14000
	v_add_u32_e32 v124, s61, v248
	v_add_u32_e32 v156, s68, v248
	ds_read_b128 v[88:91], v124
	ds_read_b128 v[100:103], v124 offset:1024
	ds_read_b128 v[112:115], v124 offset:2048
	ds_read_b128 v[124:127], v124 offset:3072
	ds_read_b128 v[136:139], v156
	ds_read_b128 v[140:143], v156 offset:1024
	ds_read_b128 v[148:151], v156 offset:2048
	ds_read_b128 v[156:159], v156 offset:3072
	v_lshl_add_u64 v[212:213], s[22:23], 0, v[210:211]
	s_add_i32 m0, s36, 0xc000
	ds_read_b128 v[160:163], v250
	ds_read_b128 v[164:167], v250 offset:1024
	ds_read_b128 v[168:171], v250 offset:2048
	ds_read_b128 v[172:175], v250 offset:3072
	ds_read_b128 v[176:179], v250 offset:4096
	ds_read_b128 v[180:183], v250 offset:5120
	ds_read_b128 v[184:187], v250 offset:6144
	ds_read_b128 v[188:191], v250 offset:7168
	global_load_lds_dwordx4 v[212:213], off
	v_lshl_add_u64 v[212:213], s[22:23], 0, v[208:209]
	s_add_i32 m0, s36, 0xe000
	s_nop 0
	global_load_lds_dwordx4 v[212:213], off
	s_waitcnt vmcnt(8)
	s_waitcnt lgkmcnt(0)
	s_barrier
	s_waitcnt lgkmcnt(0)
	v_mfma_f32_16x16x32_bf16 v[152:155], v[88:91], v[160:163], v[152:155]
	v_mfma_f32_16x16x32_bf16 v[144:147], v[112:115], v[160:163], v[144:147]
	v_mfma_f32_16x16x32_bf16 v[120:123], v[88:91], v[168:171], v[120:123]
	v_mfma_f32_16x16x32_bf16 v[116:119], v[112:115], v[168:171], v[116:119]
	v_mfma_f32_16x16x32_bf16 v[96:99], v[88:91], v[176:179], v[96:99]
	v_mfma_f32_16x16x32_bf16 v[92:95], v[112:115], v[176:179], v[92:95]
	v_mfma_f32_16x16x32_bf16 v[76:79], v[88:91], v[184:187], v[76:79]
	v_mfma_f32_16x16x32_bf16 v[72:75], v[112:115], v[184:187], v[72:75]
	v_mfma_f32_16x16x32_bf16 v[152:155], v[100:103], v[164:167], v[152:155]
	v_mfma_f32_16x16x32_bf16 v[144:147], v[124:127], v[164:167], v[144:147]
	v_mfma_f32_16x16x32_bf16 v[120:123], v[100:103], v[172:175], v[120:123]
	v_mfma_f32_16x16x32_bf16 v[116:119], v[124:127], v[172:175], v[116:119]
	v_mfma_f32_16x16x32_bf16 v[96:99], v[100:103], v[180:183], v[96:99]
	v_mfma_f32_16x16x32_bf16 v[92:95], v[124:127], v[180:183], v[92:95]
	v_mfma_f32_16x16x32_bf16 v[76:79], v[100:103], v[188:191], v[76:79]
	v_mfma_f32_16x16x32_bf16 v[72:75], v[124:127], v[188:191], v[72:75]
	v_mfma_f32_16x16x32_bf16 v[132:135], v[136:139], v[160:163], v[132:135]
	v_mfma_f32_16x16x32_bf16 v[128:131], v[148:151], v[160:163], v[128:131]
	v_mfma_f32_16x16x32_bf16 v[108:111], v[136:139], v[168:171], v[108:111]
	v_mfma_f32_16x16x32_bf16 v[104:107], v[148:151], v[168:171], v[104:107]
	v_mfma_f32_16x16x32_bf16 v[84:87], v[136:139], v[176:179], v[84:87]
	v_mfma_f32_16x16x32_bf16 v[80:83], v[148:151], v[176:179], v[80:83]
	v_mfma_f32_16x16x32_bf16 v[68:71], v[136:139], v[184:187], v[68:71]
	v_mfma_f32_16x16x32_bf16 v[64:67], v[148:151], v[184:187], v[64:67]
	v_mfma_f32_16x16x32_bf16 v[132:135], v[140:143], v[164:167], v[132:135]
	v_mfma_f32_16x16x32_bf16 v[128:131], v[156:159], v[164:167], v[128:131]
	v_mfma_f32_16x16x32_bf16 v[108:111], v[140:143], v[172:175], v[108:111]
	v_mfma_f32_16x16x32_bf16 v[104:107], v[156:159], v[172:175], v[104:107]
	v_mfma_f32_16x16x32_bf16 v[84:87], v[140:143], v[180:183], v[84:87]
	v_mfma_f32_16x16x32_bf16 v[80:83], v[156:159], v[180:183], v[80:83]
	v_mfma_f32_16x16x32_bf16 v[68:71], v[140:143], v[188:191], v[68:71]
	v_mfma_f32_16x16x32_bf16 v[64:67], v[156:159], v[188:191], v[64:67]
	s_barrier
	s_add_i32 s22, s61, s35
	v_lshl_add_u64 v[212:213], s[26:27], 0, v[192:193]
	s_mov_b32 m0, s22
	ds_read_b128 v[160:163], v250 offset:16384
	ds_read_b128 v[164:167], v250 offset:17408
	ds_read_b128 v[168:171], v250 offset:18432
	ds_read_b128 v[172:175], v250 offset:19456
	ds_read_b128 v[176:179], v250 offset:20480
	ds_read_b128 v[180:183], v250 offset:21504
	ds_read_b128 v[184:187], v250 offset:22528
	ds_read_b128 v[188:191], v250 offset:23552
	global_load_lds_dwordx4 v[212:213], off
	s_add_i32 m0, s22, 0x2000
	s_add_u32 s22, s26, 0xb0000
	v_lshl_add_u64 v[214:215], s[26:27], 0, v[202:203]
	s_addc_u32 s23, s27, 0
	s_add_i32 s61, s68, s35
	global_load_lds_dwordx4 v[214:215], off
	v_lshl_add_u64 v[216:217], s[22:23], 0, v[192:193]
	s_mov_b32 m0, s61
	v_lshl_add_u64 v[218:219], s[28:29], 0, v[204:205]
	global_load_lds_dwordx4 v[216:217], off
	v_lshl_add_u64 v[216:217], s[22:23], 0, v[202:203]
	s_add_i32 m0, s61, 0x2000
	s_nop 0
	global_load_lds_dwordx4 v[216:217], off
	v_lshl_add_u64 v[216:217], s[28:29], 0, v[206:207]
	s_mov_b32 m0, s36
	s_nop 0
	global_load_lds_dwordx4 v[216:217], off
	s_mov_b32 m0, s37
	s_nop 0
	global_load_lds_dwordx4 v[218:219], off
	s_waitcnt vmcnt(8)
	s_waitcnt lgkmcnt(0)
	s_barrier
	s_waitcnt lgkmcnt(0)
	v_mfma_f32_16x16x32_bf16 v[60:63], v[88:91], v[160:163], v[60:63]
	v_mfma_f32_16x16x32_bf16 v[56:59], v[112:115], v[160:163], v[56:59]
	v_mfma_f32_16x16x32_bf16 v[44:47], v[88:91], v[168:171], v[44:47]
	v_mfma_f32_16x16x32_bf16 v[40:43], v[112:115], v[168:171], v[40:43]
	v_mfma_f32_16x16x32_bf16 v[28:31], v[88:91], v[176:179], v[28:31]
	v_mfma_f32_16x16x32_bf16 v[24:27], v[112:115], v[176:179], v[24:27]
	v_mfma_f32_16x16x32_bf16 v[12:15], v[88:91], v[184:187], v[12:15]
	v_mfma_f32_16x16x32_bf16 v[8:11], v[112:115], v[184:187], v[8:11]
	v_mfma_f32_16x16x32_bf16 v[60:63], v[100:103], v[164:167], v[60:63]
	v_mfma_f32_16x16x32_bf16 v[56:59], v[124:127], v[164:167], v[56:59]
	v_mfma_f32_16x16x32_bf16 v[44:47], v[100:103], v[172:175], v[44:47]
	v_mfma_f32_16x16x32_bf16 v[40:43], v[124:127], v[172:175], v[40:43]
	v_mfma_f32_16x16x32_bf16 v[28:31], v[100:103], v[180:183], v[28:31]
	v_mfma_f32_16x16x32_bf16 v[24:27], v[124:127], v[180:183], v[24:27]
	v_mfma_f32_16x16x32_bf16 v[12:15], v[100:103], v[188:191], v[12:15]
	v_mfma_f32_16x16x32_bf16 v[8:11], v[124:127], v[188:191], v[8:11]
	v_mfma_f32_16x16x32_bf16 v[52:55], v[136:139], v[160:163], v[52:55]
	v_mfma_f32_16x16x32_bf16 v[48:51], v[148:151], v[160:163], v[48:51]
	v_mfma_f32_16x16x32_bf16 v[36:39], v[136:139], v[168:171], v[36:39]
	v_mfma_f32_16x16x32_bf16 v[32:35], v[148:151], v[168:171], v[32:35]
	v_mfma_f32_16x16x32_bf16 v[20:23], v[136:139], v[176:179], v[20:23]
	v_mfma_f32_16x16x32_bf16 v[16:19], v[148:151], v[176:179], v[16:19]
	v_mfma_f32_16x16x32_bf16 v[4:7], v[136:139], v[184:187], v[4:7]
	v_mfma_f32_16x16x32_bf16 v[0:3], v[148:151], v[184:187], v[0:3]
	v_mfma_f32_16x16x32_bf16 v[52:55], v[140:143], v[164:167], v[52:55]
	v_mfma_f32_16x16x32_bf16 v[48:51], v[156:159], v[164:167], v[48:51]
	v_mfma_f32_16x16x32_bf16 v[36:39], v[140:143], v[172:175], v[36:39]
	v_mfma_f32_16x16x32_bf16 v[32:35], v[156:159], v[172:175], v[32:35]
	v_mfma_f32_16x16x32_bf16 v[20:23], v[140:143], v[180:183], v[20:23]
	v_mfma_f32_16x16x32_bf16 v[16:19], v[156:159], v[180:183], v[16:19]
	v_mfma_f32_16x16x32_bf16 v[4:7], v[140:143], v[188:191], v[4:7]
	v_mfma_f32_16x16x32_bf16 v[0:3], v[156:159], v[188:191], v[0:3]
	s_barrier
	s_add_i32 s61, 0, 0x18000
	s_add_i32 s68, 0, 0x1c000
	v_add_u32_e32 v124, s61, v248
	v_add_u32_e32 v156, s68, v248
	ds_read_b128 v[88:91], v124
	ds_read_b128 v[100:103], v124 offset:1024
	ds_read_b128 v[112:115], v124 offset:2048
	ds_read_b128 v[124:127], v124 offset:3072
	ds_read_b128 v[136:139], v156
	ds_read_b128 v[140:143], v156 offset:1024
	ds_read_b128 v[148:151], v156 offset:2048
	ds_read_b128 v[156:159], v156 offset:3072
	s_add_u32 s22, s28, 0xb0000
	s_addc_u32 s23, s29, 0
	s_mov_b32 m0, s38
	v_lshl_add_u64 v[220:221], s[22:23], 0, v[206:207]
	ds_read_b128 v[160:163], v250 offset:32768
	ds_read_b128 v[164:167], v250 offset:33792
	ds_read_b128 v[168:171], v250 offset:34816
	ds_read_b128 v[172:175], v250 offset:35840
	ds_read_b128 v[176:179], v250 offset:36864
	ds_read_b128 v[180:183], v250 offset:37888
	ds_read_b128 v[184:187], v250 offset:38912
	ds_read_b128 v[188:191], v250 offset:39936
	global_load_lds_dwordx4 v[220:221], off
	v_lshl_add_u64 v[220:221], s[22:23], 0, v[204:205]
	s_mov_b32 m0, s39
	s_nop 0
	global_load_lds_dwordx4 v[220:221], off
	s_waitcnt vmcnt(8)
	s_waitcnt lgkmcnt(0)
	s_barrier
	s_waitcnt lgkmcnt(0)
	v_mfma_f32_16x16x32_bf16 v[152:155], v[88:91], v[160:163], v[152:155]
	v_mfma_f32_16x16x32_bf16 v[144:147], v[112:115], v[160:163], v[144:147]
	v_mfma_f32_16x16x32_bf16 v[120:123], v[88:91], v[168:171], v[120:123]
	v_mfma_f32_16x16x32_bf16 v[116:119], v[112:115], v[168:171], v[116:119]
	v_mfma_f32_16x16x32_bf16 v[96:99], v[88:91], v[176:179], v[96:99]
	v_mfma_f32_16x16x32_bf16 v[92:95], v[112:115], v[176:179], v[92:95]
	v_mfma_f32_16x16x32_bf16 v[76:79], v[88:91], v[184:187], v[76:79]
	v_mfma_f32_16x16x32_bf16 v[72:75], v[112:115], v[184:187], v[72:75]
	v_mfma_f32_16x16x32_bf16 v[152:155], v[100:103], v[164:167], v[152:155]
	v_mfma_f32_16x16x32_bf16 v[144:147], v[124:127], v[164:167], v[144:147]
	v_mfma_f32_16x16x32_bf16 v[120:123], v[100:103], v[172:175], v[120:123]
	v_mfma_f32_16x16x32_bf16 v[116:119], v[124:127], v[172:175], v[116:119]
	v_mfma_f32_16x16x32_bf16 v[96:99], v[100:103], v[180:183], v[96:99]
	v_mfma_f32_16x16x32_bf16 v[92:95], v[124:127], v[180:183], v[92:95]
	v_mfma_f32_16x16x32_bf16 v[76:79], v[100:103], v[188:191], v[76:79]
	v_mfma_f32_16x16x32_bf16 v[72:75], v[124:127], v[188:191], v[72:75]
	v_mfma_f32_16x16x32_bf16 v[132:135], v[136:139], v[160:163], v[132:135]
	v_mfma_f32_16x16x32_bf16 v[128:131], v[148:151], v[160:163], v[128:131]
	v_mfma_f32_16x16x32_bf16 v[108:111], v[136:139], v[168:171], v[108:111]
	v_mfma_f32_16x16x32_bf16 v[104:107], v[148:151], v[168:171], v[104:107]
	v_mfma_f32_16x16x32_bf16 v[84:87], v[136:139], v[176:179], v[84:87]
	v_mfma_f32_16x16x32_bf16 v[80:83], v[148:151], v[176:179], v[80:83]
	v_mfma_f32_16x16x32_bf16 v[68:71], v[136:139], v[184:187], v[68:71]
	v_mfma_f32_16x16x32_bf16 v[64:67], v[148:151], v[184:187], v[64:67]
	v_mfma_f32_16x16x32_bf16 v[132:135], v[140:143], v[164:167], v[132:135]
	v_mfma_f32_16x16x32_bf16 v[128:131], v[156:159], v[164:167], v[128:131]
	v_mfma_f32_16x16x32_bf16 v[108:111], v[140:143], v[172:175], v[108:111]
	v_mfma_f32_16x16x32_bf16 v[104:107], v[156:159], v[172:175], v[104:107]
	v_mfma_f32_16x16x32_bf16 v[84:87], v[140:143], v[180:183], v[84:87]
	v_mfma_f32_16x16x32_bf16 v[80:83], v[156:159], v[180:183], v[80:83]
	v_mfma_f32_16x16x32_bf16 v[68:71], v[140:143], v[188:191], v[68:71]
	v_mfma_f32_16x16x32_bf16 v[64:67], v[156:159], v[188:191], v[64:67]
	s_barrier
	s_add_i32 s22, s61, s35
	v_lshl_add_u64 v[212:213], v[212:213], 0, s[76:77]
	s_mov_b32 m0, s22
	ds_read_b128 v[160:163], v250 offset:49152
	ds_read_b128 v[164:167], v250 offset:50176
	ds_read_b128 v[168:171], v250 offset:51200
	ds_read_b128 v[172:175], v250 offset:52224
	ds_read_b128 v[176:179], v250 offset:53248
	ds_read_b128 v[180:183], v250 offset:54272
	ds_read_b128 v[184:187], v250 offset:55296
	ds_read_b128 v[188:191], v250 offset:56320
	global_load_lds_dwordx4 v[212:213], off
	s_add_i32 m0, s22, 0x2000
	s_add_u32 s22, s26, 0xb0080
	v_lshl_add_u64 v[212:213], v[214:215], 0, s[76:77]
	s_addc_u32 s23, s27, 0
	s_add_i32 s26, s68, s35
	global_load_lds_dwordx4 v[212:213], off
	v_lshl_add_u64 v[212:213], s[22:23], 0, v[192:193]
	s_mov_b32 m0, s26
	s_nop 0
	global_load_lds_dwordx4 v[212:213], off
	v_lshl_add_u64 v[212:213], s[22:23], 0, v[202:203]
	s_add_i32 m0, s26, 0x2000
	s_nop 0
	global_load_lds_dwordx4 v[212:213], off
	v_lshl_add_u64 v[212:213], v[216:217], 0, s[76:77]
	s_mov_b32 m0, s47
	s_nop 0
	global_load_lds_dwordx4 v[212:213], off
	v_lshl_add_u64 v[212:213], v[218:219], 0, s[76:77]
	s_mov_b32 m0, s48
	s_nop 0
	global_load_lds_dwordx4 v[212:213], off
	s_waitcnt vmcnt(8)
	s_waitcnt lgkmcnt(0)
	s_barrier
	s_waitcnt lgkmcnt(0)
	v_mfma_f32_16x16x32_bf16 v[60:63], v[88:91], v[160:163], v[60:63]
	v_mfma_f32_16x16x32_bf16 v[56:59], v[112:115], v[160:163], v[56:59]
	v_mfma_f32_16x16x32_bf16 v[44:47], v[88:91], v[168:171], v[44:47]
	v_mfma_f32_16x16x32_bf16 v[40:43], v[112:115], v[168:171], v[40:43]
	v_mfma_f32_16x16x32_bf16 v[28:31], v[88:91], v[176:179], v[28:31]
	v_mfma_f32_16x16x32_bf16 v[24:27], v[112:115], v[176:179], v[24:27]
	v_mfma_f32_16x16x32_bf16 v[12:15], v[88:91], v[184:187], v[12:15]
	v_mfma_f32_16x16x32_bf16 v[8:11], v[112:115], v[184:187], v[8:11]
	v_mfma_f32_16x16x32_bf16 v[60:63], v[100:103], v[164:167], v[60:63]
	v_mfma_f32_16x16x32_bf16 v[56:59], v[124:127], v[164:167], v[56:59]
	v_mfma_f32_16x16x32_bf16 v[44:47], v[100:103], v[172:175], v[44:47]
	v_mfma_f32_16x16x32_bf16 v[40:43], v[124:127], v[172:175], v[40:43]
	v_mfma_f32_16x16x32_bf16 v[28:31], v[100:103], v[180:183], v[28:31]
	v_mfma_f32_16x16x32_bf16 v[24:27], v[124:127], v[180:183], v[24:27]
	v_mfma_f32_16x16x32_bf16 v[12:15], v[100:103], v[188:191], v[12:15]
	v_mfma_f32_16x16x32_bf16 v[8:11], v[124:127], v[188:191], v[8:11]
	v_mfma_f32_16x16x32_bf16 v[52:55], v[136:139], v[160:163], v[52:55]
	v_mfma_f32_16x16x32_bf16 v[48:51], v[148:151], v[160:163], v[48:51]
	v_mfma_f32_16x16x32_bf16 v[36:39], v[136:139], v[168:171], v[36:39]
	v_mfma_f32_16x16x32_bf16 v[32:35], v[148:151], v[168:171], v[32:35]
	v_mfma_f32_16x16x32_bf16 v[20:23], v[136:139], v[176:179], v[20:23]
	v_mfma_f32_16x16x32_bf16 v[16:19], v[148:151], v[176:179], v[16:19]
	v_mfma_f32_16x16x32_bf16 v[4:7], v[136:139], v[184:187], v[4:7]
	v_mfma_f32_16x16x32_bf16 v[0:3], v[148:151], v[184:187], v[0:3]
	v_mfma_f32_16x16x32_bf16 v[52:55], v[140:143], v[164:167], v[52:55]
	v_mfma_f32_16x16x32_bf16 v[48:51], v[156:159], v[164:167], v[48:51]
	v_mfma_f32_16x16x32_bf16 v[36:39], v[140:143], v[172:175], v[36:39]
	v_mfma_f32_16x16x32_bf16 v[32:35], v[156:159], v[172:175], v[32:35]
	v_mfma_f32_16x16x32_bf16 v[20:23], v[140:143], v[180:183], v[20:23]
	v_mfma_f32_16x16x32_bf16 v[16:19], v[156:159], v[180:183], v[16:19]
	v_mfma_f32_16x16x32_bf16 v[4:7], v[140:143], v[188:191], v[4:7]
	v_mfma_f32_16x16x32_bf16 v[0:3], v[156:159], v[188:191], v[0:3]
	s_barrier
	s_add_i32 s60, s60, 2
	s_add_u32 s56, s56, 0x100
	s_addc_u32 s57, s57, 0
	s_cmp_gt_u32 s60, 41
	s_mov_b64 s[22:23], s[24:25]
	s_cbranch_scc0 .LBB0_1004
